# K-loops: per-phase setprio flips removed; one static s_setprio 1 for waves 4-7 at kernel entry
# speedup vs baseline: 1.0754x; 1.0444x over previous
; #define LAS __attribute__((address_space(3)))
; __global__ void __launch_bounds__(NTHREADS, 2) mk_fwd(Params P_arg) {
;     extern __shared__ __attribute__((aligned(16))) unsigned char lds_raw[];
;     LAS unsigned char* lds = (LAS unsigned char*)lds_raw;
;     cg::grid_group grid = cg::this_grid();
;     volatile LAS unsigned* bar_st = (volatile LAS unsigned*)(lds + LDS_BYTES - 64);
;     if (threadIdx.x == 0) { bar_st[0] = 0u; bar_st[1] = 0u; }
;     __syncthreads();
;     const XcdBarrier xbar = xcd_barrier_post((unsigned*)(P_arg.ws + WS_CTL), bar_st);
_Z6mk_fwd6Params:
	v_readfirstlane_b32 s98, v0
	s_nop 3
	s_and_b32 s98, s98, 0x3ff
	s_lshr_b32 s98, s98, 6
	s_cmp_ge_u32 s98, 4
	s_cbranch_scc0 .Lsprio_skip
	s_setprio 1
.Lsprio_skip:
	s_load_dwordx4 s[48:51], s[0:1], 0x110
	s_load_dwordx2 s[90:91], s[0:1], 0x120
	s_mov_b32 s88, s2
	s_add_u32 s2, s0, 0x120
	v_writelane_b32 v248, s0, 0
	s_addc_u32 s3, s1, 0
	v_and_b32_e32 v179, 0x3ff, v0
	v_writelane_b32 v248, s1, 1
	v_writelane_b32 v248, s2, 2
	s_nop 1
	v_writelane_b32 v248, s3, 3
	v_cmp_eq_u32_e64 s[2:3], 0, v179
	s_mov_b64 s[0:1], exec
	s_nop 0
	v_writelane_b32 v248, s2, 4
	s_nop 1
	v_writelane_b32 v248, s3, 5
	s_and_b64 s[2:3], s[0:1], s[2:3]
	s_mov_b64 exec, s[2:3]
	s_cbranch_execz .LBB0_2
	s_add_i32 s2, 0, 0x23fc0
	v_mov_b32_e32 v1, 0
	v_mov_b32_e32 v2, s2
	s_add_i32 s2, 0, 0x23fc4
	ds_write_b32 v2, v1
	v_mov_b32_e32 v2, s2
	ds_write_b32 v2, v1

; #define PG8_STAGE(bufoff, gbase, voff) do { _Pragma("unroll") for (int _i = 0; _i < 2; ++_i) \
;         __builtin_amdgcn_global_load_lds((const unsigned*)((const char*)(gbase) + (voff)[_i]), (LAS unsigned*)(lds + (bufoff) + ldsw + _i * 8192), 16, 0, 0); } while (0)
; #define PG8_LDA(dst, b, h) do { _Pragma("unroll") for (int m = 0; m < 4; ++m) _Pragma("unroll") for (int k = 0; k < 2; ++k) dst[m][k] = *(const LAS bf16x8*)(lds + PG8_SA(b, h) + aoff + m * 2048 + k * 1024); } while (0)
; #define PG8_LDB(dst, b, h) do { _Pragma("unroll") for (int n = 0; n < 2; ++n) _Pragma("unroll") for (int k = 0; k < 2; ++k) dst[n][k] = *(const LAS bf16x8*)(lds + PG8_SB(b, h) + boff + n * 2048 + k * 1024); } while (0)
; #define PG8_MMA(ai, bj, At, Bt) do { __builtin_amdgcn_s_setprio(1); _Pragma("unroll") for (int m = 0; m < 4; ++m) _Pragma("unroll") for (int n = 0; n < 2; ++n) _Pragma("unroll") for (int k = 0; k < 2; ++k) \
;         acc[ai][bj][m][n] = __builtin_amdgcn_mfma_f32_16x16x32_bf16(Bt[n][k], At[m][k], acc[ai][bj][m][n], 0, 0, 0); __builtin_amdgcn_s_setprio(0); } while (0)
; #define PG8_WAIT_L(n) asm volatile("s_waitcnt lgkmcnt(" #n ")" ::: "memory")
; #define PG8_BAR __builtin_amdgcn_s_barrier()
; #define PG8_SCHED __builtin_amdgcn_sched_barrier(0)
; template <int MODE, class EpiT, class Sched>
; __device__ __forceinline__ void gemm_phase(LAS unsigned char* lds, const Gemm g, const Sched& S, const EpiT& E) {
;     ...
;         for (int t = 0; t < nt; t += 2) {
;             const bool last = (t == nt - 2);
;             const char* a1 = cA + (size_t)(t + 1) * kstep;
;             const char* a2 = last ? nA : cA + (size_t)(t + 2) * kstep; const char* b2 = last ? nB : cB + (size_t)(t + 2) * kstep;
;             const char* a3 = a2 + kstep; const char* b3 = b2 + kstep;
;             PG8_LDB(B0, 0, 0); PG8_SCHED; PG8_LDA(At, 0, 0); PG8_STAGE(PG8_SA(1, 1), a1 + hstep, voffA);
;             PG8_WAIT_L(8); PG8_BAR; PG8_WAIT_L(0); PG8_MMA(0, 0, At, B0); PG8_BAR; PG8_SCHED;
;             PG8_LDB(B1, 0, 1); PG8_STAGE(PG8_SB(0, 0), b2, voffB);
;             PG8_BAR; PG8_WAIT_L(0); PG8_MMA(0, 1, At, B1); PG8_BAR;
;             PG8_LDA(At, 0, 1); PG8_STAGE(PG8_SA(0, 0), a2, voffA);
;             PG8_BAR; PG8_WAIT_L(0); PG8_MMA(1, 0, At, B0); PG8_BAR; PG8_SCHED;
.LBB0_115:
	s_add_i32 s58, s52, 2
	s_add_u32 s59, s44, 0x80
	s_addc_u32 s53, s45, 0
	s_add_i32 s91, 0, 0x10000
	v_add_u32_e32 v86, s91, v192
	ds_read_b128 v[70:73], v86
	ds_read_b128 v[74:77], v86 offset:1024
	ds_read_b128 v[82:85], v86 offset:2048
	ds_read_b128 v[86:89], v86 offset:3072
	s_cmp_eq_u32 s57, s52
	s_cselect_b32 s52, s4, s59
	s_cselect_b32 s53, s5, s53
	s_cselect_b32 s75, s47, vcc_hi
	s_cselect_b32 s74, s46, vcc_lo
	v_lshl_add_u64 v[188:189], s[44:45], 0, v[176:177]
	s_add_i32 m0, s20, 0xc000
	ds_read_b128 v[138:141], v194
	ds_read_b128 v[142:145], v194 offset:1024
	ds_read_b128 v[146:149], v194 offset:2048
	ds_read_b128 v[154:157], v194 offset:3072
	ds_read_b128 v[162:165], v194 offset:4096
	ds_read_b128 v[166:169], v194 offset:5120
	ds_read_b128 v[170:173], v194 offset:6144
	ds_read_b128 v[184:187], v194 offset:7168
	global_load_lds_dwordx4 v[188:189], off
	v_lshl_add_u64 v[188:189], s[44:45], 0, v[182:183]
	s_add_i32 m0, s20, 0xe000
	s_nop 0
	global_load_lds_dwordx4 v[188:189], off
	s_waitcnt lgkmcnt(8)
	s_barrier
	s_waitcnt lgkmcnt(0)
	s_waitcnt lgkmcnt(0)
	v_mfma_f32_16x16x32_bf16 v[158:161], v[70:73], v[138:141], v[158:161]
	v_mfma_f32_16x16x32_bf16 v[150:153], v[82:85], v[138:141], v[150:153]
	v_mfma_f32_16x16x32_bf16 v[126:129], v[70:73], v[146:149], v[126:129]
	v_mfma_f32_16x16x32_bf16 v[122:125], v[82:85], v[146:149], v[122:125]
	v_mfma_f32_16x16x32_bf16 v[110:113], v[70:73], v[162:165], v[110:113]
	v_mfma_f32_16x16x32_bf16 v[106:109], v[82:85], v[162:165], v[106:109]
	v_mfma_f32_16x16x32_bf16 v[94:97], v[70:73], v[170:173], v[94:97]
	v_mfma_f32_16x16x32_bf16 v[90:93], v[82:85], v[170:173], v[90:93]
	v_mfma_f32_16x16x32_bf16 v[158:161], v[74:77], v[142:145], v[158:161]
	v_mfma_f32_16x16x32_bf16 v[150:153], v[86:89], v[142:145], v[150:153]
	v_mfma_f32_16x16x32_bf16 v[126:129], v[74:77], v[154:157], v[126:129]
	v_mfma_f32_16x16x32_bf16 v[122:125], v[86:89], v[154:157], v[122:125]
	v_mfma_f32_16x16x32_bf16 v[110:113], v[74:77], v[166:169], v[110:113]
	v_mfma_f32_16x16x32_bf16 v[106:109], v[86:89], v[166:169], v[106:109]
	v_mfma_f32_16x16x32_bf16 v[94:97], v[74:77], v[184:187], v[94:97]
	v_mfma_f32_16x16x32_bf16 v[90:93], v[86:89], v[184:187], v[90:93]
	s_barrier
	s_add_i32 s59, 0, 0x14000
	s_add_i32 s91, s91, s9
	v_add_u32_e32 v195, s59, v192
	v_lshl_add_u64 v[228:229], s[74:75], 0, v[0:1]
	s_mov_b32 m0, s91
	ds_read_b128 v[188:191], v195
	ds_read_b128 v[196:199], v195 offset:1024
	ds_read_b128 v[220:223], v195 offset:2048
	ds_read_b128 v[224:227], v195 offset:3072
	global_load_lds_dwordx4 v[228:229], off
	v_lshl_add_u64 v[230:231], s[74:75], 0, v[174:175]
	s_add_i32 m0, s91, 0x2000
	s_nop 0
	global_load_lds_dwordx4 v[230:231], off
	s_barrier
	s_waitcnt lgkmcnt(0)
	s_waitcnt lgkmcnt(0)
	v_mfma_f32_16x16x32_bf16 v[134:137], v[188:191], v[138:141], v[134:137]
	v_mfma_f32_16x16x32_bf16 v[130:133], v[220:223], v[138:141], v[130:133]
	v_mfma_f32_16x16x32_bf16 v[118:121], v[188:191], v[146:149], v[118:121]
	v_mfma_f32_16x16x32_bf16 v[114:117], v[220:223], v[146:149], v[114:117]
	v_mfma_f32_16x16x32_bf16 v[102:105], v[188:191], v[162:165], v[102:105]
	v_mfma_f32_16x16x32_bf16 v[98:101], v[220:223], v[162:165], v[98:101]
	v_mfma_f32_16x16x32_bf16 v[78:81], v[188:191], v[170:173], v[78:81]
	v_mfma_f32_16x16x32_bf16 v[66:69], v[220:223], v[170:173], v[66:69]
	v_mfma_f32_16x16x32_bf16 v[134:137], v[196:199], v[142:145], v[134:137]
	v_mfma_f32_16x16x32_bf16 v[130:133], v[224:227], v[142:145], v[130:133]
	v_mfma_f32_16x16x32_bf16 v[118:121], v[196:199], v[154:157], v[118:121]
	v_mfma_f32_16x16x32_bf16 v[114:117], v[224:227], v[154:157], v[114:117]
	v_mfma_f32_16x16x32_bf16 v[102:105], v[196:199], v[166:169], v[102:105]
	v_mfma_f32_16x16x32_bf16 v[98:101], v[224:227], v[166:169], v[98:101]
	v_mfma_f32_16x16x32_bf16 v[78:81], v[196:199], v[184:187], v[78:81]
	v_mfma_f32_16x16x32_bf16 v[66:69], v[224:227], v[184:187], v[66:69]
	s_mov_b32 m0, s20
	v_lshl_add_u64 v[232:233], s[52:53], 0, v[0:1]
	s_barrier
	ds_read_b128 v[138:141], v194 offset:16384
	ds_read_b128 v[142:145], v194 offset:17408
	ds_read_b128 v[146:149], v194 offset:18432
	ds_read_b128 v[154:157], v194 offset:19456
	ds_read_b128 v[162:165], v194 offset:20480
	ds_read_b128 v[166:169], v194 offset:21504
	ds_read_b128 v[170:173], v194 offset:22528
	ds_read_b128 v[184:187], v194 offset:23552
	global_load_lds_dwordx4 v[232:233], off
	v_lshl_add_u64 v[234:235], s[52:53], 0, v[174:175]
	s_mov_b32 m0, s21
	s_nop 0
	global_load_lds_dwordx4 v[234:235], off
	s_barrier
	s_waitcnt lgkmcnt(0)
	s_waitcnt lgkmcnt(0)
	v_mfma_f32_16x16x32_bf16 v[62:65], v[70:73], v[138:141], v[62:65]
	v_mfma_f32_16x16x32_bf16 v[58:61], v[82:85], v[138:141], v[58:61]
	v_mfma_f32_16x16x32_bf16 v[46:49], v[70:73], v[146:149], v[46:49]
	v_mfma_f32_16x16x32_bf16 v[42:45], v[82:85], v[146:149], v[42:45]
	v_mfma_f32_16x16x32_bf16 v[30:33], v[70:73], v[162:165], v[30:33]
	v_mfma_f32_16x16x32_bf16 v[26:29], v[82:85], v[162:165], v[26:29]
	v_mfma_f32_16x16x32_bf16 v[14:17], v[70:73], v[170:173], v[14:17]
	v_mfma_f32_16x16x32_bf16 v[10:13], v[82:85], v[170:173], v[10:13]
	v_mfma_f32_16x16x32_bf16 v[62:65], v[74:77], v[142:145], v[62:65]
	v_mfma_f32_16x16x32_bf16 v[58:61], v[86:89], v[142:145], v[58:61]
	v_mfma_f32_16x16x32_bf16 v[46:49], v[74:77], v[154:157], v[46:49]
	v_mfma_f32_16x16x32_bf16 v[42:45], v[86:89], v[154:157], v[42:45]
	v_mfma_f32_16x16x32_bf16 v[30:33], v[74:77], v[166:169], v[30:33]
	v_mfma_f32_16x16x32_bf16 v[26:29], v[86:89], v[166:169], v[26:29]
	v_mfma_f32_16x16x32_bf16 v[14:17], v[74:77], v[184:187], v[14:17]
	v_mfma_f32_16x16x32_bf16 v[10:13], v[86:89], v[184:187], v[10:13]
	s_barrier
; #define PG8_STAGE(bufoff, gbase, voff) do { _Pragma("unroll") for (int _i = 0; _i < 2; ++_i) \
;         __builtin_amdgcn_global_load_lds((const unsigned*)((const char*)(gbase) + (voff)[_i]), (LAS unsigned*)(lds + (bufoff) + ldsw + _i * 8192), 16, 0, 0); } while (0)
; #define PG8_LDA(dst, b, h) do { _Pragma("unroll") for (int m = 0; m < 4; ++m) _Pragma("unroll") for (int k = 0; k < 2; ++k) dst[m][k] = *(const LAS bf16x8*)(lds + PG8_SA(b, h) + aoff + m * 2048 + k * 1024); } while (0)
; #define PG8_LDB(dst, b, h) do { _Pragma("unroll") for (int n = 0; n < 2; ++n) _Pragma("unroll") for (int k = 0; k < 2; ++k) dst[n][k] = *(const LAS bf16x8*)(lds + PG8_SB(b, h) + boff + n * 2048 + k * 1024); } while (0)
; #define PG8_MMA(ai, bj, At, Bt) do { __builtin_amdgcn_s_setprio(1); _Pragma("unroll") for (int m = 0; m < 4; ++m) _Pragma("unroll") for (int n = 0; n < 2; ++n) _Pragma("unroll") for (int k = 0; k < 2; ++k) \
;         acc[ai][bj][m][n] = __builtin_amdgcn_mfma_f32_16x16x32_bf16(Bt[n][k], At[m][k], acc[ai][bj][m][n], 0, 0, 0); __builtin_amdgcn_s_setprio(0); } while (0)
; #define PG8_WAIT_V(n) asm volatile("s_waitcnt vmcnt(" #n ")" ::: "memory")
; #define PG8_WAIT_L(n) asm volatile("s_waitcnt lgkmcnt(" #n ")" ::: "memory")
; #define PG8_BAR __builtin_amdgcn_s_barrier()
; #define PG8_SCHED __builtin_amdgcn_sched_barrier(0)
; template <int MODE, class EpiT, class Sched>
; __device__ __forceinline__ void gemm_phase(LAS unsigned char* lds, const Gemm g, const Sched& S, const EpiT& E) {
;     ...
;             PG8_BAR; PG8_WAIT_L(0); PG8_MMA(1, 0, At, B0); PG8_BAR; PG8_SCHED;
;             PG8_STAGE(PG8_SB(0, 1), b2 + hstep, voffB);
;             PG8_WAIT_V(6); PG8_BAR; PG8_MMA(1, 1, At, B1); PG8_BAR;
;             PG8_LDB(B0, 1, 0); PG8_SCHED; PG8_LDA(At, 1, 0); PG8_STAGE(PG8_SA(0, 1), a2 + hstep, voffA);
;             PG8_WAIT_L(8); PG8_BAR; PG8_WAIT_L(0); PG8_MMA(0, 0, At, B0); PG8_BAR; PG8_SCHED;
;             PG8_LDB(B1, 1, 1); PG8_STAGE(PG8_SB(1, 0), b3, voffB);
;             PG8_BAR; PG8_WAIT_L(0); PG8_MMA(0, 1, At, B1); PG8_BAR;
;             PG8_LDA(At, 1, 1); PG8_STAGE(PG8_SA(1, 0), a3, voffA);
	s_add_u32 s74, s74, s78
	s_addc_u32 s75, s75, 0
	s_add_i32 s59, s59, s9
	v_lshl_add_u64 v[236:237], s[74:75], 0, v[0:1]
	s_mov_b32 m0, s59
	v_lshl_add_u64 v[238:239], s[74:75], 0, v[174:175]
	global_load_lds_dwordx4 v[236:237], off
	s_add_i32 m0, s59, 0x2000
	s_nop 0
	global_load_lds_dwordx4 v[238:239], off
	s_waitcnt vmcnt(6)
	s_barrier
	v_mfma_f32_16x16x32_bf16 v[54:57], v[188:191], v[138:141], v[54:57]
	v_mfma_f32_16x16x32_bf16 v[50:53], v[220:223], v[138:141], v[50:53]
	v_mfma_f32_16x16x32_bf16 v[38:41], v[188:191], v[146:149], v[38:41]
	v_mfma_f32_16x16x32_bf16 v[34:37], v[220:223], v[146:149], v[34:37]
	v_mfma_f32_16x16x32_bf16 v[22:25], v[188:191], v[162:165], v[22:25]
	v_mfma_f32_16x16x32_bf16 v[18:21], v[220:223], v[162:165], v[18:21]
	v_mfma_f32_16x16x32_bf16 v[6:9], v[188:191], v[170:173], v[6:9]
	v_mfma_f32_16x16x32_bf16 v[2:5], v[220:223], v[170:173], v[2:5]
	v_mfma_f32_16x16x32_bf16 v[54:57], v[196:199], v[142:145], v[54:57]
	v_mfma_f32_16x16x32_bf16 v[50:53], v[224:227], v[142:145], v[50:53]
	v_mfma_f32_16x16x32_bf16 v[38:41], v[196:199], v[154:157], v[38:41]
	v_mfma_f32_16x16x32_bf16 v[34:37], v[224:227], v[154:157], v[34:37]
	v_mfma_f32_16x16x32_bf16 v[22:25], v[196:199], v[166:169], v[22:25]
	v_mfma_f32_16x16x32_bf16 v[18:21], v[224:227], v[166:169], v[18:21]
	v_mfma_f32_16x16x32_bf16 v[6:9], v[196:199], v[184:187], v[6:9]
	v_mfma_f32_16x16x32_bf16 v[2:5], v[224:227], v[184:187], v[2:5]
	s_add_i32 s59, 0, 0x18000
	v_add_u32_e32 v86, s59, v192
	s_barrier
	ds_read_b128 v[70:73], v86
	ds_read_b128 v[74:77], v86 offset:1024
	ds_read_b128 v[82:85], v86 offset:2048
	ds_read_b128 v[86:89], v86 offset:3072
	s_add_u32 s52, s52, s78
	s_addc_u32 s53, s53, 0
	s_mov_b32 m0, s22
	v_lshl_add_u64 v[188:189], s[52:53], 0, v[0:1]
	ds_read_b128 v[138:141], v194 offset:32768
	ds_read_b128 v[142:145], v194 offset:33792
	ds_read_b128 v[146:149], v194 offset:34816
	ds_read_b128 v[154:157], v194 offset:35840
	ds_read_b128 v[162:165], v194 offset:36864
	ds_read_b128 v[166:169], v194 offset:37888
	ds_read_b128 v[170:173], v194 offset:38912
	ds_read_b128 v[184:187], v194 offset:39936
	global_load_lds_dwordx4 v[188:189], off
	v_lshl_add_u64 v[188:189], s[52:53], 0, v[174:175]
	s_mov_b32 m0, s23
	s_nop 0
	global_load_lds_dwordx4 v[188:189], off
	s_waitcnt lgkmcnt(8)
	s_barrier
	s_waitcnt lgkmcnt(0)
	s_waitcnt lgkmcnt(0)
	v_mfma_f32_16x16x32_bf16 v[158:161], v[70:73], v[138:141], v[158:161]
	v_mfma_f32_16x16x32_bf16 v[150:153], v[82:85], v[138:141], v[150:153]
	v_mfma_f32_16x16x32_bf16 v[126:129], v[70:73], v[146:149], v[126:129]
	v_mfma_f32_16x16x32_bf16 v[122:125], v[82:85], v[146:149], v[122:125]
	v_mfma_f32_16x16x32_bf16 v[110:113], v[70:73], v[162:165], v[110:113]
	v_mfma_f32_16x16x32_bf16 v[106:109], v[82:85], v[162:165], v[106:109]
	v_mfma_f32_16x16x32_bf16 v[94:97], v[70:73], v[170:173], v[94:97]
	v_mfma_f32_16x16x32_bf16 v[90:93], v[82:85], v[170:173], v[90:93]
	v_mfma_f32_16x16x32_bf16 v[158:161], v[74:77], v[142:145], v[158:161]
	v_mfma_f32_16x16x32_bf16 v[150:153], v[86:89], v[142:145], v[150:153]
	v_mfma_f32_16x16x32_bf16 v[126:129], v[74:77], v[154:157], v[126:129]
	v_mfma_f32_16x16x32_bf16 v[122:125], v[86:89], v[154:157], v[122:125]
	v_mfma_f32_16x16x32_bf16 v[110:113], v[74:77], v[166:169], v[110:113]
	v_mfma_f32_16x16x32_bf16 v[106:109], v[86:89], v[166:169], v[106:109]
	v_mfma_f32_16x16x32_bf16 v[94:97], v[74:77], v[184:187], v[94:97]
	v_mfma_f32_16x16x32_bf16 v[90:93], v[86:89], v[184:187], v[90:93]
	s_barrier
	s_add_i32 s52, 0, 0x1c000
	s_add_i32 s53, s59, s9
	v_add_u32_e32 v195, s52, v192
	v_lshl_add_u64 v[228:229], v[228:229], 0, s[76:77]
	s_mov_b32 m0, s53
	ds_read_b128 v[188:191], v195
	ds_read_b128 v[196:199], v195 offset:1024
	ds_read_b128 v[220:223], v195 offset:2048
	ds_read_b128 v[224:227], v195 offset:3072
	global_load_lds_dwordx4 v[228:229], off
	v_lshl_add_u64 v[228:229], v[230:231], 0, s[76:77]
	s_add_i32 m0, s53, 0x2000
	s_nop 0
	global_load_lds_dwordx4 v[228:229], off
	s_barrier
; #define PG8_STAGE(bufoff, gbase, voff) do { _Pragma("unroll") for (int _i = 0; _i < 2; ++_i) \
;         __builtin_amdgcn_global_load_lds((const unsigned*)((const char*)(gbase) + (voff)[_i]), (LAS unsigned*)(lds + (bufoff) + ldsw + _i * 8192), 16, 0, 0); } while (0)
; #define PG8_LDA(dst, b, h) do { _Pragma("unroll") for (int m = 0; m < 4; ++m) _Pragma("unroll") for (int k = 0; k < 2; ++k) dst[m][k] = *(const LAS bf16x8*)(lds + PG8_SA(b, h) + aoff + m * 2048 + k * 1024); } while (0)
; #define PG8_MMA(ai, bj, At, Bt) do { __builtin_amdgcn_s_setprio(1); _Pragma("unroll") for (int m = 0; m < 4; ++m) _Pragma("unroll") for (int n = 0; n < 2; ++n) _Pragma("unroll") for (int k = 0; k < 2; ++k) \
;         acc[ai][bj][m][n] = __builtin_amdgcn_mfma_f32_16x16x32_bf16(Bt[n][k], At[m][k], acc[ai][bj][m][n], 0, 0, 0); __builtin_amdgcn_s_setprio(0); } while (0)
; #define PG8_WAIT_V(n) asm volatile("s_waitcnt vmcnt(" #n ")" ::: "memory")
; #define PG8_WAIT_L(n) asm volatile("s_waitcnt lgkmcnt(" #n ")" ::: "memory")
; #define PG8_BAR __builtin_amdgcn_s_barrier()
; #define PG8_SCHED __builtin_amdgcn_sched_barrier(0)
; template <int MODE, class EpiT, class Sched>
; __device__ __forceinline__ void gemm_phase(LAS unsigned char* lds, const Gemm g, const Sched& S, const EpiT& E) {
;     ...
;             PG8_LDA(At, 1, 1); PG8_STAGE(PG8_SA(1, 0), a3, voffA);
;             PG8_BAR; PG8_WAIT_L(0); PG8_MMA(1, 0, At, B0); PG8_BAR; PG8_SCHED;
;             PG8_STAGE(PG8_SB(1, 1), b3 + hstep, voffB);
;             PG8_WAIT_V(6); PG8_BAR; PG8_MMA(1, 1, At, B1); PG8_BAR;
;         }
	s_waitcnt lgkmcnt(0)
	s_waitcnt lgkmcnt(0)
	v_mfma_f32_16x16x32_bf16 v[134:137], v[188:191], v[138:141], v[134:137]
	v_mfma_f32_16x16x32_bf16 v[130:133], v[220:223], v[138:141], v[130:133]
	v_mfma_f32_16x16x32_bf16 v[118:121], v[188:191], v[146:149], v[118:121]
	v_mfma_f32_16x16x32_bf16 v[114:117], v[220:223], v[146:149], v[114:117]
	v_mfma_f32_16x16x32_bf16 v[102:105], v[188:191], v[162:165], v[102:105]
	v_mfma_f32_16x16x32_bf16 v[98:101], v[220:223], v[162:165], v[98:101]
	v_mfma_f32_16x16x32_bf16 v[78:81], v[188:191], v[170:173], v[78:81]
	v_mfma_f32_16x16x32_bf16 v[66:69], v[220:223], v[170:173], v[66:69]
	v_mfma_f32_16x16x32_bf16 v[134:137], v[196:199], v[142:145], v[134:137]
	v_mfma_f32_16x16x32_bf16 v[130:133], v[224:227], v[142:145], v[130:133]
	v_mfma_f32_16x16x32_bf16 v[118:121], v[196:199], v[154:157], v[118:121]
	v_mfma_f32_16x16x32_bf16 v[114:117], v[224:227], v[154:157], v[114:117]
	v_mfma_f32_16x16x32_bf16 v[102:105], v[196:199], v[166:169], v[102:105]
	v_mfma_f32_16x16x32_bf16 v[98:101], v[224:227], v[166:169], v[98:101]
	v_mfma_f32_16x16x32_bf16 v[78:81], v[196:199], v[184:187], v[78:81]
	v_mfma_f32_16x16x32_bf16 v[66:69], v[224:227], v[184:187], v[66:69]
	s_mov_b32 m0, s51
	v_lshl_add_u64 v[228:229], v[232:233], 0, s[76:77]
	s_barrier
	ds_read_b128 v[138:141], v194 offset:49152
	ds_read_b128 v[142:145], v194 offset:50176
	ds_read_b128 v[146:149], v194 offset:51200
	ds_read_b128 v[154:157], v194 offset:52224
	ds_read_b128 v[162:165], v194 offset:53248
	ds_read_b128 v[166:169], v194 offset:54272
	ds_read_b128 v[170:173], v194 offset:55296
	ds_read_b128 v[184:187], v194 offset:56320
	global_load_lds_dwordx4 v[228:229], off
	v_lshl_add_u64 v[228:229], v[234:235], 0, s[76:77]
	s_mov_b32 m0, s56
	s_nop 0
	global_load_lds_dwordx4 v[228:229], off
	s_barrier
	s_waitcnt lgkmcnt(0)
	s_waitcnt lgkmcnt(0)
	v_mfma_f32_16x16x32_bf16 v[62:65], v[70:73], v[138:141], v[62:65]
	v_mfma_f32_16x16x32_bf16 v[58:61], v[82:85], v[138:141], v[58:61]
	v_mfma_f32_16x16x32_bf16 v[46:49], v[70:73], v[146:149], v[46:49]
	v_mfma_f32_16x16x32_bf16 v[42:45], v[82:85], v[146:149], v[42:45]
	v_mfma_f32_16x16x32_bf16 v[30:33], v[70:73], v[162:165], v[30:33]
	v_mfma_f32_16x16x32_bf16 v[26:29], v[82:85], v[162:165], v[26:29]
	v_mfma_f32_16x16x32_bf16 v[14:17], v[70:73], v[170:173], v[14:17]
	v_mfma_f32_16x16x32_bf16 v[10:13], v[82:85], v[170:173], v[10:13]
	v_mfma_f32_16x16x32_bf16 v[62:65], v[74:77], v[142:145], v[62:65]
	v_mfma_f32_16x16x32_bf16 v[58:61], v[86:89], v[142:145], v[58:61]
	v_mfma_f32_16x16x32_bf16 v[46:49], v[74:77], v[154:157], v[46:49]
	v_mfma_f32_16x16x32_bf16 v[42:45], v[86:89], v[154:157], v[42:45]
	v_mfma_f32_16x16x32_bf16 v[30:33], v[74:77], v[166:169], v[30:33]
	v_mfma_f32_16x16x32_bf16 v[26:29], v[86:89], v[166:169], v[26:29]
	v_mfma_f32_16x16x32_bf16 v[14:17], v[74:77], v[184:187], v[14:17]
	v_mfma_f32_16x16x32_bf16 v[10:13], v[86:89], v[184:187], v[10:13]
	s_barrier
	s_add_i32 s52, s52, s9
	v_lshl_add_u64 v[70:71], v[236:237], 0, s[76:77]
	s_mov_b32 m0, s52
	s_nop 0
	global_load_lds_dwordx4 v[70:71], off
	v_lshl_add_u64 v[70:71], v[238:239], 0, s[76:77]
	s_add_i32 m0, s52, 0x2000
	s_nop 0
	global_load_lds_dwordx4 v[70:71], off
	s_waitcnt vmcnt(6)
	s_barrier
	v_mfma_f32_16x16x32_bf16 v[54:57], v[188:191], v[138:141], v[54:57]
	v_mfma_f32_16x16x32_bf16 v[50:53], v[220:223], v[138:141], v[50:53]
	v_mfma_f32_16x16x32_bf16 v[38:41], v[188:191], v[146:149], v[38:41]
	v_mfma_f32_16x16x32_bf16 v[34:37], v[220:223], v[146:149], v[34:37]
	v_mfma_f32_16x16x32_bf16 v[22:25], v[188:191], v[162:165], v[22:25]
	v_mfma_f32_16x16x32_bf16 v[18:21], v[220:223], v[162:165], v[18:21]
	v_mfma_f32_16x16x32_bf16 v[6:9], v[188:191], v[170:173], v[6:9]
	v_mfma_f32_16x16x32_bf16 v[2:5], v[220:223], v[170:173], v[2:5]
	v_mfma_f32_16x16x32_bf16 v[54:57], v[196:199], v[142:145], v[54:57]
	v_mfma_f32_16x16x32_bf16 v[50:53], v[224:227], v[142:145], v[50:53]
	v_mfma_f32_16x16x32_bf16 v[38:41], v[196:199], v[154:157], v[38:41]
	v_mfma_f32_16x16x32_bf16 v[34:37], v[224:227], v[154:157], v[34:37]
	v_mfma_f32_16x16x32_bf16 v[22:25], v[196:199], v[166:169], v[22:25]
	v_mfma_f32_16x16x32_bf16 v[18:21], v[224:227], v[166:169], v[18:21]
	v_mfma_f32_16x16x32_bf16 v[6:9], v[196:199], v[184:187], v[6:9]
	v_mfma_f32_16x16x32_bf16 v[2:5], v[224:227], v[184:187], v[2:5]
	s_add_u32 s44, s44, 0x100
	s_addc_u32 s45, s45, 0
	s_add_u32 vcc_lo, vcc_lo, 0x100
	s_addc_u32 vcc_hi, vcc_hi, 0
	s_cmp_ge_u32 s58, s50
	s_mov_b32 s52, s58
	s_barrier
	s_cbranch_scc0 .LBB0_115
	v_lshl_or_b32 v184, s24, 8, v193
	v_ashrrev_i32_e32 v185, 31, v184
	v_mov_b32_e32 v74, 0
	v_cndmask_b32_e64 v70, 0, 1, s[68:69]
	v_lshl_add_u64 v[138:139], v[184:185], 2, s[12:13]
	v_cmp_ne_u32_e64 s[44:45], 1, v70
	s_andn2_b64 vcc, exec, s[68:69]
	v_mov_b32_e32 v86, 0
	v_mov_b32_e32 v87, v74
	v_mov_b32_e32 v186, 0
	v_mov_b32_e32 v187, v74
	s_cbranch_vccnz .LBB0_118
	global_load_dwordx4 v[86:89], v[138:139], off
	s_waitcnt vmcnt(0)
	v_mov_b32_e32 v186, v88
	v_mov_b32_e32 v187, v89

; #define PG8_STAGE(bufoff, gbase, voff) do { _Pragma("unroll") for (int _i = 0; _i < 2; ++_i) \
;         __builtin_amdgcn_global_load_lds((const unsigned*)((const char*)(gbase) + (voff)[_i]), (LAS unsigned*)(lds + (bufoff) + ldsw + _i * 8192), 16, 0, 0); } while (0)
; #define PG8_LDA(dst, b, h) do { _Pragma("unroll") for (int m = 0; m < 4; ++m) _Pragma("unroll") for (int k = 0; k < 2; ++k) dst[m][k] = *(const LAS bf16x8*)(lds + PG8_SA(b, h) + aoff + m * 2048 + k * 1024); } while (0)
; #define PG8_LDB(dst, b, h) do { _Pragma("unroll") for (int n = 0; n < 2; ++n) _Pragma("unroll") for (int k = 0; k < 2; ++k) dst[n][k] = *(const LAS bf16x8*)(lds + PG8_SB(b, h) + boff + n * 2048 + k * 1024); } while (0)
; #define PG8_MMA(ai, bj, At, Bt) do { __builtin_amdgcn_s_setprio(1); _Pragma("unroll") for (int m = 0; m < 4; ++m) _Pragma("unroll") for (int n = 0; n < 2; ++n) _Pragma("unroll") for (int k = 0; k < 2; ++k) \
;         acc[ai][bj][m][n] = __builtin_amdgcn_mfma_f32_16x16x32_bf16(Bt[n][k], At[m][k], acc[ai][bj][m][n], 0, 0, 0); __builtin_amdgcn_s_setprio(0); } while (0)
; #define PG8_WAIT_L(n) asm volatile("s_waitcnt lgkmcnt(" #n ")" ::: "memory")
; #define PG8_BAR __builtin_amdgcn_s_barrier()
; #define PG8_SCHED __builtin_amdgcn_sched_barrier(0)
; template <int MODE, class EpiT, class Sched>
; __device__ __forceinline__ void gemm_phase(LAS unsigned char* lds, const Gemm g, const Sched& S, const EpiT& E) {
;     ...
;         for (int t = 0; t < nt; t += 2) {
;             const bool last = (t == nt - 2);
;             const char* a1 = cA + (size_t)(t + 1) * kstep;
;             const char* a2 = last ? nA : cA + (size_t)(t + 2) * kstep; const char* b2 = last ? nB : cB + (size_t)(t + 2) * kstep;
;             const char* a3 = a2 + kstep; const char* b3 = b2 + kstep;
;             PG8_LDB(B0, 0, 0); PG8_SCHED; PG8_LDA(At, 0, 0); PG8_STAGE(PG8_SA(1, 1), a1 + hstep, voffA);
;             PG8_WAIT_L(8); PG8_BAR; PG8_WAIT_L(0); PG8_MMA(0, 0, At, B0); PG8_BAR; PG8_SCHED;
;             PG8_LDB(B1, 0, 1); PG8_STAGE(PG8_SB(0, 0), b2, voffB);
;             PG8_BAR; PG8_WAIT_L(0); PG8_MMA(0, 1, At, B1); PG8_BAR;
;             PG8_LDA(At, 0, 1); PG8_STAGE(PG8_SA(0, 0), a2, voffA);
;             PG8_BAR; PG8_WAIT_L(0); PG8_MMA(1, 0, At, B0); PG8_BAR; PG8_SCHED;
.LBB0_159:
	s_add_i32 s89, s30, 2
	s_add_u32 s44, s4, 0x80
	s_addc_u32 s45, s5, 0
	s_add_i32 s58, 0, 0x10000
	v_add_u32_e32 v142, s58, v220
	ds_read_b128 v[130:133], v142
	ds_read_b128 v[134:137], v142 offset:1024
	ds_read_b128 v[138:141], v142 offset:2048
	ds_read_b128 v[142:145], v142 offset:3072
	s_cmp_eq_u32 s61, s30
	s_cselect_b32 s45, s79, s45
	s_cselect_b32 s44, s78, s44
	s_cselect_b32 s53, s47, s24
	s_cselect_b32 s52, s46, s23
	v_lshl_add_u64 v[188:189], s[4:5], 0, v[184:185]
	s_add_i32 m0, s69, 0xc000
	ds_read_b128 v[146:149], v223
	ds_read_b128 v[150:153], v223 offset:1024
	ds_read_b128 v[154:157], v223 offset:2048
	ds_read_b128 v[158:161], v223 offset:3072
	ds_read_b128 v[162:165], v223 offset:4096
	ds_read_b128 v[166:169], v223 offset:5120
	ds_read_b128 v[170:173], v223 offset:6144
	ds_read_b128 v[174:177], v223 offset:7168
	global_load_lds_dwordx4 v[188:189], off
	v_lshl_add_u64 v[188:189], s[4:5], 0, v[186:187]
	s_add_i32 m0, s69, 0xe000
	s_nop 0
	global_load_lds_dwordx4 v[188:189], off
	s_waitcnt lgkmcnt(8)
	s_barrier
	s_waitcnt lgkmcnt(0)
	s_waitcnt lgkmcnt(0)
	v_mfma_f32_16x16x32_bf16 v[126:129], v[130:133], v[146:149], v[126:129]
	v_mfma_f32_16x16x32_bf16 v[122:125], v[138:141], v[146:149], v[122:125]
	v_mfma_f32_16x16x32_bf16 v[110:113], v[130:133], v[154:157], v[110:113]
	v_mfma_f32_16x16x32_bf16 v[106:109], v[138:141], v[154:157], v[106:109]
	v_mfma_f32_16x16x32_bf16 v[94:97], v[130:133], v[162:165], v[94:97]
	v_mfma_f32_16x16x32_bf16 v[90:93], v[138:141], v[162:165], v[90:93]
	v_mfma_f32_16x16x32_bf16 v[78:81], v[130:133], v[170:173], v[78:81]
	v_mfma_f32_16x16x32_bf16 v[74:77], v[138:141], v[170:173], v[74:77]
	v_mfma_f32_16x16x32_bf16 v[126:129], v[134:137], v[150:153], v[126:129]
	v_mfma_f32_16x16x32_bf16 v[122:125], v[142:145], v[150:153], v[122:125]
	v_mfma_f32_16x16x32_bf16 v[110:113], v[134:137], v[158:161], v[110:113]
	v_mfma_f32_16x16x32_bf16 v[106:109], v[142:145], v[158:161], v[106:109]
	v_mfma_f32_16x16x32_bf16 v[94:97], v[134:137], v[166:169], v[94:97]
	v_mfma_f32_16x16x32_bf16 v[90:93], v[142:145], v[166:169], v[90:93]
	v_mfma_f32_16x16x32_bf16 v[78:81], v[134:137], v[174:177], v[78:81]
	v_mfma_f32_16x16x32_bf16 v[74:77], v[142:145], v[174:177], v[74:77]
	s_barrier
	s_add_i32 s30, 0, 0x14000
	s_add_i32 s58, s58, s68
	v_add_u32_e32 v200, s30, v220
	v_lshl_add_u64 v[228:229], s[52:53], 0, v[0:1]
	s_mov_b32 m0, s58
	ds_read_b128 v[188:191], v200
	ds_read_b128 v[192:195], v200 offset:1024
	ds_read_b128 v[196:199], v200 offset:2048
	ds_read_b128 v[224:227], v200 offset:3072
	global_load_lds_dwordx4 v[228:229], off
	v_lshl_add_u64 v[230:231], s[52:53], 0, v[182:183]
	s_add_i32 m0, s58, 0x2000
	s_nop 0
	global_load_lds_dwordx4 v[230:231], off
	s_barrier
	s_waitcnt lgkmcnt(0)
	s_waitcnt lgkmcnt(0)
	v_mfma_f32_16x16x32_bf16 v[118:121], v[188:191], v[146:149], v[118:121]
	v_mfma_f32_16x16x32_bf16 v[114:117], v[196:199], v[146:149], v[114:117]
	v_mfma_f32_16x16x32_bf16 v[102:105], v[188:191], v[154:157], v[102:105]
	v_mfma_f32_16x16x32_bf16 v[98:101], v[196:199], v[154:157], v[98:101]
	v_mfma_f32_16x16x32_bf16 v[86:89], v[188:191], v[162:165], v[86:89]
	v_mfma_f32_16x16x32_bf16 v[82:85], v[196:199], v[162:165], v[82:85]
	v_mfma_f32_16x16x32_bf16 v[70:73], v[188:191], v[170:173], v[70:73]
	v_mfma_f32_16x16x32_bf16 v[66:69], v[196:199], v[170:173], v[66:69]
	v_mfma_f32_16x16x32_bf16 v[118:121], v[192:195], v[150:153], v[118:121]
	v_mfma_f32_16x16x32_bf16 v[114:117], v[224:227], v[150:153], v[114:117]
	v_mfma_f32_16x16x32_bf16 v[102:105], v[192:195], v[158:161], v[102:105]
	v_mfma_f32_16x16x32_bf16 v[98:101], v[224:227], v[158:161], v[98:101]
	v_mfma_f32_16x16x32_bf16 v[86:89], v[192:195], v[166:169], v[86:89]
	v_mfma_f32_16x16x32_bf16 v[82:85], v[224:227], v[166:169], v[82:85]
	v_mfma_f32_16x16x32_bf16 v[70:73], v[192:195], v[174:177], v[70:73]
	v_mfma_f32_16x16x32_bf16 v[66:69], v[224:227], v[174:177], v[66:69]
	s_mov_b32 m0, s69
	v_lshl_add_u64 v[232:233], s[44:45], 0, v[0:1]
	s_barrier
	ds_read_b128 v[146:149], v223 offset:16384
	ds_read_b128 v[150:153], v223 offset:17408
	ds_read_b128 v[154:157], v223 offset:18432
	ds_read_b128 v[158:161], v223 offset:19456
	ds_read_b128 v[162:165], v223 offset:20480
	ds_read_b128 v[166:169], v223 offset:21504
	ds_read_b128 v[170:173], v223 offset:22528
	ds_read_b128 v[174:177], v223 offset:23552
	global_load_lds_dwordx4 v[232:233], off
	v_lshl_add_u64 v[234:235], s[44:45], 0, v[182:183]
	s_mov_b32 m0, s74
	s_nop 0
	global_load_lds_dwordx4 v[234:235], off
	s_barrier
	s_waitcnt lgkmcnt(0)
	s_waitcnt lgkmcnt(0)
	v_mfma_f32_16x16x32_bf16 v[62:65], v[130:133], v[146:149], v[62:65]
	v_mfma_f32_16x16x32_bf16 v[58:61], v[138:141], v[146:149], v[58:61]
	v_mfma_f32_16x16x32_bf16 v[46:49], v[130:133], v[154:157], v[46:49]
	v_mfma_f32_16x16x32_bf16 v[42:45], v[138:141], v[154:157], v[42:45]
	v_mfma_f32_16x16x32_bf16 v[30:33], v[130:133], v[162:165], v[30:33]
	v_mfma_f32_16x16x32_bf16 v[26:29], v[138:141], v[162:165], v[26:29]
	v_mfma_f32_16x16x32_bf16 v[14:17], v[130:133], v[170:173], v[14:17]
	v_mfma_f32_16x16x32_bf16 v[10:13], v[138:141], v[170:173], v[10:13]
	v_mfma_f32_16x16x32_bf16 v[62:65], v[134:137], v[150:153], v[62:65]
	v_mfma_f32_16x16x32_bf16 v[58:61], v[142:145], v[150:153], v[58:61]
	v_mfma_f32_16x16x32_bf16 v[46:49], v[134:137], v[158:161], v[46:49]
	v_mfma_f32_16x16x32_bf16 v[42:45], v[142:145], v[158:161], v[42:45]
	v_mfma_f32_16x16x32_bf16 v[30:33], v[134:137], v[166:169], v[30:33]
	v_mfma_f32_16x16x32_bf16 v[26:29], v[142:145], v[166:169], v[26:29]
	v_mfma_f32_16x16x32_bf16 v[14:17], v[134:137], v[174:177], v[14:17]
	v_mfma_f32_16x16x32_bf16 v[10:13], v[142:145], v[174:177], v[10:13]
	s_barrier
; #define PG8_STAGE(bufoff, gbase, voff) do { _Pragma("unroll") for (int _i = 0; _i < 2; ++_i) \
;         __builtin_amdgcn_global_load_lds((const unsigned*)((const char*)(gbase) + (voff)[_i]), (LAS unsigned*)(lds + (bufoff) + ldsw + _i * 8192), 16, 0, 0); } while (0)
; #define PG8_LDA(dst, b, h) do { _Pragma("unroll") for (int m = 0; m < 4; ++m) _Pragma("unroll") for (int k = 0; k < 2; ++k) dst[m][k] = *(const LAS bf16x8*)(lds + PG8_SA(b, h) + aoff + m * 2048 + k * 1024); } while (0)
; #define PG8_LDB(dst, b, h) do { _Pragma("unroll") for (int n = 0; n < 2; ++n) _Pragma("unroll") for (int k = 0; k < 2; ++k) dst[n][k] = *(const LAS bf16x8*)(lds + PG8_SB(b, h) + boff + n * 2048 + k * 1024); } while (0)
; #define PG8_MMA(ai, bj, At, Bt) do { __builtin_amdgcn_s_setprio(1); _Pragma("unroll") for (int m = 0; m < 4; ++m) _Pragma("unroll") for (int n = 0; n < 2; ++n) _Pragma("unroll") for (int k = 0; k < 2; ++k) \
;         acc[ai][bj][m][n] = __builtin_amdgcn_mfma_f32_16x16x32_bf16(Bt[n][k], At[m][k], acc[ai][bj][m][n], 0, 0, 0); __builtin_amdgcn_s_setprio(0); } while (0)
; #define PG8_WAIT_V(n) asm volatile("s_waitcnt vmcnt(" #n ")" ::: "memory")
; #define PG8_WAIT_L(n) asm volatile("s_waitcnt lgkmcnt(" #n ")" ::: "memory")
; #define PG8_BAR __builtin_amdgcn_s_barrier()
; #define PG8_SCHED __builtin_amdgcn_sched_barrier(0)
; template <int MODE, class EpiT, class Sched>
; __device__ __forceinline__ void gemm_phase(LAS unsigned char* lds, const Gemm g, const Sched& S, const EpiT& E) {
;     ...
;             PG8_BAR; PG8_WAIT_L(0); PG8_MMA(1, 0, At, B0); PG8_BAR; PG8_SCHED;
;             PG8_STAGE(PG8_SB(0, 1), b2 + hstep, voffB);
;             PG8_WAIT_V(6); PG8_BAR; PG8_MMA(1, 1, At, B1); PG8_BAR;
;             PG8_LDB(B0, 1, 0); PG8_SCHED; PG8_LDA(At, 1, 0); PG8_STAGE(PG8_SA(0, 1), a2 + hstep, voffA);
;             PG8_WAIT_L(8); PG8_BAR; PG8_WAIT_L(0); PG8_MMA(0, 0, At, B0); PG8_BAR; PG8_SCHED;
;             PG8_LDB(B1, 1, 1); PG8_STAGE(PG8_SB(1, 0), b3, voffB);
;             PG8_BAR; PG8_WAIT_L(0); PG8_MMA(0, 1, At, B1); PG8_BAR;
;             PG8_LDA(At, 1, 1); PG8_STAGE(PG8_SA(1, 0), a3, voffA);
;             PG8_BAR; PG8_WAIT_L(0); PG8_MMA(1, 0, At, B0); PG8_BAR; PG8_SCHED;
	s_add_u32 s52, s52, s38
	s_addc_u32 s53, s53, 0
	s_add_i32 s30, s30, s68
	v_lshl_add_u64 v[236:237], s[52:53], 0, v[0:1]
	s_mov_b32 m0, s30
	v_lshl_add_u64 v[238:239], s[52:53], 0, v[182:183]
	global_load_lds_dwordx4 v[236:237], off
	s_add_i32 m0, s30, 0x2000
	s_nop 0
	global_load_lds_dwordx4 v[238:239], off
	s_waitcnt vmcnt(6)
	s_barrier
	v_mfma_f32_16x16x32_bf16 v[54:57], v[188:191], v[146:149], v[54:57]
	v_mfma_f32_16x16x32_bf16 v[50:53], v[196:199], v[146:149], v[50:53]
	v_mfma_f32_16x16x32_bf16 v[38:41], v[188:191], v[154:157], v[38:41]
	v_mfma_f32_16x16x32_bf16 v[34:37], v[196:199], v[154:157], v[34:37]
	v_mfma_f32_16x16x32_bf16 v[22:25], v[188:191], v[162:165], v[22:25]
	v_mfma_f32_16x16x32_bf16 v[18:21], v[196:199], v[162:165], v[18:21]
	v_mfma_f32_16x16x32_bf16 v[6:9], v[188:191], v[170:173], v[6:9]
	v_mfma_f32_16x16x32_bf16 v[2:5], v[196:199], v[170:173], v[2:5]
	v_mfma_f32_16x16x32_bf16 v[54:57], v[192:195], v[150:153], v[54:57]
	v_mfma_f32_16x16x32_bf16 v[50:53], v[224:227], v[150:153], v[50:53]
	v_mfma_f32_16x16x32_bf16 v[38:41], v[192:195], v[158:161], v[38:41]
	v_mfma_f32_16x16x32_bf16 v[34:37], v[224:227], v[158:161], v[34:37]
	v_mfma_f32_16x16x32_bf16 v[22:25], v[192:195], v[166:169], v[22:25]
	v_mfma_f32_16x16x32_bf16 v[18:21], v[224:227], v[166:169], v[18:21]
	v_mfma_f32_16x16x32_bf16 v[6:9], v[192:195], v[174:177], v[6:9]
	v_mfma_f32_16x16x32_bf16 v[2:5], v[224:227], v[174:177], v[2:5]
	s_add_i32 s30, 0, 0x18000
	v_add_u32_e32 v142, s30, v220
	s_barrier
	ds_read_b128 v[130:133], v142
	ds_read_b128 v[134:137], v142 offset:1024
	ds_read_b128 v[138:141], v142 offset:2048
	ds_read_b128 v[142:145], v142 offset:3072
	s_add_u32 s44, s44, s38
	s_addc_u32 s45, s45, 0
	s_mov_b32 m0, s75
	v_lshl_add_u64 v[188:189], s[44:45], 0, v[0:1]
	ds_read_b128 v[146:149], v223 offset:32768
	ds_read_b128 v[150:153], v223 offset:33792
	ds_read_b128 v[154:157], v223 offset:34816
	ds_read_b128 v[158:161], v223 offset:35840
	ds_read_b128 v[162:165], v223 offset:36864
	ds_read_b128 v[166:169], v223 offset:37888
	ds_read_b128 v[170:173], v223 offset:38912
	ds_read_b128 v[174:177], v223 offset:39936
	global_load_lds_dwordx4 v[188:189], off
	v_lshl_add_u64 v[188:189], s[44:45], 0, v[182:183]
	s_mov_b32 m0, s9
	s_nop 0
	global_load_lds_dwordx4 v[188:189], off
	s_waitcnt lgkmcnt(8)
	s_barrier
	s_waitcnt lgkmcnt(0)
	s_waitcnt lgkmcnt(0)
	v_mfma_f32_16x16x32_bf16 v[126:129], v[130:133], v[146:149], v[126:129]
	v_mfma_f32_16x16x32_bf16 v[122:125], v[138:141], v[146:149], v[122:125]
	v_mfma_f32_16x16x32_bf16 v[110:113], v[130:133], v[154:157], v[110:113]
	v_mfma_f32_16x16x32_bf16 v[106:109], v[138:141], v[154:157], v[106:109]
	v_mfma_f32_16x16x32_bf16 v[94:97], v[130:133], v[162:165], v[94:97]
	v_mfma_f32_16x16x32_bf16 v[90:93], v[138:141], v[162:165], v[90:93]
	v_mfma_f32_16x16x32_bf16 v[78:81], v[130:133], v[170:173], v[78:81]
	v_mfma_f32_16x16x32_bf16 v[74:77], v[138:141], v[170:173], v[74:77]
	v_mfma_f32_16x16x32_bf16 v[126:129], v[134:137], v[150:153], v[126:129]
	v_mfma_f32_16x16x32_bf16 v[122:125], v[142:145], v[150:153], v[122:125]
	v_mfma_f32_16x16x32_bf16 v[110:113], v[134:137], v[158:161], v[110:113]
	v_mfma_f32_16x16x32_bf16 v[106:109], v[142:145], v[158:161], v[106:109]
	v_mfma_f32_16x16x32_bf16 v[94:97], v[134:137], v[166:169], v[94:97]
	v_mfma_f32_16x16x32_bf16 v[90:93], v[142:145], v[166:169], v[90:93]
	v_mfma_f32_16x16x32_bf16 v[78:81], v[134:137], v[174:177], v[78:81]
	v_mfma_f32_16x16x32_bf16 v[74:77], v[142:145], v[174:177], v[74:77]
	s_barrier
	s_add_i32 s44, 0, 0x1c000
	s_add_i32 s30, s30, s68
	v_add_u32_e32 v200, s44, v220
	v_lshl_add_u64 v[228:229], v[228:229], 0, s[76:77]
	s_mov_b32 m0, s30
	ds_read_b128 v[188:191], v200
	ds_read_b128 v[192:195], v200 offset:1024
	ds_read_b128 v[196:199], v200 offset:2048
	ds_read_b128 v[224:227], v200 offset:3072
	global_load_lds_dwordx4 v[228:229], off
	v_lshl_add_u64 v[228:229], v[230:231], 0, s[76:77]
	s_add_i32 m0, s30, 0x2000
	s_nop 0
	global_load_lds_dwordx4 v[228:229], off
	s_barrier
	s_waitcnt lgkmcnt(0)
	s_waitcnt lgkmcnt(0)
	v_mfma_f32_16x16x32_bf16 v[118:121], v[188:191], v[146:149], v[118:121]
	v_mfma_f32_16x16x32_bf16 v[114:117], v[196:199], v[146:149], v[114:117]
	v_mfma_f32_16x16x32_bf16 v[102:105], v[188:191], v[154:157], v[102:105]
	v_mfma_f32_16x16x32_bf16 v[98:101], v[196:199], v[154:157], v[98:101]
	v_mfma_f32_16x16x32_bf16 v[86:89], v[188:191], v[162:165], v[86:89]
	v_mfma_f32_16x16x32_bf16 v[82:85], v[196:199], v[162:165], v[82:85]
	v_mfma_f32_16x16x32_bf16 v[70:73], v[188:191], v[170:173], v[70:73]
	v_mfma_f32_16x16x32_bf16 v[66:69], v[196:199], v[170:173], v[66:69]
	v_mfma_f32_16x16x32_bf16 v[118:121], v[192:195], v[150:153], v[118:121]
	v_mfma_f32_16x16x32_bf16 v[114:117], v[224:227], v[150:153], v[114:117]
	v_mfma_f32_16x16x32_bf16 v[102:105], v[192:195], v[158:161], v[102:105]
	v_mfma_f32_16x16x32_bf16 v[98:101], v[224:227], v[158:161], v[98:101]
	v_mfma_f32_16x16x32_bf16 v[86:89], v[192:195], v[166:169], v[86:89]
	v_mfma_f32_16x16x32_bf16 v[82:85], v[224:227], v[166:169], v[82:85]
	v_mfma_f32_16x16x32_bf16 v[70:73], v[192:195], v[174:177], v[70:73]
	v_mfma_f32_16x16x32_bf16 v[66:69], v[224:227], v[174:177], v[66:69]
	s_mov_b32 m0, s57
	v_lshl_add_u64 v[228:229], v[232:233], 0, s[76:77]
	s_barrier
	ds_read_b128 v[146:149], v223 offset:49152
	ds_read_b128 v[150:153], v223 offset:50176
	ds_read_b128 v[154:157], v223 offset:51200
	ds_read_b128 v[158:161], v223 offset:52224
	ds_read_b128 v[162:165], v223 offset:53248
	ds_read_b128 v[166:169], v223 offset:54272
	ds_read_b128 v[170:173], v223 offset:55296
	ds_read_b128 v[174:177], v223 offset:56320
	global_load_lds_dwordx4 v[228:229], off
	v_lshl_add_u64 v[228:229], v[234:235], 0, s[76:77]
	s_mov_b32 m0, s60
	s_nop 0
	global_load_lds_dwordx4 v[228:229], off
	s_barrier
; #define PG8_STAGE(bufoff, gbase, voff) do { _Pragma("unroll") for (int _i = 0; _i < 2; ++_i) \
;         __builtin_amdgcn_global_load_lds((const unsigned*)((const char*)(gbase) + (voff)[_i]), (LAS unsigned*)(lds + (bufoff) + ldsw + _i * 8192), 16, 0, 0); } while (0)
; #define PG8_MMA(ai, bj, At, Bt) do { __builtin_amdgcn_s_setprio(1); _Pragma("unroll") for (int m = 0; m < 4; ++m) _Pragma("unroll") for (int n = 0; n < 2; ++n) _Pragma("unroll") for (int k = 0; k < 2; ++k) \
;         acc[ai][bj][m][n] = __builtin_amdgcn_mfma_f32_16x16x32_bf16(Bt[n][k], At[m][k], acc[ai][bj][m][n], 0, 0, 0); __builtin_amdgcn_s_setprio(0); } while (0)
; #define PG8_WAIT_V(n) asm volatile("s_waitcnt vmcnt(" #n ")" ::: "memory")
; #define PG8_WAIT_L(n) asm volatile("s_waitcnt lgkmcnt(" #n ")" ::: "memory")
; #define PG8_BAR __builtin_amdgcn_s_barrier()
; #define PG8_SCHED __builtin_amdgcn_sched_barrier(0)
;     __device__ __forceinline__ void scales2(const Unit& u, int wr, int fr, int fq, float& sA, float& sB) const {
;         const int rowA = u.pm * BM + wr * 64 + fq * 16 + fr;
;         const f32x4* pa = (const f32x4*)(ssq_in + (size_t)rowA * 16); const f32x4* pb = (const f32x4*)(ssq_in + (size_t)(rowA + HALF) * 16);
;         const f32x4 a0 = pa[0], a1 = pa[1], a2 = pa[2], a3 = pa[3], b0 = pb[0], b1 = pb[1], b2 = pb[2], b3 = pb[3];
;         const float ta = (((a0[0] + a0[1]) + (a0[2] + a0[3])) + ((a1[0] + a1[1]) + (a1[2] + a1[3]))) + (((a2[0] + a2[1]) + (a2[2] + a2[3])) + ((a3[0] + a3[1]) + (a3[2] + a3[3])));
;         const float tb = (((b0[0] + b0[1]) + (b0[2] + b0[3])) + ((b1[0] + b1[1]) + (b1[2] + b1[3]))) + (((b2[0] + b2[1]) + (b2[2] + b2[3])) + ((b3[0] + b3[1]) + (b3[2] + b3[3])));
;         sA = rsqrtf(ta * (1.0f / 1024.0f) + EPS); sB = rsqrtf(tb * (1.0f / 1024.0f) + EPS);
;     }
; template <int MODE, class EpiT, class Sched>
; __device__ __forceinline__ void gemm_phase(LAS unsigned char* lds, const Gemm g, const Sched& S, const EpiT& E) {
;     ...
;             PG8_BAR; PG8_WAIT_L(0); PG8_MMA(1, 0, At, B0); PG8_BAR; PG8_SCHED;
;             PG8_STAGE(PG8_SB(1, 1), b3 + hstep, voffB);
;             PG8_WAIT_V(6); PG8_BAR; PG8_MMA(1, 1, At, B1); PG8_BAR;
	s_waitcnt lgkmcnt(0)
	s_waitcnt lgkmcnt(0)
	v_mfma_f32_16x16x32_bf16 v[62:65], v[130:133], v[146:149], v[62:65]
	v_mfma_f32_16x16x32_bf16 v[58:61], v[138:141], v[146:149], v[58:61]
	v_mfma_f32_16x16x32_bf16 v[46:49], v[130:133], v[154:157], v[46:49]
	v_mfma_f32_16x16x32_bf16 v[42:45], v[138:141], v[154:157], v[42:45]
	v_mfma_f32_16x16x32_bf16 v[30:33], v[130:133], v[162:165], v[30:33]
	v_mfma_f32_16x16x32_bf16 v[26:29], v[138:141], v[162:165], v[26:29]
	v_mfma_f32_16x16x32_bf16 v[14:17], v[130:133], v[170:173], v[14:17]
	v_mfma_f32_16x16x32_bf16 v[10:13], v[138:141], v[170:173], v[10:13]
	v_mfma_f32_16x16x32_bf16 v[62:65], v[134:137], v[150:153], v[62:65]
	v_mfma_f32_16x16x32_bf16 v[58:61], v[142:145], v[150:153], v[58:61]
	v_mfma_f32_16x16x32_bf16 v[46:49], v[134:137], v[158:161], v[46:49]
	v_mfma_f32_16x16x32_bf16 v[42:45], v[142:145], v[158:161], v[42:45]
	v_mfma_f32_16x16x32_bf16 v[30:33], v[134:137], v[166:169], v[30:33]
	v_mfma_f32_16x16x32_bf16 v[26:29], v[142:145], v[166:169], v[26:29]
	v_mfma_f32_16x16x32_bf16 v[14:17], v[134:137], v[174:177], v[14:17]
	v_mfma_f32_16x16x32_bf16 v[10:13], v[142:145], v[174:177], v[10:13]
	s_barrier
	s_add_i32 s30, s44, s68
	v_lshl_add_u64 v[130:131], v[236:237], 0, s[76:77]
	s_mov_b32 m0, s30
	s_nop 0
	global_load_lds_dwordx4 v[130:131], off
	v_lshl_add_u64 v[130:131], v[238:239], 0, s[76:77]
	s_add_i32 m0, s30, 0x2000
	s_nop 0
	global_load_lds_dwordx4 v[130:131], off
	s_waitcnt vmcnt(6)
	s_barrier
	v_mfma_f32_16x16x32_bf16 v[54:57], v[188:191], v[146:149], v[54:57]
	v_mfma_f32_16x16x32_bf16 v[50:53], v[196:199], v[146:149], v[50:53]
	v_mfma_f32_16x16x32_bf16 v[38:41], v[188:191], v[154:157], v[38:41]
	v_mfma_f32_16x16x32_bf16 v[34:37], v[196:199], v[154:157], v[34:37]
	v_mfma_f32_16x16x32_bf16 v[22:25], v[188:191], v[162:165], v[22:25]
	v_mfma_f32_16x16x32_bf16 v[18:21], v[196:199], v[162:165], v[18:21]
	v_mfma_f32_16x16x32_bf16 v[6:9], v[188:191], v[170:173], v[6:9]
	v_mfma_f32_16x16x32_bf16 v[2:5], v[196:199], v[170:173], v[2:5]
	v_mfma_f32_16x16x32_bf16 v[54:57], v[192:195], v[150:153], v[54:57]
	v_mfma_f32_16x16x32_bf16 v[50:53], v[224:227], v[150:153], v[50:53]
	v_mfma_f32_16x16x32_bf16 v[38:41], v[192:195], v[158:161], v[38:41]
	v_mfma_f32_16x16x32_bf16 v[34:37], v[224:227], v[158:161], v[34:37]
	v_mfma_f32_16x16x32_bf16 v[22:25], v[192:195], v[166:169], v[22:25]
	v_mfma_f32_16x16x32_bf16 v[18:21], v[224:227], v[166:169], v[18:21]
	v_mfma_f32_16x16x32_bf16 v[6:9], v[192:195], v[174:177], v[6:9]
	v_mfma_f32_16x16x32_bf16 v[2:5], v[224:227], v[174:177], v[2:5]
	s_add_u32 s4, s4, 0x100
	s_addc_u32 s5, s5, 0
	s_add_u32 s23, s23, 0x100
	s_addc_u32 s24, s24, 0
	s_cmp_ge_u32 s89, s21
	s_mov_b32 s30, s89
	s_barrier
	s_cbranch_scc0 .LBB0_159
	s_lshl_b32 s4, s22, 8
	s_add_i32 s4, s4, s56
	v_or_b32_e32 v130, s4, v222
	v_ashrrev_i32_e32 v131, 31, v130
	v_lshlrev_b64 v[130:131], 6, v[130:131]
	v_lshl_add_u64 v[146:147], s[66:67], 0, v[130:131]
	global_load_dwordx4 v[130:133], v[146:147], off offset:16
	global_load_dwordx4 v[134:137], v[146:147], off offset:48
	global_load_dwordx4 v[138:141], v[146:147], off
	global_load_dwordx4 v[142:145], v[146:147], off offset:32
	v_or_b32_e32 v192, s4, v181
	s_mov_b64 s[4:5], 0x2000
	v_lshl_add_u64 v[158:159], v[146:147], 0, s[4:5]
	v_add_co_u32_e32 v146, vcc, 0x2000, v146
	s_mov_b32 s4, 0x3a800000
	s_nop 0
	v_addc_co_u32_e32 v147, vcc, 0, v147, vcc
	global_load_dwordx4 v[146:149], v[146:147], off
	s_nop 0
	global_load_dwordx4 v[150:153], v[158:159], off offset:16
	global_load_dwordx4 v[154:157], v[158:159], off offset:48
	s_nop 0
	global_load_dwordx4 v[158:161], v[158:159], off offset:32
	v_lshl_or_b32 v188, s2, 8, v221
	v_ashrrev_i32_e32 v193, 31, v192
	v_ashrrev_i32_e32 v189, 31, v188
	v_or_b32_e32 v194, 16, v192
	v_ashrrev_i32_e32 v195, 31, v194
	s_waitcnt vmcnt(0)
	v_mov_b32_e32 v162, v138
	v_mov_b32_e32 v163, v142
	v_mov_b32_e32 v142, v139
	v_pk_add_f32 v[138:139], v[162:163], v[142:143]
	v_mov_b32_e32 v142, v140
	v_mov_b32_e32 v143, v144
	v_mov_b32_e32 v144, v141
	v_pk_add_f32 v[140:141], v[142:143], v[144:145]
	s_nop 0
	v_pk_add_f32 v[138:139], v[138:139], v[140:141]
	v_mov_b32_e32 v140, v130
	v_mov_b32_e32 v141, v134
	v_mov_b32_e32 v134, v131
	v_pk_add_f32 v[130:131], v[140:141], v[134:135]
	v_mov_b32_e32 v134, v132
	v_mov_b32_e32 v135, v136
	v_mov_b32_e32 v136, v133
	v_pk_add_f32 v[132:133], v[134:135], v[136:137]
	v_mov_b32_e32 v134, v148
	v_pk_add_f32 v[130:131], v[130:131], v[132:133]
	v_mov_b32_e32 v132, v146
	v_mov_b32_e32 v133, v158
	v_mov_b32_e32 v158, v147
	v_mov_b32_e32 v135, v160
	v_mov_b32_e32 v160, v149
	v_pk_add_f32 v[132:133], v[132:133], v[158:159]
	v_pk_add_f32 v[134:135], v[134:135], v[160:161]
	v_mov_b32_e32 v136, v152
	v_pk_add_f32 v[132:133], v[132:133], v[134:135]
	v_mov_b32_e32 v134, v150
	v_mov_b32_e32 v135, v154
	v_mov_b32_e32 v154, v151
	v_mov_b32_e32 v137, v156
	v_mov_b32_e32 v156, v153
	v_pk_add_f32 v[134:135], v[134:135], v[154:155]
	v_pk_add_f32 v[136:137], v[136:137], v[156:157]
	v_pk_add_f32 v[130:131], v[138:139], v[130:131]
	v_pk_add_f32 v[134:135], v[134:135], v[136:137]
	s_nop 0
	v_pk_add_f32 v[132:133], v[132:133], v[134:135]
	v_mov_b32_e32 v135, v130
	v_mov_b32_e32 v134, v132
	v_mov_b32_e32 v130, v133
	v_pk_add_f32 v[130:131], v[134:135], v[130:131]
	s_nop 0
	v_pk_fma_f32 v[190:191], v[130:131], s[4:5], v[178:179] op_sel_hi:[1,0,0]
	s_mov_b32 s4, 0x800000
	v_mul_f32_e32 v130, 0x4b800000, v191
	v_cmp_gt_f32_e64 s[44:45], s4, v191
	v_cmp_gt_f32_e32 vcc, s4, v190
	s_nop 0
	v_cndmask_b32_e64 v130, v191, v130, s[44:45]
	v_rsq_f32_e32 v130, v130
	s_nop 0
	v_mul_f32_e32 v131, 0x45800000, v130
	v_cndmask_b32_e64 v226, v130, v131, s[44:45]
	v_lshlrev_b64 v[130:131], 10, v[192:193]
	v_lshl_add_u64 v[130:131], v[130:131], 0, v[188:189]
	v_lshlrev_b64 v[198:199], 1, v[130:131]
	v_lshl_add_u64 v[130:131], s[34:35], 0, v[198:199]
	v_lshl_add_u64 v[132:133], s[92:93], 0, v[198:199]
	global_load_dwordx4 v[170:173], v[130:131], off
	global_load_dwordx4 v[174:177], v[132:133], off
	v_lshl_add_u64 v[134:135], s[6:7], 0, v[198:199]
	global_load_dwordx4 v[166:169], v[134:135], off
	global_load_dwordx4 v[158:161], v[130:131], off offset:256
	global_load_dwordx4 v[162:165], v[132:133], off offset:256
	global_load_dwordx4 v[146:149], v[134:135], off offset:256
	v_and_b32_e32 v130, 64, v205
	v_or_b32_e32 v200, v130, v181
	v_lshlrev_b32_e32 v225, 2, v200
	ds_bpermute_b32 v200, v225, v226
	v_xor_b32_e32 v131, 16, v205
	v_add_u32_e32 v130, 64, v130
	v_cmp_lt_i32_e64 s[44:45], v131, v130
	s_waitcnt lgkmcnt(0)
;     template <int mode> __device__ __forceinline__ void run(const f32x4 (&acc)[2][2][4][2], const Unit& u, int wr, int wc, int fr, int fq, const LAS float* sc) const {
;     ...
; #pragma unroll
;             for (int g = 0; g < 8; ++g) {
;                 const int ai = g >> 2, m = g & 3, cb = g & 1, nb = cb ^ 1;
;                 const int row = row0 + ai * HALF + m * 16;
;                 const size_t off = (size_t)row * D + col0;
;                 if (g < 7) {
;                     const size_t offn = (size_t)(row0 + ((g + 1) >> 2) * HALF + ((g + 1) & 3) * 16) * D + col0;
; #pragma unroll
;                     for (int bj = 0; bj < 2; ++bj) {
;                         const size_t o = offn + bj * HALF;
;                         if (mode == 5) { xi[nb][2 * bj] = *(const f32x4*)(xin + o); xi[nb][2 * bj + 1] = *(const f32x4*)(xin + o + 4); }
;                         else { xh[nb][bj] = *(const u32x4*)(hin + o); xl[nb][bj] = *(const u32x4*)(lin + o); }
;                         if (mode == 4) pq[nb][bj] = *(const u32x4*)(ob + o);
;                     }
;                 }
;                 float s = 1.f;
;                 if (mode == 4) s = __shfl(ai ? sB : sA, m * 16 + fr);
;                 float ss = 0.f;
; #pragma unroll
;                 for (int bj = 0; bj < 2; ++bj) {
;                     u32x4 wh, wl;
; #pragma unroll
;                     for (int n = 0; n < 2; ++n) {
;                         const int q = 2 * bj + n;
;                         const unsigned h0 = n ? xh[cb][bj].z : xh[cb][bj].x, h1 = n ? xh[cb][bj].w : xh[cb][bj].y, l0 = n ? xl[cb][bj].z : xl[cb][bj].x, l1 = n ? xl[cb][bj].w : xl[cb][bj].y;
;                         f32x4 xo;
;                         if (mode == 5) xo = xi[cb][q];
;                         else { xo[0] = bf_lo(h0) + bf_lo(l0); xo[1] = bf_hi(h0) + bf_hi(l0); xo[2] = bf_lo(h1) + bf_lo(l1); xo[3] = bf_hi(h1) + bf_hi(l1); }
;                         f32x4 v;
;                         if (mode != 4) v = xo + acc[ai][bj][m][n] * alpha + bvv[q];
;                         else {
;                             const f32x4 a = acc[ai][bj][m][n] * s;
;                             const unsigned p0 = n ? pq[cb][bj].z : pq[cb][bj].x, p1 = n ? pq[cb][bj].w : pq[cb][bj].y;
;                             v[0] = xo[0] + sigmoidf_(a[0]) * bf_lo(p0); v[1] = xo[1] + sigmoidf_(a[1]) * bf_hi(p0);
	v_pk_mul_f32 v[126:127], v[126:127], v[200:201] op_sel_hi:[1,0]
	v_cndmask_b32_e64 v131, v205, v131, s[44:45]
	v_lshlrev_b32_e32 v191, 2, v131
	v_xor_b32_e32 v131, 32, v205
	v_mul_f32_e32 v126, 0xbfb8aa3b, v126
	v_cmp_lt_i32_e64 s[44:45], v131, v130
	v_exp_f32_e32 v126, v126
	v_pk_mul_f32 v[128:129], v[128:129], v[200:201] op_sel_hi:[1,0]
	v_cndmask_b32_e64 v130, v205, v131, s[44:45]
	v_lshlrev_b32_e32 v224, 2, v130
	v_lshlrev_b64 v[130:131], 10, v[194:195]
	v_lshl_add_u64 v[130:131], v[130:131], 0, v[188:189]
	v_lshlrev_b64 v[196:197], 1, v[130:131]
	v_add_f32_e32 v126, 1.0, v126
	v_lshl_add_u64 v[130:131], s[34:35], 0, v[196:197]
	v_lshl_add_u64 v[132:133], s[92:93], 0, v[196:197]
	v_lshl_add_u64 v[228:229], s[6:7], 0, v[196:197]
	v_rcp_f32_e32 v126, v126
	global_load_dwordx4 v[150:153], v[130:131], off
	global_load_dwordx4 v[154:157], v[132:133], off
	global_load_dwordx4 v[142:145], v[228:229], off
	global_load_dwordx4 v[134:137], v[130:131], off offset:256
	global_load_dwordx4 v[138:141], v[132:133], off offset:256
	s_nop 0
	global_load_dwordx4 v[130:133], v[228:229], off offset:256
	v_pk_mul_f32 v[122:123], v[122:123], v[200:201] op_sel_hi:[1,0]
	v_pk_mul_f32 v[124:125], v[124:125], v[200:201] op_sel_hi:[1,0]
	v_mul_f32_e32 v122, 0xbfb8aa3b, v122
	v_exp_f32_e32 v122, v122
	v_pk_mul_f32 v[118:119], v[118:119], v[200:201] op_sel_hi:[1,0]
	v_pk_mul_f32 v[120:121], v[120:121], v[200:201] op_sel_hi:[1,0]
	v_mul_f32_e32 v118, 0xbfb8aa3b, v118
	v_add_f32_e32 v122, 1.0, v122
	v_rcp_f32_e32 v122, v122
	v_exp_f32_e32 v118, v118
	v_pk_mul_f32 v[114:115], v[114:115], v[200:201] op_sel_hi:[1,0]
	v_pk_mul_f32 v[116:117], v[116:117], v[200:201] op_sel_hi:[1,0]
	v_mul_f32_e32 v114, 0xbfb8aa3b, v114
	v_add_f32_e32 v118, 1.0, v118
	v_rcp_f32_e32 v118, v118
	v_exp_f32_e32 v114, v114
	s_lshl_b32 s44, s2, 2
	s_ashr_i32 s45, s44, 31
	v_add_f32_e32 v114, 1.0, v114
	v_rcp_f32_e32 v114, v114
	s_waitcnt vmcnt(11)
	v_lshlrev_b32_e32 v227, 16, v170
	s_waitcnt vmcnt(10)
	v_lshlrev_b32_e32 v228, 16, v174
	v_and_b32_e32 v174, 0xffff0000, v174
	v_and_b32_e32 v170, 0xffff0000, v170
	v_add_f32_e32 v227, v228, v227
	v_add_f32_e32 v170, v174, v170
	v_lshlrev_b32_e32 v174, 16, v171
	v_lshlrev_b32_e32 v228, 16, v175
	v_and_b32_e32 v175, 0xffff0000, v175
	v_and_b32_e32 v171, 0xffff0000, v171
	v_add_f32_e32 v171, v175, v171
	s_waitcnt vmcnt(9)
	v_lshlrev_b32_e32 v175, 16, v166
	v_fmac_f32_e32 v227, v126, v175
	v_mul_f32_e32 v126, 0xbfb8aa3b, v127
	v_exp_f32_e32 v126, v126
	v_and_b32_e32 v127, 0xffff0000, v166
	v_add_f32_e32 v174, v228, v174
	v_add_f32_e32 v126, 1.0, v126
	v_rcp_f32_e32 v126, v126
	s_nop 0
	v_fmac_f32_e32 v170, v126, v127
	v_mul_f32_e32 v126, 0xbfb8aa3b, v128
	v_exp_f32_e32 v126, v126
	v_lshlrev_b32_e32 v127, 16, v167
	v_add_f32_e32 v126, 1.0, v126
	v_rcp_f32_e32 v126, v126
	s_nop 0
	v_fmac_f32_e32 v174, v126, v127
	v_mul_f32_e32 v126, 0xbfb8aa3b, v129
	v_exp_f32_e32 v126, v126
	v_and_b32_e32 v127, 0xffff0000, v167
	v_add_f32_e32 v126, 1.0, v126
	v_rcp_f32_e32 v126, v126
	s_nop 0
	v_fmac_f32_e32 v171, v126, v127
	v_cvt_pk_bf16_f32 v126, v227, v170
	v_cvt_pk_bf16_f32 v127, v174, v171
	s_nop 0
	v_lshlrev_b32_e32 v128, 16, v126
	v_and_b32_e32 v129, 0xffff0000, v126
	v_sub_f32_e32 v128, v227, v128
	v_sub_f32_e32 v129, v170, v129
	v_cvt_pk_bf16_f32 v166, v128, v129
	v_lshlrev_b32_e32 v128, 16, v127
	v_and_b32_e32 v129, 0xffff0000, v127
	v_sub_f32_e32 v128, v174, v128
	v_sub_f32_e32 v129, v171, v129
	v_cvt_pk_bf16_f32 v167, v128, v129
	v_mul_f32_e32 v128, v170, v170
	v_mul_f32_e32 v129, v171, v171
	v_fmac_f32_e32 v128, v227, v227
	v_fmac_f32_e32 v129, v174, v174
	v_add_f32_e32 v170, v128, v129
	v_lshlrev_b32_e32 v128, 16, v172
	v_lshlrev_b32_e32 v129, 16, v176
	v_add_f32_e32 v171, v129, v128
	v_and_b32_e32 v128, 0xffff0000, v176
	v_and_b32_e32 v129, 0xffff0000, v172
	v_add_f32_e32 v172, v128, v129
	v_lshlrev_b32_e32 v128, 16, v173
	v_lshlrev_b32_e32 v129, 16, v177
	v_add_f32_e32 v174, v129, v128
	v_and_b32_e32 v128, 0xffff0000, v177
	v_and_b32_e32 v129, 0xffff0000, v173
	v_add_f32_e32 v173, v128, v129
	v_lshlrev_b32_e32 v128, 16, v168
	v_fmac_f32_e32 v171, v122, v128
	v_mul_f32_e32 v122, 0xbfb8aa3b, v123
	v_exp_f32_e32 v122, v122
	v_and_b32_e32 v123, 0xffff0000, v168
	v_add_f32_e32 v122, 1.0, v122
	v_rcp_f32_e32 v122, v122
	s_nop 0
	v_fmac_f32_e32 v172, v122, v123
	v_mul_f32_e32 v122, 0xbfb8aa3b, v124
	v_exp_f32_e32 v122, v122
	v_lshlrev_b32_e32 v123, 16, v169
	v_cvt_pk_bf16_f32 v128, v171, v172
	v_add_f32_e32 v122, 1.0, v122
	v_rcp_f32_e32 v122, v122
	s_nop 0
	v_fmac_f32_e32 v174, v122, v123
	v_mul_f32_e32 v122, 0xbfb8aa3b, v125
	v_exp_f32_e32 v122, v122
	v_and_b32_e32 v123, 0xffff0000, v169
	v_lshl_add_u64 v[124:125], s[28:29], 0, v[198:199]
	v_add_f32_e32 v122, 1.0, v122
	v_rcp_f32_e32 v122, v122
	s_nop 0
	v_fmac_f32_e32 v173, v122, v123
	v_lshlrev_b32_e32 v122, 16, v128
	v_and_b32_e32 v123, 0xffff0000, v128
	v_sub_f32_e32 v122, v171, v122
	v_sub_f32_e32 v123, v172, v123
	v_cvt_pk_bf16_f32 v129, v174, v173
	v_cvt_pk_bf16_f32 v168, v122, v123
	s_nop 0
	v_lshlrev_b32_e32 v122, 16, v129
	v_and_b32_e32 v123, 0xffff0000, v129
	v_sub_f32_e32 v122, v174, v122
	v_sub_f32_e32 v123, v173, v123
	v_cvt_pk_bf16_f32 v169, v122, v123
	v_mul_f32_e32 v122, v172, v172
	v_mul_f32_e32 v123, v173, v173
	v_fmac_f32_e32 v122, v171, v171
	v_fmac_f32_e32 v123, v174, v174
	v_add_f32_e32 v122, v122, v123
	v_add_f32_e32 v170, v170, v122
	v_lshl_add_u64 v[122:123], s[10:11], 0, v[198:199]
	global_store_dwordx4 v[122:123], v[126:129], off
	global_store_dwordx4 v[124:125], v[166:169], off
	s_waitcnt vmcnt(10)
; __device__ __forceinline__ float bf_lo(unsigned w) { return __uint_as_float(w << 16); }
; __device__ __forceinline__ float bf_hi(unsigned w) { return __uint_as_float(w & 0xffff0000u); }
;     template <int mode> __device__ __forceinline__ void run(const f32x4 (&acc)[2][2][4][2], const Unit& u, int wr, int wc, int fr, int fq, const LAS float* sc) const {
;     ...
;                 for (int bj = 0; bj < 2; ++bj) {
;                     u32x4 wh, wl;
; #pragma unroll
;                     for (int n = 0; n < 2; ++n) {
;                         const int q = 2 * bj + n;
;                         const unsigned h0 = n ? xh[cb][bj].z : xh[cb][bj].x, h1 = n ? xh[cb][bj].w : xh[cb][bj].y, l0 = n ? xl[cb][bj].z : xl[cb][bj].x, l1 = n ? xl[cb][bj].w : xl[cb][bj].y;
;                         f32x4 xo;
;                         if (mode == 5) xo = xi[cb][q];
;                         else { xo[0] = bf_lo(h0) + bf_lo(l0); xo[1] = bf_hi(h0) + bf_hi(l0); xo[2] = bf_lo(h1) + bf_lo(l1); xo[3] = bf_hi(h1) + bf_hi(l1); }
;                         f32x4 v;
;                         if (mode != 4) v = xo + acc[ai][bj][m][n] * alpha + bvv[q];
;                         else {
;                             const f32x4 a = acc[ai][bj][m][n] * s;
;                             const unsigned p0 = n ? pq[cb][bj].z : pq[cb][bj].x, p1 = n ? pq[cb][bj].w : pq[cb][bj].y;
;                             v[0] = xo[0] + sigmoidf_(a[0]) * bf_lo(p0); v[1] = xo[1] + sigmoidf_(a[1]) * bf_hi(p0);
;                             v[2] = xo[2] + sigmoidf_(a[2]) * bf_lo(p1); v[3] = xo[3] + sigmoidf_(a[3]) * bf_hi(p1);
;                         }
;                         const unsigned w0 = pk2(v[0], v[1]), w1 = pk2(v[2], v[3]);
;                         const unsigned m0 = pk2(v[0] - bf_lo(w0), v[1] - bf_hi(w0)), m1 = pk2(v[2] - bf_lo(w1), v[3] - bf_hi(w1));
;                         if (n == 0) { wh.x = w0; wh.y = w1; wl.x = m0; wl.y = m1; } else { wh.z = w0; wh.w = w1; wl.z = m0; wl.w = m1; }
;                         ss += (v[0] * v[0] + v[1] * v[1]) + (v[2] * v[2] + v[3] * v[3]);
;                     }
;                     *(u32x4*)(xb + off + bj * HALF) = wh;
;                     *(u32x4*)(lout + off + bj * HALF) = wl;
;                 }
;                 ss += __shfl_xor(ss, 16); ss += __shfl_xor(ss, 32);
;                 if (fq == 0) ssq_out[(size_t)row * 16 + u.pn * 4 + wc] = ss;
	v_lshlrev_b32_e32 v126, 16, v158
	s_waitcnt vmcnt(9)
	v_lshlrev_b32_e32 v127, 16, v162
	v_add_f32_e32 v128, v127, v126
	v_and_b32_e32 v126, 0xffff0000, v162
	v_and_b32_e32 v127, 0xffff0000, v158
	v_add_f32_e32 v129, v126, v127
	v_lshlrev_b32_e32 v126, 16, v159
	v_lshlrev_b32_e32 v127, 16, v163
	v_add_f32_e32 v158, v127, v126
	v_and_b32_e32 v126, 0xffff0000, v163
	v_and_b32_e32 v127, 0xffff0000, v159
	v_add_f32_e32 v159, v126, v127
	s_waitcnt vmcnt(8)
	v_lshlrev_b32_e32 v126, 16, v146
	v_fmac_f32_e32 v128, v118, v126
	v_mul_f32_e32 v118, 0xbfb8aa3b, v119
	v_exp_f32_e32 v118, v118
	v_and_b32_e32 v119, 0xffff0000, v146
	v_add_f32_e32 v118, 1.0, v118
	v_rcp_f32_e32 v118, v118
	s_nop 0
	v_fmac_f32_e32 v129, v118, v119
	v_mul_f32_e32 v118, 0xbfb8aa3b, v120
	v_exp_f32_e32 v118, v118
	v_lshlrev_b32_e32 v119, 16, v147
	v_add_f32_e32 v118, 1.0, v118
	v_rcp_f32_e32 v118, v118
	s_nop 0
	v_fmac_f32_e32 v158, v118, v119
	v_mul_f32_e32 v118, 0xbfb8aa3b, v121
	v_exp_f32_e32 v118, v118
	v_and_b32_e32 v119, 0xffff0000, v147
	v_add_f32_e32 v118, 1.0, v118
	v_rcp_f32_e32 v118, v118
	s_nop 0
	v_fmac_f32_e32 v159, v118, v119
	v_cvt_pk_bf16_f32 v118, v128, v129
	v_cvt_pk_bf16_f32 v119, v158, v159
	s_nop 0
	v_lshlrev_b32_e32 v120, 16, v118
	v_and_b32_e32 v121, 0xffff0000, v118
	v_sub_f32_e32 v120, v128, v120
	v_sub_f32_e32 v121, v129, v121
	v_cvt_pk_bf16_f32 v126, v120, v121
	v_lshlrev_b32_e32 v120, 16, v119
	v_and_b32_e32 v121, 0xffff0000, v119
	v_sub_f32_e32 v120, v158, v120
	v_sub_f32_e32 v121, v159, v121
	v_cvt_pk_bf16_f32 v127, v120, v121
	v_mul_f32_e32 v120, v129, v129
	v_mul_f32_e32 v121, v159, v159
	v_fmac_f32_e32 v120, v128, v128
	v_fmac_f32_e32 v121, v158, v158
	v_add_f32_e32 v120, v120, v121
	v_add_f32_e32 v146, v120, v170
	v_lshlrev_b32_e32 v120, 16, v160
	v_lshlrev_b32_e32 v121, 16, v164
	v_add_f32_e32 v147, v121, v120
	v_and_b32_e32 v120, 0xffff0000, v164
	v_and_b32_e32 v121, 0xffff0000, v160
	v_add_f32_e32 v158, v120, v121
	v_lshlrev_b32_e32 v120, 16, v161
	v_lshlrev_b32_e32 v121, 16, v165
	v_add_f32_e32 v159, v121, v120
	v_and_b32_e32 v120, 0xffff0000, v165
	v_and_b32_e32 v121, 0xffff0000, v161
	v_add_f32_e32 v160, v120, v121
	v_lshlrev_b32_e32 v120, 16, v148
	v_fmac_f32_e32 v147, v114, v120
	v_mul_f32_e32 v114, 0xbfb8aa3b, v115
	v_exp_f32_e32 v114, v114
	v_and_b32_e32 v115, 0xffff0000, v148
	v_add_f32_e32 v114, 1.0, v114
	v_rcp_f32_e32 v114, v114
	s_nop 0
	v_fmac_f32_e32 v158, v114, v115
	v_mul_f32_e32 v114, 0xbfb8aa3b, v116
	v_exp_f32_e32 v114, v114
	v_lshlrev_b32_e32 v115, 16, v149
	v_cvt_pk_bf16_f32 v120, v147, v158
	v_add_f32_e32 v114, 1.0, v114
	v_rcp_f32_e32 v114, v114
	s_nop 0
	v_fmac_f32_e32 v159, v114, v115
	v_mul_f32_e32 v114, 0xbfb8aa3b, v117
	v_exp_f32_e32 v114, v114
	v_and_b32_e32 v115, 0xffff0000, v149
	v_add_f32_e32 v114, 1.0, v114
	v_rcp_f32_e32 v114, v114
	s_nop 0
	v_fmac_f32_e32 v160, v114, v115
	v_lshlrev_b32_e32 v114, 16, v120
	v_and_b32_e32 v115, 0xffff0000, v120
	v_sub_f32_e32 v114, v147, v114
	v_sub_f32_e32 v115, v158, v115
	v_cvt_pk_bf16_f32 v121, v159, v160
	v_cvt_pk_bf16_f32 v128, v114, v115
	s_nop 0
	v_lshlrev_b32_e32 v114, 16, v121
	v_and_b32_e32 v115, 0xffff0000, v121
	v_sub_f32_e32 v114, v159, v114
	v_sub_f32_e32 v115, v160, v115
	v_cvt_pk_bf16_f32 v129, v114, v115
	v_mul_f32_e32 v114, v158, v158
	v_mul_f32_e32 v115, v160, v160
	v_fmac_f32_e32 v114, v147, v147
	v_fmac_f32_e32 v115, v159, v159
	v_add_f32_e32 v114, v114, v115
	v_add_f32_e32 v114, v114, v146
	ds_bpermute_b32 v115, v191, v114
	global_store_dwordx4 v[122:123], v[118:121], off offset:256
	global_store_dwordx4 v[124:125], v[126:129], off offset:256
	s_waitcnt lgkmcnt(0)
	v_add_f32_e32 v114, v114, v115
	ds_bpermute_b32 v115, v224, v114
	s_and_saveexec_b64 s[4:5], s[40:41]
	s_cbranch_execz .LBB0_162
	v_lshlrev_b64 v[116:117], 6, v[192:193]
	v_lshl_add_u64 v[116:117], s[62:63], 0, v[116:117]
	v_lshl_add_u64 v[116:117], s[44:45], 2, v[116:117]
	s_lshl_b32 s24, s20, 2
	v_lshl_add_u64 v[116:117], v[116:117], 0, s[24:25]
	s_waitcnt lgkmcnt(0)
	v_add_f32_e32 v114, v114, v115
	global_store_dword v[116:117], v114, off

; #define PG8_STAGE(bufoff, gbase, voff) do { _Pragma("unroll") for (int _i = 0; _i < 2; ++_i) \
;         __builtin_amdgcn_global_load_lds((const unsigned*)((const char*)(gbase) + (voff)[_i]), (LAS unsigned*)(lds + (bufoff) + ldsw + _i * 8192), 16, 0, 0); } while (0)
; #define PG8_LDA(dst, b, h) do { _Pragma("unroll") for (int m = 0; m < 4; ++m) _Pragma("unroll") for (int k = 0; k < 2; ++k) dst[m][k] = *(const LAS bf16x8*)(lds + PG8_SA(b, h) + aoff + m * 2048 + k * 1024); } while (0)
; #define PG8_LDB(dst, b, h) do { _Pragma("unroll") for (int n = 0; n < 2; ++n) _Pragma("unroll") for (int k = 0; k < 2; ++k) dst[n][k] = *(const LAS bf16x8*)(lds + PG8_SB(b, h) + boff + n * 2048 + k * 1024); } while (0)
; #define PG8_MMA(ai, bj, At, Bt) do { __builtin_amdgcn_s_setprio(1); _Pragma("unroll") for (int m = 0; m < 4; ++m) _Pragma("unroll") for (int n = 0; n < 2; ++n) _Pragma("unroll") for (int k = 0; k < 2; ++k) \
;         acc[ai][bj][m][n] = __builtin_amdgcn_mfma_f32_16x16x32_bf16(Bt[n][k], At[m][k], acc[ai][bj][m][n], 0, 0, 0); __builtin_amdgcn_s_setprio(0); } while (0)
; #define PG8_WAIT_L(n) asm volatile("s_waitcnt lgkmcnt(" #n ")" ::: "memory")
; #define PG8_BAR __builtin_amdgcn_s_barrier()
; #define PG8_SCHED __builtin_amdgcn_sched_barrier(0)
; template <int MODE, class EpiT, class Sched>
; __device__ __forceinline__ void gemm_phase(LAS unsigned char* lds, const Gemm g, const Sched& S, const EpiT& E) {
;     ...
;         for (int t = 0; t < nt; t += 2) {
;             const bool last = (t == nt - 2);
;             const char* a1 = cA + (size_t)(t + 1) * kstep;
;             const char* a2 = last ? nA : cA + (size_t)(t + 2) * kstep; const char* b2 = last ? nB : cB + (size_t)(t + 2) * kstep;
;             const char* a3 = a2 + kstep; const char* b3 = b2 + kstep;
;             PG8_LDB(B0, 0, 0); PG8_SCHED; PG8_LDA(At, 0, 0); PG8_STAGE(PG8_SA(1, 1), a1 + hstep, voffA);
;             PG8_WAIT_L(8); PG8_BAR; PG8_WAIT_L(0); PG8_MMA(0, 0, At, B0); PG8_BAR; PG8_SCHED;
;             PG8_LDB(B1, 0, 1); PG8_STAGE(PG8_SB(0, 0), b2, voffB);
;             PG8_BAR; PG8_WAIT_L(0); PG8_MMA(0, 1, At, B1); PG8_BAR;
;             PG8_LDA(At, 0, 1); PG8_STAGE(PG8_SA(0, 0), a2, voffA);
;             PG8_BAR; PG8_WAIT_L(0); PG8_MMA(1, 0, At, B0); PG8_BAR; PG8_SCHED;
.LBB0_195:
	s_add_i32 vcc_lo, s44, 2
	s_add_u32 s52, s4, 0x80
	s_addc_u32 s45, s5, 0
	s_add_i32 s58, 0, 0x10000
	v_add_u32_e32 v74, s58, v194
	ds_read_b128 v[58:61], v74
	ds_read_b128 v[62:65], v74 offset:1024
	ds_read_b128 v[70:73], v74 offset:2048
	ds_read_b128 v[74:77], v74 offset:3072
	s_cmp_eq_u32 s75, s44
	s_cselect_b32 s44, s68, s52
	s_cselect_b32 s45, s69, s45
	s_cselect_b32 s53, s47, s90
	s_cselect_b32 s52, s46, s89
	v_lshl_add_u64 v[188:189], s[4:5], 0, v[176:177]
	s_add_i32 m0, s21, 0xc000
	ds_read_b128 v[138:141], v196
	ds_read_b128 v[142:145], v196 offset:1024
	ds_read_b128 v[146:149], v196 offset:2048
	ds_read_b128 v[150:153], v196 offset:3072
	ds_read_b128 v[162:165], v196 offset:4096
	ds_read_b128 v[166:169], v196 offset:5120
	ds_read_b128 v[170:173], v196 offset:6144
	ds_read_b128 v[184:187], v196 offset:7168
	global_load_lds_dwordx4 v[188:189], off
	v_lshl_add_u64 v[188:189], s[4:5], 0, v[182:183]
	s_add_i32 m0, s21, 0xe000
	s_nop 0
	global_load_lds_dwordx4 v[188:189], off
	s_waitcnt lgkmcnt(8)
	s_barrier
	s_waitcnt lgkmcnt(0)
	s_waitcnt lgkmcnt(0)
	v_mfma_f32_16x16x32_bf16 v[158:161], v[58:61], v[138:141], v[158:161]
	v_mfma_f32_16x16x32_bf16 v[154:157], v[70:73], v[138:141], v[154:157]
	v_mfma_f32_16x16x32_bf16 v[126:129], v[58:61], v[146:149], v[126:129]
	v_mfma_f32_16x16x32_bf16 v[122:125], v[70:73], v[146:149], v[122:125]
	v_mfma_f32_16x16x32_bf16 v[110:113], v[58:61], v[162:165], v[110:113]
	v_mfma_f32_16x16x32_bf16 v[106:109], v[70:73], v[162:165], v[106:109]
	v_mfma_f32_16x16x32_bf16 v[94:97], v[58:61], v[170:173], v[94:97]
	v_mfma_f32_16x16x32_bf16 v[90:93], v[70:73], v[170:173], v[90:93]
	v_mfma_f32_16x16x32_bf16 v[158:161], v[62:65], v[142:145], v[158:161]
	v_mfma_f32_16x16x32_bf16 v[154:157], v[74:77], v[142:145], v[154:157]
	v_mfma_f32_16x16x32_bf16 v[126:129], v[62:65], v[150:153], v[126:129]
	v_mfma_f32_16x16x32_bf16 v[122:125], v[74:77], v[150:153], v[122:125]
	v_mfma_f32_16x16x32_bf16 v[110:113], v[62:65], v[166:169], v[110:113]
	v_mfma_f32_16x16x32_bf16 v[106:109], v[74:77], v[166:169], v[106:109]
	v_mfma_f32_16x16x32_bf16 v[94:97], v[62:65], v[184:187], v[94:97]
	v_mfma_f32_16x16x32_bf16 v[90:93], v[74:77], v[184:187], v[90:93]
	s_barrier
	s_add_i32 s59, 0, 0x14000
	v_add_u32_e32 v192, s59, v194
	s_add_i32 s58, s58, s20
	ds_read_b128 v[188:191], v192
	ds_read_b128 v[220:223], v192 offset:1024
	ds_read_b128 v[224:227], v192 offset:2048
	ds_read_b128 v[228:231], v192 offset:3072
	v_lshl_add_u64 v[192:193], s[52:53], 0, v[0:1]
	s_mov_b32 m0, s58
	v_lshl_add_u64 v[198:199], s[52:53], 0, v[174:175]
	global_load_lds_dwordx4 v[192:193], off
	s_add_i32 m0, s58, 0x2000
	s_nop 0
	global_load_lds_dwordx4 v[198:199], off
	s_barrier
	s_waitcnt lgkmcnt(0)
	s_waitcnt lgkmcnt(0)
	v_mfma_f32_16x16x32_bf16 v[134:137], v[188:191], v[138:141], v[134:137]
	v_mfma_f32_16x16x32_bf16 v[130:133], v[224:227], v[138:141], v[130:133]
	v_mfma_f32_16x16x32_bf16 v[118:121], v[188:191], v[146:149], v[118:121]
	v_mfma_f32_16x16x32_bf16 v[114:117], v[224:227], v[146:149], v[114:117]
	v_mfma_f32_16x16x32_bf16 v[102:105], v[188:191], v[162:165], v[102:105]
	v_mfma_f32_16x16x32_bf16 v[98:101], v[224:227], v[162:165], v[98:101]
	v_mfma_f32_16x16x32_bf16 v[86:89], v[188:191], v[170:173], v[86:89]
	v_mfma_f32_16x16x32_bf16 v[82:85], v[224:227], v[170:173], v[82:85]
	v_mfma_f32_16x16x32_bf16 v[134:137], v[220:223], v[142:145], v[134:137]
	v_mfma_f32_16x16x32_bf16 v[130:133], v[228:231], v[142:145], v[130:133]
	v_mfma_f32_16x16x32_bf16 v[118:121], v[220:223], v[150:153], v[118:121]
	v_mfma_f32_16x16x32_bf16 v[114:117], v[228:231], v[150:153], v[114:117]
	v_mfma_f32_16x16x32_bf16 v[102:105], v[220:223], v[166:169], v[102:105]
	v_mfma_f32_16x16x32_bf16 v[98:101], v[228:231], v[166:169], v[98:101]
	v_mfma_f32_16x16x32_bf16 v[86:89], v[220:223], v[184:187], v[86:89]
	v_mfma_f32_16x16x32_bf16 v[82:85], v[228:231], v[184:187], v[82:85]
	s_mov_b32 m0, s21
	v_lshl_add_u64 v[232:233], s[44:45], 0, v[0:1]
	s_barrier
	ds_read_b128 v[138:141], v196 offset:16384
	ds_read_b128 v[142:145], v196 offset:17408
	ds_read_b128 v[146:149], v196 offset:18432
	ds_read_b128 v[150:153], v196 offset:19456
	ds_read_b128 v[162:165], v196 offset:20480
	ds_read_b128 v[166:169], v196 offset:21504
	ds_read_b128 v[170:173], v196 offset:22528
	ds_read_b128 v[184:187], v196 offset:23552
	global_load_lds_dwordx4 v[232:233], off
	v_lshl_add_u64 v[234:235], s[44:45], 0, v[174:175]
	s_mov_b32 m0, s50
	s_nop 0
	global_load_lds_dwordx4 v[234:235], off
	s_barrier
	s_waitcnt lgkmcnt(0)
	s_waitcnt lgkmcnt(0)
	v_mfma_f32_16x16x32_bf16 v[78:81], v[58:61], v[138:141], v[78:81]
	v_mfma_f32_16x16x32_bf16 v[66:69], v[70:73], v[138:141], v[66:69]
	v_mfma_f32_16x16x32_bf16 v[46:49], v[58:61], v[146:149], v[46:49]
	v_mfma_f32_16x16x32_bf16 v[42:45], v[70:73], v[146:149], v[42:45]
	v_mfma_f32_16x16x32_bf16 v[30:33], v[58:61], v[162:165], v[30:33]
	v_mfma_f32_16x16x32_bf16 v[26:29], v[70:73], v[162:165], v[26:29]
	v_mfma_f32_16x16x32_bf16 v[14:17], v[58:61], v[170:173], v[14:17]
	v_mfma_f32_16x16x32_bf16 v[10:13], v[70:73], v[170:173], v[10:13]
	v_mfma_f32_16x16x32_bf16 v[78:81], v[62:65], v[142:145], v[78:81]
	v_mfma_f32_16x16x32_bf16 v[66:69], v[74:77], v[142:145], v[66:69]
	v_mfma_f32_16x16x32_bf16 v[46:49], v[62:65], v[150:153], v[46:49]
	v_mfma_f32_16x16x32_bf16 v[42:45], v[74:77], v[150:153], v[42:45]
	v_mfma_f32_16x16x32_bf16 v[30:33], v[62:65], v[166:169], v[30:33]
	v_mfma_f32_16x16x32_bf16 v[26:29], v[74:77], v[166:169], v[26:29]
	v_mfma_f32_16x16x32_bf16 v[14:17], v[62:65], v[184:187], v[14:17]
	v_mfma_f32_16x16x32_bf16 v[10:13], v[74:77], v[184:187], v[10:13]
	s_barrier
; #define PG8_STAGE(bufoff, gbase, voff) do { _Pragma("unroll") for (int _i = 0; _i < 2; ++_i) \
;         __builtin_amdgcn_global_load_lds((const unsigned*)((const char*)(gbase) + (voff)[_i]), (LAS unsigned*)(lds + (bufoff) + ldsw + _i * 8192), 16, 0, 0); } while (0)
; #define PG8_LDA(dst, b, h) do { _Pragma("unroll") for (int m = 0; m < 4; ++m) _Pragma("unroll") for (int k = 0; k < 2; ++k) dst[m][k] = *(const LAS bf16x8*)(lds + PG8_SA(b, h) + aoff + m * 2048 + k * 1024); } while (0)
; #define PG8_LDB(dst, b, h) do { _Pragma("unroll") for (int n = 0; n < 2; ++n) _Pragma("unroll") for (int k = 0; k < 2; ++k) dst[n][k] = *(const LAS bf16x8*)(lds + PG8_SB(b, h) + boff + n * 2048 + k * 1024); } while (0)
; #define PG8_MMA(ai, bj, At, Bt) do { __builtin_amdgcn_s_setprio(1); _Pragma("unroll") for (int m = 0; m < 4; ++m) _Pragma("unroll") for (int n = 0; n < 2; ++n) _Pragma("unroll") for (int k = 0; k < 2; ++k) \
;         acc[ai][bj][m][n] = __builtin_amdgcn_mfma_f32_16x16x32_bf16(Bt[n][k], At[m][k], acc[ai][bj][m][n], 0, 0, 0); __builtin_amdgcn_s_setprio(0); } while (0)
; #define PG8_WAIT_V(n) asm volatile("s_waitcnt vmcnt(" #n ")" ::: "memory")
; #define PG8_WAIT_L(n) asm volatile("s_waitcnt lgkmcnt(" #n ")" ::: "memory")
; #define PG8_BAR __builtin_amdgcn_s_barrier()
; #define PG8_SCHED __builtin_amdgcn_sched_barrier(0)
; template <int MODE, class EpiT, class Sched>
; __device__ __forceinline__ void gemm_phase(LAS unsigned char* lds, const Gemm g, const Sched& S, const EpiT& E) {
;     ...
;             PG8_BAR; PG8_WAIT_L(0); PG8_MMA(1, 0, At, B0); PG8_BAR; PG8_SCHED;
;             PG8_STAGE(PG8_SB(0, 1), b2 + hstep, voffB);
;             PG8_WAIT_V(6); PG8_BAR; PG8_MMA(1, 1, At, B1); PG8_BAR;
;             PG8_LDB(B0, 1, 0); PG8_SCHED; PG8_LDA(At, 1, 0); PG8_STAGE(PG8_SA(0, 1), a2 + hstep, voffA);
;             PG8_WAIT_L(8); PG8_BAR; PG8_WAIT_L(0); PG8_MMA(0, 0, At, B0); PG8_BAR; PG8_SCHED;
;             PG8_LDB(B1, 1, 1); PG8_STAGE(PG8_SB(1, 0), b3, voffB);
;             PG8_BAR; PG8_WAIT_L(0); PG8_MMA(0, 1, At, B1); PG8_BAR;
;             PG8_LDA(At, 1, 1); PG8_STAGE(PG8_SA(1, 0), a3, voffA);
	s_add_u32 s52, s52, s38
	s_addc_u32 s53, s53, 0
	s_add_i32 s58, s59, s20
	v_lshl_add_u64 v[236:237], s[52:53], 0, v[0:1]
	s_mov_b32 m0, s58
	v_lshl_add_u64 v[238:239], s[52:53], 0, v[174:175]
	global_load_lds_dwordx4 v[236:237], off
	s_add_i32 m0, s58, 0x2000
	s_nop 0
	global_load_lds_dwordx4 v[238:239], off
	s_waitcnt vmcnt(6)
	s_barrier
	v_mfma_f32_16x16x32_bf16 v[54:57], v[188:191], v[138:141], v[54:57]
	v_mfma_f32_16x16x32_bf16 v[50:53], v[224:227], v[138:141], v[50:53]
	v_mfma_f32_16x16x32_bf16 v[38:41], v[188:191], v[146:149], v[38:41]
	v_mfma_f32_16x16x32_bf16 v[34:37], v[224:227], v[146:149], v[34:37]
	v_mfma_f32_16x16x32_bf16 v[22:25], v[188:191], v[162:165], v[22:25]
	v_mfma_f32_16x16x32_bf16 v[18:21], v[224:227], v[162:165], v[18:21]
	v_mfma_f32_16x16x32_bf16 v[6:9], v[188:191], v[170:173], v[6:9]
	v_mfma_f32_16x16x32_bf16 v[2:5], v[224:227], v[170:173], v[2:5]
	v_mfma_f32_16x16x32_bf16 v[54:57], v[220:223], v[142:145], v[54:57]
	v_mfma_f32_16x16x32_bf16 v[50:53], v[228:231], v[142:145], v[50:53]
	v_mfma_f32_16x16x32_bf16 v[38:41], v[220:223], v[150:153], v[38:41]
	v_mfma_f32_16x16x32_bf16 v[34:37], v[228:231], v[150:153], v[34:37]
	v_mfma_f32_16x16x32_bf16 v[22:25], v[220:223], v[166:169], v[22:25]
	v_mfma_f32_16x16x32_bf16 v[18:21], v[228:231], v[166:169], v[18:21]
	v_mfma_f32_16x16x32_bf16 v[6:9], v[220:223], v[184:187], v[6:9]
	v_mfma_f32_16x16x32_bf16 v[2:5], v[228:231], v[184:187], v[2:5]
	s_add_i32 s52, 0, 0x18000
	v_add_u32_e32 v74, s52, v194
	s_barrier
	ds_read_b128 v[58:61], v74
	ds_read_b128 v[62:65], v74 offset:1024
	ds_read_b128 v[70:73], v74 offset:2048
	ds_read_b128 v[74:77], v74 offset:3072
	s_add_u32 s44, s44, s38
	s_addc_u32 s45, s45, 0
	s_mov_b32 m0, s51
	v_lshl_add_u64 v[188:189], s[44:45], 0, v[0:1]
	ds_read_b128 v[138:141], v196 offset:32768
	ds_read_b128 v[142:145], v196 offset:33792
	ds_read_b128 v[146:149], v196 offset:34816
	ds_read_b128 v[150:153], v196 offset:35840
	ds_read_b128 v[162:165], v196 offset:36864
	ds_read_b128 v[166:169], v196 offset:37888
	ds_read_b128 v[170:173], v196 offset:38912
	ds_read_b128 v[184:187], v196 offset:39936
	global_load_lds_dwordx4 v[188:189], off
	v_lshl_add_u64 v[188:189], s[44:45], 0, v[174:175]
	s_mov_b32 m0, s56
	s_nop 0
	global_load_lds_dwordx4 v[188:189], off
	s_waitcnt lgkmcnt(8)
	s_barrier
	s_waitcnt lgkmcnt(0)
	s_waitcnt lgkmcnt(0)
	v_mfma_f32_16x16x32_bf16 v[158:161], v[58:61], v[138:141], v[158:161]
	v_mfma_f32_16x16x32_bf16 v[154:157], v[70:73], v[138:141], v[154:157]
	v_mfma_f32_16x16x32_bf16 v[126:129], v[58:61], v[146:149], v[126:129]
	v_mfma_f32_16x16x32_bf16 v[122:125], v[70:73], v[146:149], v[122:125]
	v_mfma_f32_16x16x32_bf16 v[110:113], v[58:61], v[162:165], v[110:113]
	v_mfma_f32_16x16x32_bf16 v[106:109], v[70:73], v[162:165], v[106:109]
	v_mfma_f32_16x16x32_bf16 v[94:97], v[58:61], v[170:173], v[94:97]
	v_mfma_f32_16x16x32_bf16 v[90:93], v[70:73], v[170:173], v[90:93]
	v_mfma_f32_16x16x32_bf16 v[158:161], v[62:65], v[142:145], v[158:161]
	v_mfma_f32_16x16x32_bf16 v[154:157], v[74:77], v[142:145], v[154:157]
	v_mfma_f32_16x16x32_bf16 v[126:129], v[62:65], v[150:153], v[126:129]
	v_mfma_f32_16x16x32_bf16 v[122:125], v[74:77], v[150:153], v[122:125]
	v_mfma_f32_16x16x32_bf16 v[110:113], v[62:65], v[166:169], v[110:113]
	v_mfma_f32_16x16x32_bf16 v[106:109], v[74:77], v[166:169], v[106:109]
	v_mfma_f32_16x16x32_bf16 v[94:97], v[62:65], v[184:187], v[94:97]
	v_mfma_f32_16x16x32_bf16 v[90:93], v[74:77], v[184:187], v[90:93]
	s_barrier
	s_add_i32 s44, 0, 0x1c000
	s_add_i32 s45, s52, s20
	v_add_u32_e32 v197, s44, v194
	v_lshl_add_u64 v[192:193], v[192:193], 0, s[76:77]
	s_mov_b32 m0, s45
	ds_read_b128 v[188:191], v197
	ds_read_b128 v[220:223], v197 offset:1024
	ds_read_b128 v[224:227], v197 offset:2048
	ds_read_b128 v[228:231], v197 offset:3072
	global_load_lds_dwordx4 v[192:193], off
	v_lshl_add_u64 v[192:193], v[198:199], 0, s[76:77]
	s_add_i32 m0, s45, 0x2000
	s_nop 0
	global_load_lds_dwordx4 v[192:193], off
	s_barrier
; #define PG8_STAGE(bufoff, gbase, voff) do { _Pragma("unroll") for (int _i = 0; _i < 2; ++_i) \
;         __builtin_amdgcn_global_load_lds((const unsigned*)((const char*)(gbase) + (voff)[_i]), (LAS unsigned*)(lds + (bufoff) + ldsw + _i * 8192), 16, 0, 0); } while (0)
; #define PG8_LDA(dst, b, h) do { _Pragma("unroll") for (int m = 0; m < 4; ++m) _Pragma("unroll") for (int k = 0; k < 2; ++k) dst[m][k] = *(const LAS bf16x8*)(lds + PG8_SA(b, h) + aoff + m * 2048 + k * 1024); } while (0)
; #define PG8_MMA(ai, bj, At, Bt) do { __builtin_amdgcn_s_setprio(1); _Pragma("unroll") for (int m = 0; m < 4; ++m) _Pragma("unroll") for (int n = 0; n < 2; ++n) _Pragma("unroll") for (int k = 0; k < 2; ++k) \
;         acc[ai][bj][m][n] = __builtin_amdgcn_mfma_f32_16x16x32_bf16(Bt[n][k], At[m][k], acc[ai][bj][m][n], 0, 0, 0); __builtin_amdgcn_s_setprio(0); } while (0)
; #define PG8_WAIT_V(n) asm volatile("s_waitcnt vmcnt(" #n ")" ::: "memory")
; #define PG8_WAIT_L(n) asm volatile("s_waitcnt lgkmcnt(" #n ")" ::: "memory")
; #define PG8_BAR __builtin_amdgcn_s_barrier()
; #define PG8_SCHED __builtin_amdgcn_sched_barrier(0)
; template <int MODE, class EpiT, class Sched>
; __device__ __forceinline__ void gemm_phase(LAS unsigned char* lds, const Gemm g, const Sched& S, const EpiT& E) {
;     ...
;             PG8_LDA(At, 1, 1); PG8_STAGE(PG8_SA(1, 0), a3, voffA);
;             PG8_BAR; PG8_WAIT_L(0); PG8_MMA(1, 0, At, B0); PG8_BAR; PG8_SCHED;
;             PG8_STAGE(PG8_SB(1, 1), b3 + hstep, voffB);
;             PG8_WAIT_V(6); PG8_BAR; PG8_MMA(1, 1, At, B1); PG8_BAR;
;         }
	s_waitcnt lgkmcnt(0)
	s_waitcnt lgkmcnt(0)
	v_mfma_f32_16x16x32_bf16 v[134:137], v[188:191], v[138:141], v[134:137]
	v_mfma_f32_16x16x32_bf16 v[130:133], v[224:227], v[138:141], v[130:133]
	v_mfma_f32_16x16x32_bf16 v[118:121], v[188:191], v[146:149], v[118:121]
	v_mfma_f32_16x16x32_bf16 v[114:117], v[224:227], v[146:149], v[114:117]
	v_mfma_f32_16x16x32_bf16 v[102:105], v[188:191], v[162:165], v[102:105]
	v_mfma_f32_16x16x32_bf16 v[98:101], v[224:227], v[162:165], v[98:101]
	v_mfma_f32_16x16x32_bf16 v[86:89], v[188:191], v[170:173], v[86:89]
	v_mfma_f32_16x16x32_bf16 v[82:85], v[224:227], v[170:173], v[82:85]
	v_mfma_f32_16x16x32_bf16 v[134:137], v[220:223], v[142:145], v[134:137]
	v_mfma_f32_16x16x32_bf16 v[130:133], v[228:231], v[142:145], v[130:133]
	v_mfma_f32_16x16x32_bf16 v[118:121], v[220:223], v[150:153], v[118:121]
	v_mfma_f32_16x16x32_bf16 v[114:117], v[228:231], v[150:153], v[114:117]
	v_mfma_f32_16x16x32_bf16 v[102:105], v[220:223], v[166:169], v[102:105]
	v_mfma_f32_16x16x32_bf16 v[98:101], v[228:231], v[166:169], v[98:101]
	v_mfma_f32_16x16x32_bf16 v[86:89], v[220:223], v[184:187], v[86:89]
	v_mfma_f32_16x16x32_bf16 v[82:85], v[228:231], v[184:187], v[82:85]
	s_mov_b32 m0, s61
	v_lshl_add_u64 v[192:193], v[232:233], 0, s[76:77]
	s_barrier
	ds_read_b128 v[138:141], v196 offset:49152
	ds_read_b128 v[142:145], v196 offset:50176
	ds_read_b128 v[146:149], v196 offset:51200
	ds_read_b128 v[150:153], v196 offset:52224
	ds_read_b128 v[162:165], v196 offset:53248
	ds_read_b128 v[166:169], v196 offset:54272
	ds_read_b128 v[170:173], v196 offset:55296
	ds_read_b128 v[184:187], v196 offset:56320
	global_load_lds_dwordx4 v[192:193], off
	v_lshl_add_u64 v[192:193], v[234:235], 0, s[76:77]
	s_mov_b32 m0, s74
	s_nop 0
	global_load_lds_dwordx4 v[192:193], off
	s_barrier
	s_waitcnt lgkmcnt(0)
	s_waitcnt lgkmcnt(0)
	v_mfma_f32_16x16x32_bf16 v[78:81], v[58:61], v[138:141], v[78:81]
	v_mfma_f32_16x16x32_bf16 v[66:69], v[70:73], v[138:141], v[66:69]
	v_mfma_f32_16x16x32_bf16 v[46:49], v[58:61], v[146:149], v[46:49]
	v_mfma_f32_16x16x32_bf16 v[42:45], v[70:73], v[146:149], v[42:45]
	v_mfma_f32_16x16x32_bf16 v[30:33], v[58:61], v[162:165], v[30:33]
	v_mfma_f32_16x16x32_bf16 v[26:29], v[70:73], v[162:165], v[26:29]
	v_mfma_f32_16x16x32_bf16 v[14:17], v[58:61], v[170:173], v[14:17]
	v_mfma_f32_16x16x32_bf16 v[10:13], v[70:73], v[170:173], v[10:13]
	v_mfma_f32_16x16x32_bf16 v[78:81], v[62:65], v[142:145], v[78:81]
	v_mfma_f32_16x16x32_bf16 v[66:69], v[74:77], v[142:145], v[66:69]
	v_mfma_f32_16x16x32_bf16 v[46:49], v[62:65], v[150:153], v[46:49]
	v_mfma_f32_16x16x32_bf16 v[42:45], v[74:77], v[150:153], v[42:45]
	v_mfma_f32_16x16x32_bf16 v[30:33], v[62:65], v[166:169], v[30:33]
	v_mfma_f32_16x16x32_bf16 v[26:29], v[74:77], v[166:169], v[26:29]
	v_mfma_f32_16x16x32_bf16 v[14:17], v[62:65], v[184:187], v[14:17]
	v_mfma_f32_16x16x32_bf16 v[10:13], v[74:77], v[184:187], v[10:13]
	s_barrier
	s_add_i32 s44, s44, s20
	v_lshl_add_u64 v[58:59], v[236:237], 0, s[76:77]
	s_mov_b32 m0, s44
	s_nop 0
	global_load_lds_dwordx4 v[58:59], off
	v_lshl_add_u64 v[58:59], v[238:239], 0, s[76:77]
	s_add_i32 m0, s44, 0x2000
	s_nop 0
	global_load_lds_dwordx4 v[58:59], off
	s_waitcnt vmcnt(6)
	s_barrier
	v_mfma_f32_16x16x32_bf16 v[54:57], v[188:191], v[138:141], v[54:57]
	v_mfma_f32_16x16x32_bf16 v[50:53], v[224:227], v[138:141], v[50:53]
	v_mfma_f32_16x16x32_bf16 v[38:41], v[188:191], v[146:149], v[38:41]
	v_mfma_f32_16x16x32_bf16 v[34:37], v[224:227], v[146:149], v[34:37]
	v_mfma_f32_16x16x32_bf16 v[22:25], v[188:191], v[162:165], v[22:25]
	v_mfma_f32_16x16x32_bf16 v[18:21], v[224:227], v[162:165], v[18:21]
	v_mfma_f32_16x16x32_bf16 v[6:9], v[188:191], v[170:173], v[6:9]
	v_mfma_f32_16x16x32_bf16 v[2:5], v[224:227], v[170:173], v[2:5]
	v_mfma_f32_16x16x32_bf16 v[54:57], v[220:223], v[142:145], v[54:57]
	v_mfma_f32_16x16x32_bf16 v[50:53], v[228:231], v[142:145], v[50:53]
	v_mfma_f32_16x16x32_bf16 v[38:41], v[220:223], v[150:153], v[38:41]
	v_mfma_f32_16x16x32_bf16 v[34:37], v[228:231], v[150:153], v[34:37]
	v_mfma_f32_16x16x32_bf16 v[22:25], v[220:223], v[166:169], v[22:25]
	v_mfma_f32_16x16x32_bf16 v[18:21], v[228:231], v[166:169], v[18:21]
	v_mfma_f32_16x16x32_bf16 v[6:9], v[220:223], v[184:187], v[6:9]
	v_mfma_f32_16x16x32_bf16 v[2:5], v[228:231], v[184:187], v[2:5]
	s_add_u32 s4, s4, 0x100
	s_addc_u32 s5, s5, 0
	s_add_u32 s89, s89, 0x100
	s_addc_u32 s90, s90, 0
	s_cmp_ge_u32 vcc_lo, s60
	s_mov_b32 s44, vcc_lo
	s_barrier
	s_cbranch_scc0 .LBB0_195
	v_lshl_or_b32 v186, s24, 8, v195
	v_ashrrev_i32_e32 v187, 31, v186
	v_mov_b32_e32 v70, 0
	v_cndmask_b32_e64 v58, 0, 1, s[78:79]
	v_lshl_add_u64 v[138:139], v[186:187], 2, s[12:13]
	v_cmp_ne_u32_e64 s[44:45], 1, v58
	s_andn2_b64 vcc, exec, s[78:79]
	v_mov_b32_e32 v74, 0
	v_mov_b32_e32 v75, v70
	v_mov_b32_e32 v184, 0
	v_mov_b32_e32 v185, v70
	s_cbranch_vccnz .LBB0_198
	global_load_dwordx4 v[74:77], v[138:139], off
	s_waitcnt vmcnt(0)
	v_mov_b32_e32 v184, v76
	v_mov_b32_e32 v185, v77

; #define PG8_STAGE(bufoff, gbase, voff) do { _Pragma("unroll") for (int _i = 0; _i < 2; ++_i) \
;         __builtin_amdgcn_global_load_lds((const unsigned*)((const char*)(gbase) + (voff)[_i]), (LAS unsigned*)(lds + (bufoff) + ldsw + _i * 8192), 16, 0, 0); } while (0)
; #define PG8_LDA(dst, b, h) do { _Pragma("unroll") for (int m = 0; m < 4; ++m) _Pragma("unroll") for (int k = 0; k < 2; ++k) dst[m][k] = *(const LAS bf16x8*)(lds + PG8_SA(b, h) + aoff + m * 2048 + k * 1024); } while (0)
; #define PG8_LDB(dst, b, h) do { _Pragma("unroll") for (int n = 0; n < 2; ++n) _Pragma("unroll") for (int k = 0; k < 2; ++k) dst[n][k] = *(const LAS bf16x8*)(lds + PG8_SB(b, h) + boff + n * 2048 + k * 1024); } while (0)
; #define PG8_MMA(ai, bj, At, Bt) do { __builtin_amdgcn_s_setprio(1); _Pragma("unroll") for (int m = 0; m < 4; ++m) _Pragma("unroll") for (int n = 0; n < 2; ++n) _Pragma("unroll") for (int k = 0; k < 2; ++k) \
;         acc[ai][bj][m][n] = __builtin_amdgcn_mfma_f32_16x16x32_bf16(Bt[n][k], At[m][k], acc[ai][bj][m][n], 0, 0, 0); __builtin_amdgcn_s_setprio(0); } while (0)
; #define PG8_WAIT_L(n) asm volatile("s_waitcnt lgkmcnt(" #n ")" ::: "memory")
; #define PG8_BAR __builtin_amdgcn_s_barrier()
; #define PG8_SCHED __builtin_amdgcn_sched_barrier(0)
; template <int MODE, class EpiT, class Sched>
; __device__ __forceinline__ void gemm_phase(LAS unsigned char* lds, const Gemm g, const Sched& S, const EpiT& E) {
;     ...
;         for (int t = 0; t < nt; t += 2) {
;             const bool last = (t == nt - 2);
;             const char* a1 = cA + (size_t)(t + 1) * kstep;
;             const char* a2 = last ? nA : cA + (size_t)(t + 2) * kstep; const char* b2 = last ? nB : cB + (size_t)(t + 2) * kstep;
;             const char* a3 = a2 + kstep; const char* b3 = b2 + kstep;
;             PG8_LDB(B0, 0, 0); PG8_SCHED; PG8_LDA(At, 0, 0); PG8_STAGE(PG8_SA(1, 1), a1 + hstep, voffA);
;             PG8_WAIT_L(8); PG8_BAR; PG8_WAIT_L(0); PG8_MMA(0, 0, At, B0); PG8_BAR; PG8_SCHED;
;             PG8_LDB(B1, 0, 1); PG8_STAGE(PG8_SB(0, 0), b2, voffB);
;             PG8_BAR; PG8_WAIT_L(0); PG8_MMA(0, 1, At, B1); PG8_BAR;
;             PG8_LDA(At, 0, 1); PG8_STAGE(PG8_SA(0, 0), a2, voffA);
;             PG8_BAR; PG8_WAIT_L(0); PG8_MMA(1, 0, At, B0); PG8_BAR; PG8_SCHED;
.LBB0_236:
	s_add_i32 s44, s34, 2
	s_add_u32 s38, s28, 0x80
	s_addc_u32 s35, s29, 0
	s_add_i32 s45, 0, 0x10000
	v_add_u32_e32 v136, s45, v139
	ds_read_b128 v[142:145], v136
	ds_read_b128 v[146:149], v136 offset:1024
	ds_read_b128 v[150:153], v136 offset:2048
	ds_read_b128 v[154:157], v136 offset:3072
	s_cmp_eq_u32 s52, s34
	s_cselect_b32 s34, s4, s38
	s_cselect_b32 s35, s5, s35
	s_cselect_b32 s39, s11, s43
	s_cselect_b32 s38, s10, s42
	v_lshl_add_u64 v[136:137], s[28:29], 0, v[132:133]
	s_add_i32 m0, s22, 0xc000
	ds_read_b128 v[158:161], v141
	ds_read_b128 v[162:165], v141 offset:1024
	ds_read_b128 v[166:169], v141 offset:2048
	ds_read_b128 v[170:173], v141 offset:3072
	ds_read_b128 v[174:177], v141 offset:4096
	ds_read_b128 v[182:185], v141 offset:5120
	ds_read_b128 v[186:189], v141 offset:6144
	ds_read_b128 v[190:193], v141 offset:7168
	global_load_lds_dwordx4 v[136:137], off
	v_lshl_add_u64 v[136:137], s[28:29], 0, v[134:135]
	s_add_i32 m0, s22, 0xe000
	s_nop 0
	global_load_lds_dwordx4 v[136:137], off
	s_waitcnt lgkmcnt(8)
	s_barrier
	s_waitcnt lgkmcnt(0)
	s_waitcnt lgkmcnt(0)
	v_mfma_f32_16x16x32_bf16 v[126:129], v[142:145], v[158:161], v[126:129]
	v_mfma_f32_16x16x32_bf16 v[122:125], v[150:153], v[158:161], v[122:125]
	v_mfma_f32_16x16x32_bf16 v[118:121], v[142:145], v[166:169], v[118:121]
	v_mfma_f32_16x16x32_bf16 v[110:113], v[150:153], v[166:169], v[110:113]
	v_mfma_f32_16x16x32_bf16 v[102:105], v[142:145], v[174:177], v[102:105]
	v_mfma_f32_16x16x32_bf16 v[94:97], v[150:153], v[174:177], v[94:97]
	v_mfma_f32_16x16x32_bf16 v[86:89], v[142:145], v[186:189], v[86:89]
	v_mfma_f32_16x16x32_bf16 v[78:81], v[150:153], v[186:189], v[78:81]
	v_mfma_f32_16x16x32_bf16 v[126:129], v[146:149], v[162:165], v[126:129]
	v_mfma_f32_16x16x32_bf16 v[122:125], v[154:157], v[162:165], v[122:125]
	v_mfma_f32_16x16x32_bf16 v[118:121], v[146:149], v[170:173], v[118:121]
	v_mfma_f32_16x16x32_bf16 v[110:113], v[154:157], v[170:173], v[110:113]
	v_mfma_f32_16x16x32_bf16 v[102:105], v[146:149], v[182:185], v[102:105]
	v_mfma_f32_16x16x32_bf16 v[94:97], v[154:157], v[182:185], v[94:97]
	v_mfma_f32_16x16x32_bf16 v[86:89], v[146:149], v[190:193], v[86:89]
	v_mfma_f32_16x16x32_bf16 v[78:81], v[154:157], v[190:193], v[78:81]
	s_barrier
	s_add_i32 s58, 0, 0x14000
	v_add_u32_e32 v136, s58, v139
	s_add_i32 s45, s45, s9
	ds_read_b128 v[194:197], v136
	ds_read_b128 v[220:223], v136 offset:1024
	ds_read_b128 v[224:227], v136 offset:2048
	ds_read_b128 v[228:231], v136 offset:3072
	v_lshl_add_u64 v[136:137], s[38:39], 0, v[0:1]
	s_mov_b32 m0, s45
	v_lshl_add_u64 v[198:199], s[38:39], 0, v[130:131]
	global_load_lds_dwordx4 v[136:137], off
	s_add_i32 m0, s45, 0x2000
	s_nop 0
	global_load_lds_dwordx4 v[198:199], off
	s_barrier
	s_waitcnt lgkmcnt(0)
	s_waitcnt lgkmcnt(0)
	v_mfma_f32_16x16x32_bf16 v[114:117], v[194:197], v[158:161], v[114:117]
	v_mfma_f32_16x16x32_bf16 v[106:109], v[224:227], v[158:161], v[106:109]
	v_mfma_f32_16x16x32_bf16 v[98:101], v[194:197], v[166:169], v[98:101]
	v_mfma_f32_16x16x32_bf16 v[90:93], v[224:227], v[166:169], v[90:93]
	v_mfma_f32_16x16x32_bf16 v[82:85], v[194:197], v[174:177], v[82:85]
	v_mfma_f32_16x16x32_bf16 v[74:77], v[224:227], v[174:177], v[74:77]
	v_mfma_f32_16x16x32_bf16 v[70:73], v[194:197], v[186:189], v[70:73]
	v_mfma_f32_16x16x32_bf16 v[66:69], v[224:227], v[186:189], v[66:69]
	v_mfma_f32_16x16x32_bf16 v[114:117], v[220:223], v[162:165], v[114:117]
	v_mfma_f32_16x16x32_bf16 v[106:109], v[228:231], v[162:165], v[106:109]
	v_mfma_f32_16x16x32_bf16 v[98:101], v[220:223], v[170:173], v[98:101]
	v_mfma_f32_16x16x32_bf16 v[90:93], v[228:231], v[170:173], v[90:93]
	v_mfma_f32_16x16x32_bf16 v[82:85], v[220:223], v[182:185], v[82:85]
	v_mfma_f32_16x16x32_bf16 v[74:77], v[228:231], v[182:185], v[74:77]
	v_mfma_f32_16x16x32_bf16 v[70:73], v[220:223], v[190:193], v[70:73]
	v_mfma_f32_16x16x32_bf16 v[66:69], v[228:231], v[190:193], v[66:69]
	s_mov_b32 m0, s22
	v_lshl_add_u64 v[232:233], s[34:35], 0, v[0:1]
	s_barrier
	ds_read_b128 v[158:161], v141 offset:16384
	ds_read_b128 v[162:165], v141 offset:17408
	ds_read_b128 v[166:169], v141 offset:18432
	ds_read_b128 v[170:173], v141 offset:19456
	ds_read_b128 v[174:177], v141 offset:20480
	ds_read_b128 v[182:185], v141 offset:21504
	ds_read_b128 v[186:189], v141 offset:22528
	ds_read_b128 v[190:193], v141 offset:23552
	global_load_lds_dwordx4 v[232:233], off
	v_lshl_add_u64 v[234:235], s[34:35], 0, v[130:131]
	s_mov_b32 m0, s23
	s_nop 0
	global_load_lds_dwordx4 v[234:235], off
	s_barrier
	s_waitcnt lgkmcnt(0)
	s_waitcnt lgkmcnt(0)
	v_mfma_f32_16x16x32_bf16 v[62:65], v[142:145], v[158:161], v[62:65]
	v_mfma_f32_16x16x32_bf16 v[58:61], v[150:153], v[158:161], v[58:61]
	v_mfma_f32_16x16x32_bf16 v[54:57], v[142:145], v[166:169], v[54:57]
	v_mfma_f32_16x16x32_bf16 v[46:49], v[150:153], v[166:169], v[46:49]
	v_mfma_f32_16x16x32_bf16 v[38:41], v[142:145], v[174:177], v[38:41]
	v_mfma_f32_16x16x32_bf16 v[30:33], v[150:153], v[174:177], v[30:33]
	v_mfma_f32_16x16x32_bf16 v[22:25], v[142:145], v[186:189], v[22:25]
	v_mfma_f32_16x16x32_bf16 v[14:17], v[150:153], v[186:189], v[14:17]
	v_mfma_f32_16x16x32_bf16 v[62:65], v[146:149], v[162:165], v[62:65]
	v_mfma_f32_16x16x32_bf16 v[58:61], v[154:157], v[162:165], v[58:61]
	v_mfma_f32_16x16x32_bf16 v[54:57], v[146:149], v[170:173], v[54:57]
	v_mfma_f32_16x16x32_bf16 v[46:49], v[154:157], v[170:173], v[46:49]
	v_mfma_f32_16x16x32_bf16 v[38:41], v[146:149], v[182:185], v[38:41]
	v_mfma_f32_16x16x32_bf16 v[30:33], v[154:157], v[182:185], v[30:33]
	v_mfma_f32_16x16x32_bf16 v[22:25], v[146:149], v[190:193], v[22:25]
	v_mfma_f32_16x16x32_bf16 v[14:17], v[154:157], v[190:193], v[14:17]
	s_barrier
; #define PG8_STAGE(bufoff, gbase, voff) do { _Pragma("unroll") for (int _i = 0; _i < 2; ++_i) \
;         __builtin_amdgcn_global_load_lds((const unsigned*)((const char*)(gbase) + (voff)[_i]), (LAS unsigned*)(lds + (bufoff) + ldsw + _i * 8192), 16, 0, 0); } while (0)
; #define PG8_LDA(dst, b, h) do { _Pragma("unroll") for (int m = 0; m < 4; ++m) _Pragma("unroll") for (int k = 0; k < 2; ++k) dst[m][k] = *(const LAS bf16x8*)(lds + PG8_SA(b, h) + aoff + m * 2048 + k * 1024); } while (0)
; #define PG8_LDB(dst, b, h) do { _Pragma("unroll") for (int n = 0; n < 2; ++n) _Pragma("unroll") for (int k = 0; k < 2; ++k) dst[n][k] = *(const LAS bf16x8*)(lds + PG8_SB(b, h) + boff + n * 2048 + k * 1024); } while (0)
; #define PG8_MMA(ai, bj, At, Bt) do { __builtin_amdgcn_s_setprio(1); _Pragma("unroll") for (int m = 0; m < 4; ++m) _Pragma("unroll") for (int n = 0; n < 2; ++n) _Pragma("unroll") for (int k = 0; k < 2; ++k) \
;         acc[ai][bj][m][n] = __builtin_amdgcn_mfma_f32_16x16x32_bf16(Bt[n][k], At[m][k], acc[ai][bj][m][n], 0, 0, 0); __builtin_amdgcn_s_setprio(0); } while (0)
; #define PG8_WAIT_V(n) asm volatile("s_waitcnt vmcnt(" #n ")" ::: "memory")
; #define PG8_WAIT_L(n) asm volatile("s_waitcnt lgkmcnt(" #n ")" ::: "memory")
; #define PG8_BAR __builtin_amdgcn_s_barrier()
; #define PG8_SCHED __builtin_amdgcn_sched_barrier(0)
; template <int MODE, class EpiT, class Sched>
; __device__ __forceinline__ void gemm_phase(LAS unsigned char* lds, const Gemm g, const Sched& S, const EpiT& E) {
;     ...
;             PG8_BAR; PG8_WAIT_L(0); PG8_MMA(1, 0, At, B0); PG8_BAR; PG8_SCHED;
;             PG8_STAGE(PG8_SB(0, 1), b2 + hstep, voffB);
;             PG8_WAIT_V(6); PG8_BAR; PG8_MMA(1, 1, At, B1); PG8_BAR;
;             PG8_LDB(B0, 1, 0); PG8_SCHED; PG8_LDA(At, 1, 0); PG8_STAGE(PG8_SA(0, 1), a2 + hstep, voffA);
;             PG8_WAIT_L(8); PG8_BAR; PG8_WAIT_L(0); PG8_MMA(0, 0, At, B0); PG8_BAR; PG8_SCHED;
;             PG8_LDB(B1, 1, 1); PG8_STAGE(PG8_SB(1, 0), b3, voffB);
;             PG8_BAR; PG8_WAIT_L(0); PG8_MMA(0, 1, At, B1); PG8_BAR;
;             PG8_LDA(At, 1, 1); PG8_STAGE(PG8_SA(1, 0), a3, voffA);
;             PG8_BAR; PG8_WAIT_L(0); PG8_MMA(1, 0, At, B0); PG8_BAR; PG8_SCHED;
	s_add_u32 s38, s38, s24
	s_addc_u32 s39, s39, 0
	s_add_i32 s45, s58, s9
	v_lshl_add_u64 v[236:237], s[38:39], 0, v[0:1]
	s_mov_b32 m0, s45
	v_lshl_add_u64 v[238:239], s[38:39], 0, v[130:131]
	global_load_lds_dwordx4 v[236:237], off
	s_add_i32 m0, s45, 0x2000
	s_nop 0
	global_load_lds_dwordx4 v[238:239], off
	s_waitcnt vmcnt(6)
	s_barrier
	v_mfma_f32_16x16x32_bf16 v[50:53], v[194:197], v[158:161], v[50:53]
	v_mfma_f32_16x16x32_bf16 v[42:45], v[224:227], v[158:161], v[42:45]
	v_mfma_f32_16x16x32_bf16 v[34:37], v[194:197], v[166:169], v[34:37]
	v_mfma_f32_16x16x32_bf16 v[26:29], v[224:227], v[166:169], v[26:29]
	v_mfma_f32_16x16x32_bf16 v[18:21], v[194:197], v[174:177], v[18:21]
	v_mfma_f32_16x16x32_bf16 v[10:13], v[224:227], v[174:177], v[10:13]
	v_mfma_f32_16x16x32_bf16 v[6:9], v[194:197], v[186:189], v[6:9]
	v_mfma_f32_16x16x32_bf16 v[2:5], v[224:227], v[186:189], v[2:5]
	v_mfma_f32_16x16x32_bf16 v[50:53], v[220:223], v[162:165], v[50:53]
	v_mfma_f32_16x16x32_bf16 v[42:45], v[228:231], v[162:165], v[42:45]
	v_mfma_f32_16x16x32_bf16 v[34:37], v[220:223], v[170:173], v[34:37]
	v_mfma_f32_16x16x32_bf16 v[26:29], v[228:231], v[170:173], v[26:29]
	v_mfma_f32_16x16x32_bf16 v[18:21], v[220:223], v[182:185], v[18:21]
	v_mfma_f32_16x16x32_bf16 v[10:13], v[228:231], v[182:185], v[10:13]
	v_mfma_f32_16x16x32_bf16 v[6:9], v[220:223], v[190:193], v[6:9]
	v_mfma_f32_16x16x32_bf16 v[2:5], v[228:231], v[190:193], v[2:5]
	s_add_i32 s38, 0, 0x18000
	v_add_u32_e32 v154, s38, v139
	s_barrier
	ds_read_b128 v[142:145], v154
	ds_read_b128 v[146:149], v154 offset:1024
	ds_read_b128 v[150:153], v154 offset:2048
	ds_read_b128 v[154:157], v154 offset:3072
	s_add_u32 s34, s34, s24
	s_addc_u32 s35, s35, 0
	s_mov_b32 m0, s30
	v_lshl_add_u64 v[194:195], s[34:35], 0, v[0:1]
	ds_read_b128 v[158:161], v141 offset:32768
	ds_read_b128 v[162:165], v141 offset:33792
	ds_read_b128 v[166:169], v141 offset:34816
	ds_read_b128 v[170:173], v141 offset:35840
	ds_read_b128 v[174:177], v141 offset:36864
	ds_read_b128 v[182:185], v141 offset:37888
	ds_read_b128 v[186:189], v141 offset:38912
	ds_read_b128 v[190:193], v141 offset:39936
	global_load_lds_dwordx4 v[194:195], off
	v_lshl_add_u64 v[194:195], s[34:35], 0, v[130:131]
	s_mov_b32 m0, s46
	s_nop 0
	global_load_lds_dwordx4 v[194:195], off
	s_waitcnt lgkmcnt(8)
	s_barrier
	s_waitcnt lgkmcnt(0)
	s_waitcnt lgkmcnt(0)
	v_mfma_f32_16x16x32_bf16 v[126:129], v[142:145], v[158:161], v[126:129]
	v_mfma_f32_16x16x32_bf16 v[122:125], v[150:153], v[158:161], v[122:125]
	v_mfma_f32_16x16x32_bf16 v[118:121], v[142:145], v[166:169], v[118:121]
	v_mfma_f32_16x16x32_bf16 v[110:113], v[150:153], v[166:169], v[110:113]
	v_mfma_f32_16x16x32_bf16 v[102:105], v[142:145], v[174:177], v[102:105]
	v_mfma_f32_16x16x32_bf16 v[94:97], v[150:153], v[174:177], v[94:97]
	v_mfma_f32_16x16x32_bf16 v[86:89], v[142:145], v[186:189], v[86:89]
	v_mfma_f32_16x16x32_bf16 v[78:81], v[150:153], v[186:189], v[78:81]
	v_mfma_f32_16x16x32_bf16 v[126:129], v[146:149], v[162:165], v[126:129]
	v_mfma_f32_16x16x32_bf16 v[122:125], v[154:157], v[162:165], v[122:125]
	v_mfma_f32_16x16x32_bf16 v[118:121], v[146:149], v[170:173], v[118:121]
	v_mfma_f32_16x16x32_bf16 v[110:113], v[154:157], v[170:173], v[110:113]
	v_mfma_f32_16x16x32_bf16 v[102:105], v[146:149], v[182:185], v[102:105]
	v_mfma_f32_16x16x32_bf16 v[94:97], v[154:157], v[182:185], v[94:97]
	v_mfma_f32_16x16x32_bf16 v[86:89], v[146:149], v[190:193], v[86:89]
	v_mfma_f32_16x16x32_bf16 v[78:81], v[154:157], v[190:193], v[78:81]
	s_barrier
	s_add_i32 s34, 0, 0x1c000
	s_add_i32 s35, s38, s9
	v_add_u32_e32 v181, s34, v139
	v_lshl_add_u64 v[136:137], v[136:137], 0, s[76:77]
	s_mov_b32 m0, s35
	ds_read_b128 v[194:197], v181
	ds_read_b128 v[220:223], v181 offset:1024
	ds_read_b128 v[224:227], v181 offset:2048
	ds_read_b128 v[228:231], v181 offset:3072
	global_load_lds_dwordx4 v[136:137], off
	v_lshl_add_u64 v[136:137], v[198:199], 0, s[76:77]
	s_add_i32 m0, s35, 0x2000
	s_nop 0
	global_load_lds_dwordx4 v[136:137], off
	s_barrier
	s_waitcnt lgkmcnt(0)
	s_waitcnt lgkmcnt(0)
	v_mfma_f32_16x16x32_bf16 v[114:117], v[194:197], v[158:161], v[114:117]
	v_mfma_f32_16x16x32_bf16 v[106:109], v[224:227], v[158:161], v[106:109]
	v_mfma_f32_16x16x32_bf16 v[98:101], v[194:197], v[166:169], v[98:101]
	v_mfma_f32_16x16x32_bf16 v[90:93], v[224:227], v[166:169], v[90:93]
	v_mfma_f32_16x16x32_bf16 v[82:85], v[194:197], v[174:177], v[82:85]
	v_mfma_f32_16x16x32_bf16 v[74:77], v[224:227], v[174:177], v[74:77]
	v_mfma_f32_16x16x32_bf16 v[70:73], v[194:197], v[186:189], v[70:73]
	v_mfma_f32_16x16x32_bf16 v[66:69], v[224:227], v[186:189], v[66:69]
	v_mfma_f32_16x16x32_bf16 v[114:117], v[220:223], v[162:165], v[114:117]
	v_mfma_f32_16x16x32_bf16 v[106:109], v[228:231], v[162:165], v[106:109]
	v_mfma_f32_16x16x32_bf16 v[98:101], v[220:223], v[170:173], v[98:101]
	v_mfma_f32_16x16x32_bf16 v[90:93], v[228:231], v[170:173], v[90:93]
	v_mfma_f32_16x16x32_bf16 v[82:85], v[220:223], v[182:185], v[82:85]
	v_mfma_f32_16x16x32_bf16 v[74:77], v[228:231], v[182:185], v[74:77]
	v_mfma_f32_16x16x32_bf16 v[70:73], v[220:223], v[190:193], v[70:73]
	v_mfma_f32_16x16x32_bf16 v[66:69], v[228:231], v[190:193], v[66:69]
	s_mov_b32 m0, s50
	v_lshl_add_u64 v[136:137], v[232:233], 0, s[76:77]
	s_barrier
	ds_read_b128 v[158:161], v141 offset:49152
	ds_read_b128 v[162:165], v141 offset:50176
	ds_read_b128 v[166:169], v141 offset:51200
	ds_read_b128 v[170:173], v141 offset:52224
	ds_read_b128 v[174:177], v141 offset:53248
	ds_read_b128 v[182:185], v141 offset:54272
	ds_read_b128 v[186:189], v141 offset:55296
	ds_read_b128 v[190:193], v141 offset:56320
	global_load_lds_dwordx4 v[136:137], off
	v_lshl_add_u64 v[136:137], v[234:235], 0, s[76:77]
	s_mov_b32 m0, s51
	s_nop 0
	global_load_lds_dwordx4 v[136:137], off
	s_barrier
; #define PG8_STAGE(bufoff, gbase, voff) do { _Pragma("unroll") for (int _i = 0; _i < 2; ++_i) \
;         __builtin_amdgcn_global_load_lds((const unsigned*)((const char*)(gbase) + (voff)[_i]), (LAS unsigned*)(lds + (bufoff) + ldsw + _i * 8192), 16, 0, 0); } while (0)
; #define PG8_MMA(ai, bj, At, Bt) do { __builtin_amdgcn_s_setprio(1); _Pragma("unroll") for (int m = 0; m < 4; ++m) _Pragma("unroll") for (int n = 0; n < 2; ++n) _Pragma("unroll") for (int k = 0; k < 2; ++k) \
;         acc[ai][bj][m][n] = __builtin_amdgcn_mfma_f32_16x16x32_bf16(Bt[n][k], At[m][k], acc[ai][bj][m][n], 0, 0, 0); __builtin_amdgcn_s_setprio(0); } while (0)
; #define PG8_WAIT_V(n) asm volatile("s_waitcnt vmcnt(" #n ")" ::: "memory")
; #define PG8_WAIT_L(n) asm volatile("s_waitcnt lgkmcnt(" #n ")" ::: "memory")
; #define PG8_BAR __builtin_amdgcn_s_barrier()
; #define PG8_SCHED __builtin_amdgcn_sched_barrier(0)
; template <int MODE, class EpiT, class Sched>
; __device__ __forceinline__ void gemm_phase(LAS unsigned char* lds, const Gemm g, const Sched& S, const EpiT& E) {
;     ...
;             PG8_BAR; PG8_WAIT_L(0); PG8_MMA(1, 0, At, B0); PG8_BAR; PG8_SCHED;
;             PG8_STAGE(PG8_SB(1, 1), b3 + hstep, voffB);
;             PG8_WAIT_V(6); PG8_BAR; PG8_MMA(1, 1, At, B1); PG8_BAR;
	s_waitcnt lgkmcnt(0)
	s_waitcnt lgkmcnt(0)
	v_mfma_f32_16x16x32_bf16 v[62:65], v[142:145], v[158:161], v[62:65]
	v_mfma_f32_16x16x32_bf16 v[58:61], v[150:153], v[158:161], v[58:61]
	v_mfma_f32_16x16x32_bf16 v[54:57], v[142:145], v[166:169], v[54:57]
	v_mfma_f32_16x16x32_bf16 v[46:49], v[150:153], v[166:169], v[46:49]
	v_mfma_f32_16x16x32_bf16 v[38:41], v[142:145], v[174:177], v[38:41]
	v_mfma_f32_16x16x32_bf16 v[30:33], v[150:153], v[174:177], v[30:33]
	v_mfma_f32_16x16x32_bf16 v[22:25], v[142:145], v[186:189], v[22:25]
	v_mfma_f32_16x16x32_bf16 v[14:17], v[150:153], v[186:189], v[14:17]
	v_mfma_f32_16x16x32_bf16 v[62:65], v[146:149], v[162:165], v[62:65]
	v_mfma_f32_16x16x32_bf16 v[58:61], v[154:157], v[162:165], v[58:61]
	v_mfma_f32_16x16x32_bf16 v[54:57], v[146:149], v[170:173], v[54:57]
	v_mfma_f32_16x16x32_bf16 v[46:49], v[154:157], v[170:173], v[46:49]
	v_mfma_f32_16x16x32_bf16 v[38:41], v[146:149], v[182:185], v[38:41]
	v_mfma_f32_16x16x32_bf16 v[30:33], v[154:157], v[182:185], v[30:33]
	v_mfma_f32_16x16x32_bf16 v[22:25], v[146:149], v[190:193], v[22:25]
	v_mfma_f32_16x16x32_bf16 v[14:17], v[154:157], v[190:193], v[14:17]
	s_barrier
	s_add_i32 s34, s34, s9
	v_lshl_add_u64 v[136:137], v[236:237], 0, s[76:77]
	s_mov_b32 m0, s34
	s_nop 0
	global_load_lds_dwordx4 v[136:137], off
	v_lshl_add_u64 v[136:137], v[238:239], 0, s[76:77]
	s_add_i32 m0, s34, 0x2000
	s_nop 0
	global_load_lds_dwordx4 v[136:137], off
	s_waitcnt vmcnt(6)
	s_barrier
	v_mfma_f32_16x16x32_bf16 v[50:53], v[194:197], v[158:161], v[50:53]
	v_mfma_f32_16x16x32_bf16 v[42:45], v[224:227], v[158:161], v[42:45]
	v_mfma_f32_16x16x32_bf16 v[34:37], v[194:197], v[166:169], v[34:37]
	v_mfma_f32_16x16x32_bf16 v[26:29], v[224:227], v[166:169], v[26:29]
	v_mfma_f32_16x16x32_bf16 v[18:21], v[194:197], v[174:177], v[18:21]
	v_mfma_f32_16x16x32_bf16 v[10:13], v[224:227], v[174:177], v[10:13]
	v_mfma_f32_16x16x32_bf16 v[6:9], v[194:197], v[186:189], v[6:9]
	v_mfma_f32_16x16x32_bf16 v[2:5], v[224:227], v[186:189], v[2:5]
	v_mfma_f32_16x16x32_bf16 v[50:53], v[220:223], v[162:165], v[50:53]
	v_mfma_f32_16x16x32_bf16 v[42:45], v[228:231], v[162:165], v[42:45]
	v_mfma_f32_16x16x32_bf16 v[34:37], v[220:223], v[170:173], v[34:37]
	v_mfma_f32_16x16x32_bf16 v[26:29], v[228:231], v[170:173], v[26:29]
	v_mfma_f32_16x16x32_bf16 v[18:21], v[220:223], v[182:185], v[18:21]
	v_mfma_f32_16x16x32_bf16 v[10:13], v[228:231], v[182:185], v[10:13]
	v_mfma_f32_16x16x32_bf16 v[6:9], v[220:223], v[190:193], v[6:9]
	v_mfma_f32_16x16x32_bf16 v[2:5], v[228:231], v[190:193], v[2:5]
	s_add_u32 s28, s28, 0x100
	s_addc_u32 s29, s29, 0
	s_add_u32 s42, s42, 0x100
	s_addc_u32 s43, s43, 0
	s_cmp_ge_u32 s44, s47
	s_mov_b32 s34, s44
	s_barrier
	s_cbranch_scc0 .LBB0_236
; __device__ __forceinline__ unsigned pk2(float lo, float hi) { unsigned r; asm volatile("v_cvt_pk_bf16_f32 %0, %1, %2" : "=v"(r) : "v"(lo), "v"(hi)); return r; }
; #define PG8_WAIT_V(n) asm volatile("s_waitcnt vmcnt(" #n ")" ::: "memory")
; #define PG8_BAR __builtin_amdgcn_s_barrier()
;     template <int mode> __device__ __forceinline__ void run(const f32x4 (&acc)[2][2][4][2], const Unit& u, int wr, int wc, int fr, int fq, const LAS float* sc) const {
;     ...
;         } else if (mode == 2) {
;             const int col0 = u.pn * BM + wc * 32 + 8 * fq;
; #pragma unroll
;             for (int ai = 0; ai < 2; ++ai)
; #pragma unroll
;                 for (int m = 0; m < 4; ++m) {
;                     bf16_t* rowp = ob + (size_t)(row0 + ai * HALF + m * 16) * D + col0;
; #pragma unroll
;                     for (int bj = 0; bj < 2; ++bj) {
;                         const f32x4 v0 = acc[ai][bj][m][0], v1 = acc[ai][bj][m][1];
;                         u32x4 w; w.x = pk2(v0[0], v0[1]); w.y = pk2(v0[2], v0[3]); w.z = pk2(v1[0], v1[1]); w.w = pk2(v1[2], v1[3]);
;                         *(u32x4*)(rowp + bj * HALF) = w;
;                     }
;                 }
; template <int MODE, class EpiT, class Sched>
; __device__ __forceinline__ void gemm_phase(LAS unsigned char* lds, const Gemm g, const Sched& S, const EpiT& E) {
;     ...
;         E.template run<MODE>(acc, cur, wr, wc, fr, fq, SC + ui * 256);
;         if (!has_next) break;
; #pragma unroll
;         for (int a = 0; a < 2; ++a)
; #pragma unroll
;             for (int b = 0; b < 2; ++b)
; #pragma unroll
;                 for (int m = 0; m < 4; ++m)
; #pragma unroll
;                     for (int n = 0; n < 2; ++n) acc[a][b][m][n] = (f32x4){0.f, 0.f, 0.f, 0.f};
;         cur = nxt; cA = nA; cB = nB; ++ui;
;     }
;     PG8_WAIT_V(0);
;     if (wr == 0) PG8_BAR;
;     PG8_BAR;
	v_lshl_add_u32 v142, s56, 8, v138
	v_lshl_or_b32 v136, s61, 8, v140
	v_ashrrev_i32_e32 v143, 31, v142
	v_ashrrev_i32_e32 v137, 31, v136
	v_lshlrev_b64 v[144:145], 11, v[142:143]
	v_lshl_add_u64 v[144:145], s[6:7], 0, v[144:145]
	v_lshlrev_b64 v[146:147], 1, v[136:137]
	v_lshl_add_u64 v[136:137], v[144:145], 0, v[146:147]
	v_cvt_pk_bf16_f32 v126, v126, v127
	v_cvt_pk_bf16_f32 v127, v128, v129
	v_cvt_pk_bf16_f32 v128, v122, v123
	v_cvt_pk_bf16_f32 v129, v124, v125
	global_store_dwordx4 v[136:137], v[126:129], off
	v_cvt_pk_bf16_f32 v114, v114, v115
	v_cvt_pk_bf16_f32 v115, v116, v117
	v_cvt_pk_bf16_f32 v116, v106, v107
	v_or_b32_e32 v106, 16, v142
	v_ashrrev_i32_e32 v107, 31, v106
	v_lshlrev_b64 v[106:107], 11, v[106:107]
	v_lshl_add_u64 v[106:107], s[6:7], 0, v[106:107]
	v_cvt_pk_bf16_f32 v117, v108, v109
	global_store_dwordx4 v[136:137], v[114:117], off offset:256
	s_mov_b64 s[28:29], 0x40000
	s_mov_b32 s61, s57
	v_lshl_add_u64 v[114:115], v[106:107], 0, v[146:147]
	v_cvt_pk_bf16_f32 v106, v118, v119
	v_cvt_pk_bf16_f32 v107, v120, v121
	v_cvt_pk_bf16_f32 v108, v110, v111
	v_cvt_pk_bf16_f32 v109, v112, v113
	global_store_dwordx4 v[114:115], v[106:109], off
	v_cvt_pk_bf16_f32 v98, v98, v99
	v_cvt_pk_bf16_f32 v99, v100, v101
	v_cvt_pk_bf16_f32 v100, v90, v91
	v_or_b32_e32 v90, 32, v142
	v_ashrrev_i32_e32 v91, 31, v90
	v_lshlrev_b64 v[90:91], 11, v[90:91]
	v_lshl_add_u64 v[90:91], s[6:7], 0, v[90:91]
	v_cvt_pk_bf16_f32 v101, v92, v93
	global_store_dwordx4 v[114:115], v[98:101], off offset:256
	s_mov_b32 s56, s60
	s_mov_b64 s[34:35], s[10:11]
	v_lshl_add_u64 v[98:99], v[90:91], 0, v[146:147]
	v_cvt_pk_bf16_f32 v90, v102, v103
	v_cvt_pk_bf16_f32 v91, v104, v105
	v_cvt_pk_bf16_f32 v92, v94, v95
	v_cvt_pk_bf16_f32 v93, v96, v97
	global_store_dwordx4 v[98:99], v[90:93], off
	v_cvt_pk_bf16_f32 v82, v82, v83
	v_cvt_pk_bf16_f32 v83, v84, v85
	v_cvt_pk_bf16_f32 v84, v74, v75
	v_or_b32_e32 v74, 48, v142
	v_ashrrev_i32_e32 v75, 31, v74
	v_lshlrev_b64 v[74:75], 11, v[74:75]
	v_lshl_add_u64 v[74:75], s[6:7], 0, v[74:75]
	v_cvt_pk_bf16_f32 v85, v76, v77
	global_store_dwordx4 v[98:99], v[82:85], off offset:256
	s_nop 1
	v_lshl_add_u64 v[82:83], v[74:75], 0, v[146:147]
	v_cvt_pk_bf16_f32 v74, v86, v87
	v_cvt_pk_bf16_f32 v75, v88, v89
	v_cvt_pk_bf16_f32 v76, v78, v79
	v_cvt_pk_bf16_f32 v77, v80, v81
	global_store_dwordx4 v[82:83], v[74:77], off
	v_cvt_pk_bf16_f32 v70, v70, v71
	v_cvt_pk_bf16_f32 v71, v72, v73
	v_cvt_pk_bf16_f32 v72, v66, v67
	v_cvt_pk_bf16_f32 v73, v68, v69
	global_store_dwordx4 v[82:83], v[70:73], off offset:256
	v_cvt_pk_bf16_f32 v62, v62, v63
	v_cvt_pk_bf16_f32 v63, v64, v65
	v_cvt_pk_bf16_f32 v64, v58, v59
	v_add_co_u32_e32 v58, vcc, s91, v136
	v_lshl_add_u64 v[66:67], v[136:137], 0, s[28:29]
	s_nop 0
	v_addc_co_u32_e32 v59, vcc, 0, v137, vcc
	v_cvt_pk_bf16_f32 v65, v60, v61
	global_store_dwordx4 v[58:59], v[62:65], off
	v_cvt_pk_bf16_f32 v50, v50, v51
	v_cvt_pk_bf16_f32 v51, v52, v53
	s_mov_b64 s[28:29], 0x48000
	v_cvt_pk_bf16_f32 v52, v42, v43
	v_cvt_pk_bf16_f32 v53, v44, v45
	global_store_dwordx4 v[66:67], v[50:53], off offset:256
	v_cvt_pk_bf16_f32 v42, v54, v55
	v_cvt_pk_bf16_f32 v43, v56, v57
	v_cvt_pk_bf16_f32 v44, v46, v47
	v_cvt_pk_bf16_f32 v45, v48, v49
	s_nop 1
	v_lshl_add_u64 v[50:51], v[136:137], 0, s[28:29]
	s_mov_b32 s28, 0x48000
	v_add_co_u32_e32 v46, vcc, s28, v136
	s_mov_b64 s[28:29], 0x50000
	s_nop 0
	v_addc_co_u32_e32 v47, vcc, 0, v137, vcc
	global_store_dwordx4 v[46:47], v[42:45], off
	v_cvt_pk_bf16_f32 v34, v34, v35
	v_cvt_pk_bf16_f32 v35, v36, v37
	v_cvt_pk_bf16_f32 v36, v26, v27
	v_cvt_pk_bf16_f32 v37, v28, v29
	global_store_dwordx4 v[50:51], v[34:37], off offset:256
	v_cvt_pk_bf16_f32 v26, v38, v39
	v_cvt_pk_bf16_f32 v27, v40, v41
	v_cvt_pk_bf16_f32 v28, v30, v31
	v_cvt_pk_bf16_f32 v29, v32, v33
	s_nop 1
	v_lshl_add_u64 v[34:35], v[136:137], 0, s[28:29]
	s_mov_b32 s28, 0x50000
	v_add_co_u32_e32 v30, vcc, s28, v136
	s_mov_b64 s[28:29], 0x58000
	s_nop 0
	v_addc_co_u32_e32 v31, vcc, 0, v137, vcc
	global_store_dwordx4 v[30:31], v[26:29], off
	v_cvt_pk_bf16_f32 v18, v18, v19
	v_cvt_pk_bf16_f32 v19, v20, v21
	v_cvt_pk_bf16_f32 v20, v10, v11
	v_cvt_pk_bf16_f32 v21, v12, v13
	global_store_dwordx4 v[34:35], v[18:21], off offset:256
	v_cvt_pk_bf16_f32 v10, v22, v23
	v_cvt_pk_bf16_f32 v11, v24, v25
	v_cvt_pk_bf16_f32 v12, v14, v15
	v_cvt_pk_bf16_f32 v13, v16, v17
	s_nop 1
	v_lshl_add_u64 v[18:19], v[136:137], 0, s[28:29]
	s_mov_b32 s28, 0x58000
	v_add_co_u32_e32 v14, vcc, s28, v136
	s_mov_b64 s[28:29], s[4:5]
	s_nop 0
	v_addc_co_u32_e32 v15, vcc, 0, v137, vcc
	s_and_b64 vcc, exec, s[40:41]
	global_store_dwordx4 v[14:15], v[10:13], off
	v_cvt_pk_bf16_f32 v6, v6, v7
	v_cvt_pk_bf16_f32 v7, v8, v9
	v_cvt_pk_bf16_f32 v8, v2, v3
	v_cvt_pk_bf16_f32 v9, v4, v5
	global_store_dwordx4 v[18:19], v[6:9], off offset:256
	s_cbranch_vccz .LBB0_229
	s_waitcnt vmcnt(0)
	v_readlane_b32 s46, v247, 49
	v_readlane_b32 s50, v246, 29
	v_readlane_b32 s56, v246, 31
	v_readlane_b32 s58, v246, 33
	v_readlane_b32 s60, v246, 35
	s_cmpk_gt_u32 s2, 0xff
	s_mov_b32 s52, 0x800000
	s_movk_i32 s53, 0x1000
	s_movk_i32 s23, 0x2000
	s_movk_i32 s30, 0x2840
	s_movk_i32 s42, 0x3000
	s_mov_b64 s[44:45], 0x1800
	v_readlane_b32 s47, v247, 50
	v_readlane_b32 s43, v247, 51
	v_readlane_b32 s51, v246, 30
	v_readlane_b32 s57, v246, 32
	v_readlane_b32 s59, v246, 34
	v_readlane_b32 s61, v246, 36
	s_cbranch_scc1 .LBB0_240
	s_barrier

; #define PG8_STAGE(bufoff, gbase, voff) do { _Pragma("unroll") for (int _i = 0; _i < 2; ++_i) \
;         __builtin_amdgcn_global_load_lds((const unsigned*)((const char*)(gbase) + (voff)[_i]), (LAS unsigned*)(lds + (bufoff) + ldsw + _i * 8192), 16, 0, 0); } while (0)
; #define PG8_LDA(dst, b, h) do { _Pragma("unroll") for (int m = 0; m < 4; ++m) _Pragma("unroll") for (int k = 0; k < 2; ++k) dst[m][k] = *(const LAS bf16x8*)(lds + PG8_SA(b, h) + aoff + m * 2048 + k * 1024); } while (0)
; #define PG8_LDB(dst, b, h) do { _Pragma("unroll") for (int n = 0; n < 2; ++n) _Pragma("unroll") for (int k = 0; k < 2; ++k) dst[n][k] = *(const LAS bf16x8*)(lds + PG8_SB(b, h) + boff + n * 2048 + k * 1024); } while (0)
; #define PG8_MMA(ai, bj, At, Bt) do { __builtin_amdgcn_s_setprio(1); _Pragma("unroll") for (int m = 0; m < 4; ++m) _Pragma("unroll") for (int n = 0; n < 2; ++n) _Pragma("unroll") for (int k = 0; k < 2; ++k) \
;         acc[ai][bj][m][n] = __builtin_amdgcn_mfma_f32_16x16x32_bf16(Bt[n][k], At[m][k], acc[ai][bj][m][n], 0, 0, 0); __builtin_amdgcn_s_setprio(0); } while (0)
; #define PG8_WAIT_L(n) asm volatile("s_waitcnt lgkmcnt(" #n ")" ::: "memory")
; #define PG8_BAR __builtin_amdgcn_s_barrier()
; #define PG8_SCHED __builtin_amdgcn_sched_barrier(0)
; template <int MODE, class EpiT, class Sched>
; __device__ __forceinline__ void gemm_phase(LAS unsigned char* lds, const Gemm g, const Sched& S, const EpiT& E) {
;     ...
;         for (int t = 0; t < nt; t += 2) {
;             const bool last = (t == nt - 2);
;             const char* a1 = cA + (size_t)(t + 1) * kstep;
;             const char* a2 = last ? nA : cA + (size_t)(t + 2) * kstep; const char* b2 = last ? nB : cB + (size_t)(t + 2) * kstep;
;             const char* a3 = a2 + kstep; const char* b3 = b2 + kstep;
;             PG8_LDB(B0, 0, 0); PG8_SCHED; PG8_LDA(At, 0, 0); PG8_STAGE(PG8_SA(1, 1), a1 + hstep, voffA);
;             PG8_WAIT_L(8); PG8_BAR; PG8_WAIT_L(0); PG8_MMA(0, 0, At, B0); PG8_BAR; PG8_SCHED;
;             PG8_LDB(B1, 0, 1); PG8_STAGE(PG8_SB(0, 0), b2, voffB);
;             PG8_BAR; PG8_WAIT_L(0); PG8_MMA(0, 1, At, B1); PG8_BAR;
;             PG8_LDA(At, 0, 1); PG8_STAGE(PG8_SA(0, 0), a2, voffA);
;             PG8_BAR; PG8_WAIT_L(0); PG8_MMA(1, 0, At, B0); PG8_BAR; PG8_SCHED;
.LBB0_280:
	s_add_i32 s68, s46, 2
	s_add_u32 s52, s10, s44
	s_addc_u32 s47, s11, s45
	s_add_u32 s58, s4, s44
	s_addc_u32 s53, s5, s45
	s_add_i32 s59, 0, 0x10000
	v_add_u32_e32 v152, s59, v157
	ds_read_b128 v[134:137], v152
	ds_read_b128 v[138:141], v152 offset:1024
	ds_read_b128 v[142:145], v152 offset:2048
	ds_read_b128 v[152:155], v152 offset:3072
	s_cmp_eq_u32 s60, s46
	s_cselect_b32 s46, s34, s52
	s_cselect_b32 s47, s35, s47
	s_cselect_b32 s53, s39, s53
	s_cselect_b32 s52, s38, s58
	v_lshl_add_u64 v[198:199], s[10:11], 0, v[132:133]
	s_add_i32 m0, s30, 0xc000
	ds_read_b128 v[162:165], v160
	ds_read_b128 v[166:169], v160 offset:1024
	ds_read_b128 v[170:173], v160 offset:2048
	ds_read_b128 v[174:177], v160 offset:3072
	ds_read_b128 v[182:185], v160 offset:4096
	ds_read_b128 v[186:189], v160 offset:5120
	ds_read_b128 v[190:193], v160 offset:6144
	ds_read_b128 v[194:197], v160 offset:7168
	global_load_lds_dwordx4 v[198:199], off
	v_lshl_add_u64 v[198:199], s[10:11], 0, v[130:131]
	s_add_i32 m0, s30, 0xe000
	s_nop 0
	global_load_lds_dwordx4 v[198:199], off
	s_waitcnt lgkmcnt(8)
	s_barrier
	s_waitcnt lgkmcnt(0)
	s_waitcnt lgkmcnt(0)
	v_mfma_f32_16x16x32_bf16 v[126:129], v[134:137], v[162:165], v[126:129]
	v_mfma_f32_16x16x32_bf16 v[122:125], v[142:145], v[162:165], v[122:125]
	v_mfma_f32_16x16x32_bf16 v[118:121], v[134:137], v[170:173], v[118:121]
	v_mfma_f32_16x16x32_bf16 v[114:117], v[142:145], v[170:173], v[114:117]
	v_mfma_f32_16x16x32_bf16 v[110:113], v[134:137], v[182:185], v[110:113]
	v_mfma_f32_16x16x32_bf16 v[106:109], v[142:145], v[182:185], v[106:109]
	v_mfma_f32_16x16x32_bf16 v[102:105], v[134:137], v[190:193], v[102:105]
	v_mfma_f32_16x16x32_bf16 v[98:101], v[142:145], v[190:193], v[98:101]
	v_mfma_f32_16x16x32_bf16 v[126:129], v[138:141], v[166:169], v[126:129]
	v_mfma_f32_16x16x32_bf16 v[122:125], v[152:155], v[166:169], v[122:125]
	v_mfma_f32_16x16x32_bf16 v[118:121], v[138:141], v[174:177], v[118:121]
	v_mfma_f32_16x16x32_bf16 v[114:117], v[152:155], v[174:177], v[114:117]
	v_mfma_f32_16x16x32_bf16 v[110:113], v[138:141], v[186:189], v[110:113]
	v_mfma_f32_16x16x32_bf16 v[106:109], v[152:155], v[186:189], v[106:109]
	v_mfma_f32_16x16x32_bf16 v[102:105], v[138:141], v[194:197], v[102:105]
	v_mfma_f32_16x16x32_bf16 v[98:101], v[152:155], v[194:197], v[98:101]
	s_barrier
	s_add_i32 s58, 0, 0x14000
	s_add_i32 s59, s59, s24
	v_add_u32_e32 v161, s58, v157
	v_lshl_add_u64 v[198:199], s[52:53], 0, v[0:1]
	s_mov_b32 m0, s59
	ds_read_b128 v[220:223], v161
	ds_read_b128 v[224:227], v161 offset:1024
	ds_read_b128 v[228:231], v161 offset:2048
	ds_read_b128 v[232:235], v161 offset:3072
	global_load_lds_dwordx4 v[198:199], off
	v_lshl_add_u64 v[236:237], s[52:53], 0, v[146:147]
	s_add_i32 m0, s59, 0x2000
	s_nop 0
	global_load_lds_dwordx4 v[236:237], off
	s_barrier
	s_waitcnt lgkmcnt(0)
	s_waitcnt lgkmcnt(0)
	v_mfma_f32_16x16x32_bf16 v[94:97], v[220:223], v[162:165], v[94:97]
	v_mfma_f32_16x16x32_bf16 v[90:93], v[228:231], v[162:165], v[90:93]
	v_mfma_f32_16x16x32_bf16 v[86:89], v[220:223], v[170:173], v[86:89]
	v_mfma_f32_16x16x32_bf16 v[82:85], v[228:231], v[170:173], v[82:85]
	v_mfma_f32_16x16x32_bf16 v[78:81], v[220:223], v[182:185], v[78:81]
	v_mfma_f32_16x16x32_bf16 v[74:77], v[228:231], v[182:185], v[74:77]
	v_mfma_f32_16x16x32_bf16 v[70:73], v[220:223], v[190:193], v[70:73]
	v_mfma_f32_16x16x32_bf16 v[66:69], v[228:231], v[190:193], v[66:69]
	v_mfma_f32_16x16x32_bf16 v[94:97], v[224:227], v[166:169], v[94:97]
	v_mfma_f32_16x16x32_bf16 v[90:93], v[232:235], v[166:169], v[90:93]
	v_mfma_f32_16x16x32_bf16 v[86:89], v[224:227], v[174:177], v[86:89]
	v_mfma_f32_16x16x32_bf16 v[82:85], v[232:235], v[174:177], v[82:85]
	v_mfma_f32_16x16x32_bf16 v[78:81], v[224:227], v[186:189], v[78:81]
	v_mfma_f32_16x16x32_bf16 v[74:77], v[232:235], v[186:189], v[74:77]
	v_mfma_f32_16x16x32_bf16 v[70:73], v[224:227], v[194:197], v[70:73]
	v_mfma_f32_16x16x32_bf16 v[66:69], v[232:235], v[194:197], v[66:69]
	s_mov_b32 m0, s30
	v_lshl_add_u64 v[238:239], s[46:47], 0, v[0:1]
	s_barrier
	ds_read_b128 v[162:165], v160 offset:16384
	ds_read_b128 v[166:169], v160 offset:17408
	ds_read_b128 v[170:173], v160 offset:18432
	ds_read_b128 v[174:177], v160 offset:19456
	ds_read_b128 v[182:185], v160 offset:20480
	ds_read_b128 v[186:189], v160 offset:21504
	ds_read_b128 v[190:193], v160 offset:22528
	ds_read_b128 v[194:197], v160 offset:23552
	global_load_lds_dwordx4 v[238:239], off
	v_lshl_add_u64 v[240:241], s[46:47], 0, v[146:147]
	s_mov_b32 m0, s50
	s_nop 0
	global_load_lds_dwordx4 v[240:241], off
	s_barrier
	s_waitcnt lgkmcnt(0)
	s_waitcnt lgkmcnt(0)
	v_mfma_f32_16x16x32_bf16 v[62:65], v[134:137], v[162:165], v[62:65]
	v_mfma_f32_16x16x32_bf16 v[58:61], v[142:145], v[162:165], v[58:61]
	v_mfma_f32_16x16x32_bf16 v[54:57], v[134:137], v[170:173], v[54:57]
	v_mfma_f32_16x16x32_bf16 v[50:53], v[142:145], v[170:173], v[50:53]
	v_mfma_f32_16x16x32_bf16 v[46:49], v[134:137], v[182:185], v[46:49]
	v_mfma_f32_16x16x32_bf16 v[42:45], v[142:145], v[182:185], v[42:45]
	v_mfma_f32_16x16x32_bf16 v[38:41], v[134:137], v[190:193], v[38:41]
	v_mfma_f32_16x16x32_bf16 v[34:37], v[142:145], v[190:193], v[34:37]
	v_mfma_f32_16x16x32_bf16 v[62:65], v[138:141], v[166:169], v[62:65]
	v_mfma_f32_16x16x32_bf16 v[58:61], v[152:155], v[166:169], v[58:61]
	v_mfma_f32_16x16x32_bf16 v[54:57], v[138:141], v[174:177], v[54:57]
	v_mfma_f32_16x16x32_bf16 v[50:53], v[152:155], v[174:177], v[50:53]
	v_mfma_f32_16x16x32_bf16 v[46:49], v[138:141], v[186:189], v[46:49]
	v_mfma_f32_16x16x32_bf16 v[42:45], v[152:155], v[186:189], v[42:45]
	v_mfma_f32_16x16x32_bf16 v[38:41], v[138:141], v[194:197], v[38:41]
	v_mfma_f32_16x16x32_bf16 v[34:37], v[152:155], v[194:197], v[34:37]
	s_barrier
; #define PG8_STAGE(bufoff, gbase, voff) do { _Pragma("unroll") for (int _i = 0; _i < 2; ++_i) \
;         __builtin_amdgcn_global_load_lds((const unsigned*)((const char*)(gbase) + (voff)[_i]), (LAS unsigned*)(lds + (bufoff) + ldsw + _i * 8192), 16, 0, 0); } while (0)
; #define PG8_LDA(dst, b, h) do { _Pragma("unroll") for (int m = 0; m < 4; ++m) _Pragma("unroll") for (int k = 0; k < 2; ++k) dst[m][k] = *(const LAS bf16x8*)(lds + PG8_SA(b, h) + aoff + m * 2048 + k * 1024); } while (0)
; #define PG8_LDB(dst, b, h) do { _Pragma("unroll") for (int n = 0; n < 2; ++n) _Pragma("unroll") for (int k = 0; k < 2; ++k) dst[n][k] = *(const LAS bf16x8*)(lds + PG8_SB(b, h) + boff + n * 2048 + k * 1024); } while (0)
; #define PG8_MMA(ai, bj, At, Bt) do { __builtin_amdgcn_s_setprio(1); _Pragma("unroll") for (int m = 0; m < 4; ++m) _Pragma("unroll") for (int n = 0; n < 2; ++n) _Pragma("unroll") for (int k = 0; k < 2; ++k) \
;         acc[ai][bj][m][n] = __builtin_amdgcn_mfma_f32_16x16x32_bf16(Bt[n][k], At[m][k], acc[ai][bj][m][n], 0, 0, 0); __builtin_amdgcn_s_setprio(0); } while (0)
; #define PG8_WAIT_V(n) asm volatile("s_waitcnt vmcnt(" #n ")" ::: "memory")
; #define PG8_WAIT_L(n) asm volatile("s_waitcnt lgkmcnt(" #n ")" ::: "memory")
; #define PG8_BAR __builtin_amdgcn_s_barrier()
; #define PG8_SCHED __builtin_amdgcn_sched_barrier(0)
; template <int MODE, class EpiT, class Sched>
; __device__ __forceinline__ void gemm_phase(LAS unsigned char* lds, const Gemm g, const Sched& S, const EpiT& E) {
;     ...
;             PG8_STAGE(PG8_SB(0, 1), b2 + hstep, voffB);
;             PG8_WAIT_V(6); PG8_BAR; PG8_MMA(1, 1, At, B1); PG8_BAR;
;             PG8_LDB(B0, 1, 0); PG8_SCHED; PG8_LDA(At, 1, 0); PG8_STAGE(PG8_SA(0, 1), a2 + hstep, voffA);
;             PG8_WAIT_L(8); PG8_BAR; PG8_WAIT_L(0); PG8_MMA(0, 0, At, B0); PG8_BAR; PG8_SCHED;
;             PG8_LDB(B1, 1, 1); PG8_STAGE(PG8_SB(1, 0), b3, voffB);
;             PG8_BAR; PG8_WAIT_L(0); PG8_MMA(0, 1, At, B1); PG8_BAR;
	s_add_u32 s52, s52, s22
	s_addc_u32 s53, s53, 0
	s_add_i32 s58, s58, s24
	v_lshl_add_u64 v[242:243], s[52:53], 0, v[0:1]
	s_mov_b32 m0, s58
	v_lshl_add_u64 v[244:245], s[52:53], 0, v[146:147]
	global_load_lds_dwordx4 v[242:243], off
	s_add_i32 m0, s58, 0x2000
	s_nop 0
	global_load_lds_dwordx4 v[244:245], off
	s_waitcnt vmcnt(6)
	s_barrier
	v_mfma_f32_16x16x32_bf16 v[30:33], v[220:223], v[162:165], v[30:33]
	v_mfma_f32_16x16x32_bf16 v[26:29], v[228:231], v[162:165], v[26:29]
	v_mfma_f32_16x16x32_bf16 v[22:25], v[220:223], v[170:173], v[22:25]
	v_mfma_f32_16x16x32_bf16 v[18:21], v[228:231], v[170:173], v[18:21]
	v_mfma_f32_16x16x32_bf16 v[14:17], v[220:223], v[182:185], v[14:17]
	v_mfma_f32_16x16x32_bf16 v[10:13], v[228:231], v[182:185], v[10:13]
	v_mfma_f32_16x16x32_bf16 v[6:9], v[220:223], v[190:193], v[6:9]
	v_mfma_f32_16x16x32_bf16 v[2:5], v[228:231], v[190:193], v[2:5]
	v_mfma_f32_16x16x32_bf16 v[30:33], v[224:227], v[166:169], v[30:33]
	v_mfma_f32_16x16x32_bf16 v[26:29], v[232:235], v[166:169], v[26:29]
	v_mfma_f32_16x16x32_bf16 v[22:25], v[224:227], v[174:177], v[22:25]
	v_mfma_f32_16x16x32_bf16 v[18:21], v[232:235], v[174:177], v[18:21]
	v_mfma_f32_16x16x32_bf16 v[14:17], v[224:227], v[186:189], v[14:17]
	v_mfma_f32_16x16x32_bf16 v[10:13], v[232:235], v[186:189], v[10:13]
	v_mfma_f32_16x16x32_bf16 v[6:9], v[224:227], v[194:197], v[6:9]
	v_mfma_f32_16x16x32_bf16 v[2:5], v[232:235], v[194:197], v[2:5]
	s_add_i32 s52, 0, 0x18000
	v_add_u32_e32 v152, s52, v157
	s_barrier
	ds_read_b128 v[134:137], v152
	ds_read_b128 v[138:141], v152 offset:1024
	ds_read_b128 v[142:145], v152 offset:2048
	ds_read_b128 v[152:155], v152 offset:3072
	s_add_u32 s46, s46, s22
	s_addc_u32 s47, s47, 0
	s_mov_b32 m0, s51
	v_lshl_add_u64 v[220:221], s[46:47], 0, v[0:1]
	ds_read_b128 v[162:165], v160 offset:32768
	ds_read_b128 v[166:169], v160 offset:33792
	ds_read_b128 v[170:173], v160 offset:34816
	ds_read_b128 v[174:177], v160 offset:35840
	ds_read_b128 v[182:185], v160 offset:36864
	ds_read_b128 v[186:189], v160 offset:37888
	ds_read_b128 v[190:193], v160 offset:38912
	ds_read_b128 v[194:197], v160 offset:39936
	global_load_lds_dwordx4 v[220:221], off
	v_lshl_add_u64 v[220:221], s[46:47], 0, v[146:147]
	s_mov_b32 m0, s54
	s_nop 0
	global_load_lds_dwordx4 v[220:221], off
	s_waitcnt lgkmcnt(8)
	s_barrier
	s_waitcnt lgkmcnt(0)
	s_waitcnt lgkmcnt(0)
	v_mfma_f32_16x16x32_bf16 v[126:129], v[134:137], v[162:165], v[126:129]
	v_mfma_f32_16x16x32_bf16 v[122:125], v[142:145], v[162:165], v[122:125]
	v_mfma_f32_16x16x32_bf16 v[118:121], v[134:137], v[170:173], v[118:121]
	v_mfma_f32_16x16x32_bf16 v[114:117], v[142:145], v[170:173], v[114:117]
	v_mfma_f32_16x16x32_bf16 v[110:113], v[134:137], v[182:185], v[110:113]
	v_mfma_f32_16x16x32_bf16 v[106:109], v[142:145], v[182:185], v[106:109]
	v_mfma_f32_16x16x32_bf16 v[102:105], v[134:137], v[190:193], v[102:105]
	v_mfma_f32_16x16x32_bf16 v[98:101], v[142:145], v[190:193], v[98:101]
	v_mfma_f32_16x16x32_bf16 v[126:129], v[138:141], v[166:169], v[126:129]
	v_mfma_f32_16x16x32_bf16 v[122:125], v[152:155], v[166:169], v[122:125]
	v_mfma_f32_16x16x32_bf16 v[118:121], v[138:141], v[174:177], v[118:121]
	v_mfma_f32_16x16x32_bf16 v[114:117], v[152:155], v[174:177], v[114:117]
	v_mfma_f32_16x16x32_bf16 v[110:113], v[138:141], v[186:189], v[110:113]
	v_mfma_f32_16x16x32_bf16 v[106:109], v[152:155], v[186:189], v[106:109]
	v_mfma_f32_16x16x32_bf16 v[102:105], v[138:141], v[194:197], v[102:105]
	v_mfma_f32_16x16x32_bf16 v[98:101], v[152:155], v[194:197], v[98:101]
	s_barrier
	s_add_i32 s46, 0, 0x1c000
	s_add_i32 s47, s52, s24
	v_add_u32_e32 v161, s46, v157
	v_lshl_add_u64 v[198:199], v[198:199], 0, s[76:77]
	s_mov_b32 m0, s47
	ds_read_b128 v[220:223], v161
	ds_read_b128 v[224:227], v161 offset:1024
	ds_read_b128 v[228:231], v161 offset:2048
	ds_read_b128 v[232:235], v161 offset:3072
	global_load_lds_dwordx4 v[198:199], off
	v_lshl_add_u64 v[198:199], v[236:237], 0, s[76:77]
	s_add_i32 m0, s47, 0x2000
	s_nop 0
	global_load_lds_dwordx4 v[198:199], off
	s_barrier
; #define PG8_STAGE(bufoff, gbase, voff) do { _Pragma("unroll") for (int _i = 0; _i < 2; ++_i) \
;         __builtin_amdgcn_global_load_lds((const unsigned*)((const char*)(gbase) + (voff)[_i]), (LAS unsigned*)(lds + (bufoff) + ldsw + _i * 8192), 16, 0, 0); } while (0)
; #define PG8_LDA(dst, b, h) do { _Pragma("unroll") for (int m = 0; m < 4; ++m) _Pragma("unroll") for (int k = 0; k < 2; ++k) dst[m][k] = *(const LAS bf16x8*)(lds + PG8_SA(b, h) + aoff + m * 2048 + k * 1024); } while (0)
; #define PG8_MMA(ai, bj, At, Bt) do { __builtin_amdgcn_s_setprio(1); _Pragma("unroll") for (int m = 0; m < 4; ++m) _Pragma("unroll") for (int n = 0; n < 2; ++n) _Pragma("unroll") for (int k = 0; k < 2; ++k) \
;         acc[ai][bj][m][n] = __builtin_amdgcn_mfma_f32_16x16x32_bf16(Bt[n][k], At[m][k], acc[ai][bj][m][n], 0, 0, 0); __builtin_amdgcn_s_setprio(0); } while (0)
; #define PG8_WAIT_V(n) asm volatile("s_waitcnt vmcnt(" #n ")" ::: "memory")
; #define PG8_WAIT_L(n) asm volatile("s_waitcnt lgkmcnt(" #n ")" ::: "memory")
; #define PG8_BAR __builtin_amdgcn_s_barrier()
; #define PG8_SCHED __builtin_amdgcn_sched_barrier(0)
;     template <int mode> __device__ __forceinline__ void run(const f32x4 (&acc)[2][2][4][2], const Unit& u, int wr, int wc, int fr, int fq, const LAS float* sc) const {
;     ...
;             const int col0 = u.pn * BM + wc * 32 + 8 * fq;
;             f32x4 bv[2][2];
; #pragma unroll
;             for (int bj = 0; bj < 2; ++bj)
; #pragma unroll
;                 for (int n = 0; n < 2; ++n) bv[bj][n] = bias ? *(const f32x4*)(bias + col0 + bj * HALF + 4 * n) : (f32x4){0.f, 0.f, 0.f, 0.f};
; template <int MODE, class EpiT, class Sched>
; __device__ __forceinline__ void gemm_phase(LAS unsigned char* lds, const Gemm g, const Sched& S, const EpiT& E) {
;     ...
;             PG8_BAR; PG8_WAIT_L(0); PG8_MMA(0, 1, At, B1); PG8_BAR;
;             PG8_LDA(At, 1, 1); PG8_STAGE(PG8_SA(1, 0), a3, voffA);
;             PG8_BAR; PG8_WAIT_L(0); PG8_MMA(1, 0, At, B0); PG8_BAR; PG8_SCHED;
;             PG8_STAGE(PG8_SB(1, 1), b3 + hstep, voffB);
;             PG8_WAIT_V(6); PG8_BAR; PG8_MMA(1, 1, At, B1); PG8_BAR;
	s_waitcnt lgkmcnt(0)
	s_waitcnt lgkmcnt(0)
	v_mfma_f32_16x16x32_bf16 v[94:97], v[220:223], v[162:165], v[94:97]
	v_mfma_f32_16x16x32_bf16 v[90:93], v[228:231], v[162:165], v[90:93]
	v_mfma_f32_16x16x32_bf16 v[86:89], v[220:223], v[170:173], v[86:89]
	v_mfma_f32_16x16x32_bf16 v[82:85], v[228:231], v[170:173], v[82:85]
	v_mfma_f32_16x16x32_bf16 v[78:81], v[220:223], v[182:185], v[78:81]
	v_mfma_f32_16x16x32_bf16 v[74:77], v[228:231], v[182:185], v[74:77]
	v_mfma_f32_16x16x32_bf16 v[70:73], v[220:223], v[190:193], v[70:73]
	v_mfma_f32_16x16x32_bf16 v[66:69], v[228:231], v[190:193], v[66:69]
	v_mfma_f32_16x16x32_bf16 v[94:97], v[224:227], v[166:169], v[94:97]
	v_mfma_f32_16x16x32_bf16 v[90:93], v[232:235], v[166:169], v[90:93]
	v_mfma_f32_16x16x32_bf16 v[86:89], v[224:227], v[174:177], v[86:89]
	v_mfma_f32_16x16x32_bf16 v[82:85], v[232:235], v[174:177], v[82:85]
	v_mfma_f32_16x16x32_bf16 v[78:81], v[224:227], v[186:189], v[78:81]
	v_mfma_f32_16x16x32_bf16 v[74:77], v[232:235], v[186:189], v[74:77]
	v_mfma_f32_16x16x32_bf16 v[70:73], v[224:227], v[194:197], v[70:73]
	v_mfma_f32_16x16x32_bf16 v[66:69], v[232:235], v[194:197], v[66:69]
	s_mov_b32 m0, s56
	v_lshl_add_u64 v[198:199], v[238:239], 0, s[76:77]
	s_barrier
	ds_read_b128 v[162:165], v160 offset:49152
	ds_read_b128 v[166:169], v160 offset:50176
	ds_read_b128 v[170:173], v160 offset:51200
	ds_read_b128 v[174:177], v160 offset:52224
	ds_read_b128 v[182:185], v160 offset:53248
	ds_read_b128 v[186:189], v160 offset:54272
	ds_read_b128 v[190:193], v160 offset:55296
	ds_read_b128 v[194:197], v160 offset:56320
	global_load_lds_dwordx4 v[198:199], off
	v_lshl_add_u64 v[198:199], v[240:241], 0, s[76:77]
	s_mov_b32 m0, s57
	s_nop 0
	global_load_lds_dwordx4 v[198:199], off
	s_barrier
	s_waitcnt lgkmcnt(0)
	s_waitcnt lgkmcnt(0)
	v_mfma_f32_16x16x32_bf16 v[62:65], v[134:137], v[162:165], v[62:65]
	v_mfma_f32_16x16x32_bf16 v[58:61], v[142:145], v[162:165], v[58:61]
	v_mfma_f32_16x16x32_bf16 v[54:57], v[134:137], v[170:173], v[54:57]
	v_mfma_f32_16x16x32_bf16 v[50:53], v[142:145], v[170:173], v[50:53]
	v_mfma_f32_16x16x32_bf16 v[46:49], v[134:137], v[182:185], v[46:49]
	v_mfma_f32_16x16x32_bf16 v[42:45], v[142:145], v[182:185], v[42:45]
	v_mfma_f32_16x16x32_bf16 v[38:41], v[134:137], v[190:193], v[38:41]
	v_mfma_f32_16x16x32_bf16 v[34:37], v[142:145], v[190:193], v[34:37]
	v_mfma_f32_16x16x32_bf16 v[62:65], v[138:141], v[166:169], v[62:65]
	v_mfma_f32_16x16x32_bf16 v[58:61], v[152:155], v[166:169], v[58:61]
	v_mfma_f32_16x16x32_bf16 v[54:57], v[138:141], v[174:177], v[54:57]
	v_mfma_f32_16x16x32_bf16 v[50:53], v[152:155], v[174:177], v[50:53]
	v_mfma_f32_16x16x32_bf16 v[46:49], v[138:141], v[186:189], v[46:49]
	v_mfma_f32_16x16x32_bf16 v[42:45], v[152:155], v[186:189], v[42:45]
	v_mfma_f32_16x16x32_bf16 v[38:41], v[138:141], v[194:197], v[38:41]
	v_mfma_f32_16x16x32_bf16 v[34:37], v[152:155], v[194:197], v[34:37]
	s_barrier
	s_add_i32 s46, s46, s24
	v_lshl_add_u64 v[134:135], v[242:243], 0, s[76:77]
	s_mov_b32 m0, s46
	s_nop 0
	global_load_lds_dwordx4 v[134:135], off
	v_lshl_add_u64 v[134:135], v[244:245], 0, s[76:77]
	s_add_i32 m0, s46, 0x2000
	s_nop 0
	global_load_lds_dwordx4 v[134:135], off
	s_waitcnt vmcnt(6)
	s_barrier
	v_mfma_f32_16x16x32_bf16 v[30:33], v[220:223], v[162:165], v[30:33]
	v_mfma_f32_16x16x32_bf16 v[26:29], v[228:231], v[162:165], v[26:29]
	v_mfma_f32_16x16x32_bf16 v[22:25], v[220:223], v[170:173], v[22:25]
	v_mfma_f32_16x16x32_bf16 v[18:21], v[228:231], v[170:173], v[18:21]
	v_mfma_f32_16x16x32_bf16 v[14:17], v[220:223], v[182:185], v[14:17]
	v_mfma_f32_16x16x32_bf16 v[10:13], v[228:231], v[182:185], v[10:13]
	v_mfma_f32_16x16x32_bf16 v[6:9], v[220:223], v[190:193], v[6:9]
	v_mfma_f32_16x16x32_bf16 v[2:5], v[228:231], v[190:193], v[2:5]
	v_mfma_f32_16x16x32_bf16 v[30:33], v[224:227], v[166:169], v[30:33]
	v_mfma_f32_16x16x32_bf16 v[26:29], v[232:235], v[166:169], v[26:29]
	v_mfma_f32_16x16x32_bf16 v[22:25], v[224:227], v[174:177], v[22:25]
	v_mfma_f32_16x16x32_bf16 v[18:21], v[232:235], v[174:177], v[18:21]
	v_mfma_f32_16x16x32_bf16 v[14:17], v[224:227], v[186:189], v[14:17]
	v_mfma_f32_16x16x32_bf16 v[10:13], v[232:235], v[186:189], v[10:13]
	v_mfma_f32_16x16x32_bf16 v[6:9], v[224:227], v[194:197], v[6:9]
	v_mfma_f32_16x16x32_bf16 v[2:5], v[232:235], v[194:197], v[2:5]
	s_add_u32 s44, s44, 0x100
	s_addc_u32 s45, s45, 0
	v_lshl_add_u64 v[132:133], v[132:133], 0, s[80:81]
	v_lshl_add_u64 v[130:131], v[130:131], 0, s[80:81]
	s_cmp_ge_u32 s68, s55
	s_mov_b32 s46, s68
	s_barrier
	s_cbranch_scc0 .LBB0_280
	v_lshl_or_b32 v152, s3, 8, v159
	v_ashrrev_i32_e32 v153, 31, v152
	v_cndmask_b32_e64 v131, 0, 1, s[28:29]
	v_lshl_add_u64 v[154:155], v[152:153], 2, s[12:13]
	v_mov_b32_e32 v130, 0
	v_cmp_ne_u32_e64 s[44:45], 1, v131
	s_andn2_b64 vcc, exec, s[28:29]
	v_mov_b32_e32 v134, 0
	v_mov_b32_e32 v135, 0
	v_mov_b32_e32 v136, 0
	v_mov_b32_e32 v137, 0
	s_cbranch_vccnz .LBB0_283
	global_load_dwordx4 v[134:137], v[154:155], off

; #define PG8_STAGE(bufoff, gbase, voff) do { _Pragma("unroll") for (int _i = 0; _i < 2; ++_i) \
;         __builtin_amdgcn_global_load_lds((const unsigned*)((const char*)(gbase) + (voff)[_i]), (LAS unsigned*)(lds + (bufoff) + ldsw + _i * 8192), 16, 0, 0); } while (0)
; #define PG8_LDA(dst, b, h) do { _Pragma("unroll") for (int m = 0; m < 4; ++m) _Pragma("unroll") for (int k = 0; k < 2; ++k) dst[m][k] = *(const LAS bf16x8*)(lds + PG8_SA(b, h) + aoff + m * 2048 + k * 1024); } while (0)
; #define PG8_LDB(dst, b, h) do { _Pragma("unroll") for (int n = 0; n < 2; ++n) _Pragma("unroll") for (int k = 0; k < 2; ++k) dst[n][k] = *(const LAS bf16x8*)(lds + PG8_SB(b, h) + boff + n * 2048 + k * 1024); } while (0)
; #define PG8_MMA(ai, bj, At, Bt) do { __builtin_amdgcn_s_setprio(1); _Pragma("unroll") for (int m = 0; m < 4; ++m) _Pragma("unroll") for (int n = 0; n < 2; ++n) _Pragma("unroll") for (int k = 0; k < 2; ++k) \
;         acc[ai][bj][m][n] = __builtin_amdgcn_mfma_f32_16x16x32_bf16(Bt[n][k], At[m][k], acc[ai][bj][m][n], 0, 0, 0); __builtin_amdgcn_s_setprio(0); } while (0)
; #define PG8_WAIT_L(n) asm volatile("s_waitcnt lgkmcnt(" #n ")" ::: "memory")
; #define PG8_BAR __builtin_amdgcn_s_barrier()
; template <int MODE, class EpiT, class Sched>
; __device__ __forceinline__ void gemm_phase(LAS unsigned char* lds, const Gemm g, const Sched& S, const EpiT& E) {
;     ...
;         const char* nA = has_next ? (const char*)g.A + (size_t)nxt.pm * tstep : cA; const char* nB = has_next ? (const char*)g.Bt + (size_t)nxt.pn * tstep : cB;
;         for (int t = 0; t < nt; t += 2) {
;             const bool last = (t == nt - 2);
;             const char* a1 = cA + (size_t)(t + 1) * kstep;
;             const char* a2 = last ? nA : cA + (size_t)(t + 2) * kstep; const char* b2 = last ? nB : cB + (size_t)(t + 2) * kstep;
;             const char* a3 = a2 + kstep; const char* b3 = b2 + kstep;
;             PG8_LDB(B0, 0, 0); PG8_SCHED; PG8_LDA(At, 0, 0); PG8_STAGE(PG8_SA(1, 1), a1 + hstep, voffA);
;             PG8_WAIT_L(8); PG8_BAR; PG8_WAIT_L(0); PG8_MMA(0, 0, At, B0); PG8_BAR; PG8_SCHED;
;             PG8_LDB(B1, 0, 1); PG8_STAGE(PG8_SB(0, 0), b2, voffB);
;             PG8_BAR; PG8_WAIT_L(0); PG8_MMA(0, 1, At, B1); PG8_BAR;
;             PG8_LDA(At, 0, 1); PG8_STAGE(PG8_SA(0, 0), a2, voffA);
;             PG8_BAR; PG8_WAIT_L(0); PG8_MMA(1, 0, At, B0); PG8_BAR; PG8_SCHED;
.LBB0_332:
	s_add_i32 s23, s22, 2
	s_add_u32 s30, s12, s4
	s_addc_u32 s38, s13, s5
	s_add_u32 s44, s10, s4
	s_addc_u32 s45, s11, s5
	s_add_i32 s58, 0, 0x10000
	v_add_u32_e32 v145, s58, v141
	ds_read_b128 v[146:149], v145
	ds_read_b128 v[150:153], v145 offset:1024
	ds_read_b128 v[154:157], v145 offset:2048
	ds_read_b128 v[158:161], v145 offset:3072
	s_cmp_eq_u32 s55, s22
	s_cselect_b32 s39, s29, s38
	s_cselect_b32 s38, s28, s30
	s_cselect_b32 s45, s35, s45
	s_cselect_b32 s44, s34, s44
	v_lshl_add_u64 v[198:199], s[12:13], 0, v[138:139]
	s_add_i32 m0, s47, 0xc000
	ds_read_b128 v[162:165], v144
	ds_read_b128 v[166:169], v144 offset:1024
	ds_read_b128 v[170:173], v144 offset:2048
	ds_read_b128 v[174:177], v144 offset:3072
	ds_read_b128 v[182:185], v144 offset:4096
	ds_read_b128 v[186:189], v144 offset:5120
	ds_read_b128 v[190:193], v144 offset:6144
	ds_read_b128 v[194:197], v144 offset:7168
	global_load_lds_dwordx4 v[198:199], off
	v_lshl_add_u64 v[198:199], s[12:13], 0, v[136:137]
	s_add_i32 m0, s47, 0xe000
	s_nop 0
	global_load_lds_dwordx4 v[198:199], off
	s_waitcnt lgkmcnt(8)
	s_barrier
	s_waitcnt lgkmcnt(0)
	s_waitcnt lgkmcnt(0)
	v_mfma_f32_16x16x32_bf16 v[126:129], v[146:149], v[162:165], v[126:129]
	v_mfma_f32_16x16x32_bf16 v[122:125], v[154:157], v[162:165], v[122:125]
	v_mfma_f32_16x16x32_bf16 v[118:121], v[146:149], v[170:173], v[118:121]
	v_mfma_f32_16x16x32_bf16 v[114:117], v[154:157], v[170:173], v[114:117]
	v_mfma_f32_16x16x32_bf16 v[110:113], v[146:149], v[182:185], v[110:113]
	v_mfma_f32_16x16x32_bf16 v[106:109], v[154:157], v[182:185], v[106:109]
	v_mfma_f32_16x16x32_bf16 v[102:105], v[146:149], v[190:193], v[102:105]
	v_mfma_f32_16x16x32_bf16 v[98:101], v[154:157], v[190:193], v[98:101]
	v_mfma_f32_16x16x32_bf16 v[126:129], v[150:153], v[166:169], v[126:129]
	v_mfma_f32_16x16x32_bf16 v[122:125], v[158:161], v[166:169], v[122:125]
	v_mfma_f32_16x16x32_bf16 v[118:121], v[150:153], v[174:177], v[118:121]
	v_mfma_f32_16x16x32_bf16 v[114:117], v[158:161], v[174:177], v[114:117]
	v_mfma_f32_16x16x32_bf16 v[110:113], v[150:153], v[186:189], v[110:113]
	v_mfma_f32_16x16x32_bf16 v[106:109], v[158:161], v[186:189], v[106:109]
	v_mfma_f32_16x16x32_bf16 v[102:105], v[150:153], v[194:197], v[102:105]
	v_mfma_f32_16x16x32_bf16 v[98:101], v[158:161], v[194:197], v[98:101]
	s_barrier
	s_add_i32 s22, 0, 0x14000
	s_add_i32 s30, s58, s46
	v_add_u32_e32 v145, s22, v141
	v_lshl_add_u64 v[198:199], s[44:45], 0, v[0:1]
	s_mov_b32 m0, s30
	ds_read_b128 v[220:223], v145
	ds_read_b128 v[224:227], v145 offset:1024
	ds_read_b128 v[228:231], v145 offset:2048
	ds_read_b128 v[232:235], v145 offset:3072
	global_load_lds_dwordx4 v[198:199], off
	v_lshl_add_u64 v[236:237], s[44:45], 0, v[130:131]
	s_add_i32 m0, s30, 0x2000
	s_nop 0
	global_load_lds_dwordx4 v[236:237], off
	s_barrier
	s_waitcnt lgkmcnt(0)
	s_waitcnt lgkmcnt(0)
	v_mfma_f32_16x16x32_bf16 v[94:97], v[220:223], v[162:165], v[94:97]
	v_mfma_f32_16x16x32_bf16 v[90:93], v[228:231], v[162:165], v[90:93]
	v_mfma_f32_16x16x32_bf16 v[86:89], v[220:223], v[170:173], v[86:89]
	v_mfma_f32_16x16x32_bf16 v[82:85], v[228:231], v[170:173], v[82:85]
	v_mfma_f32_16x16x32_bf16 v[78:81], v[220:223], v[182:185], v[78:81]
	v_mfma_f32_16x16x32_bf16 v[74:77], v[228:231], v[182:185], v[74:77]
	v_mfma_f32_16x16x32_bf16 v[70:73], v[220:223], v[190:193], v[70:73]
	v_mfma_f32_16x16x32_bf16 v[66:69], v[228:231], v[190:193], v[66:69]
	v_mfma_f32_16x16x32_bf16 v[94:97], v[224:227], v[166:169], v[94:97]
	v_mfma_f32_16x16x32_bf16 v[90:93], v[232:235], v[166:169], v[90:93]
	v_mfma_f32_16x16x32_bf16 v[86:89], v[224:227], v[174:177], v[86:89]
	v_mfma_f32_16x16x32_bf16 v[82:85], v[232:235], v[174:177], v[82:85]
	v_mfma_f32_16x16x32_bf16 v[78:81], v[224:227], v[186:189], v[78:81]
	v_mfma_f32_16x16x32_bf16 v[74:77], v[232:235], v[186:189], v[74:77]
	v_mfma_f32_16x16x32_bf16 v[70:73], v[224:227], v[194:197], v[70:73]
	v_mfma_f32_16x16x32_bf16 v[66:69], v[232:235], v[194:197], v[66:69]
	s_mov_b32 m0, s47
	v_lshl_add_u64 v[238:239], s[38:39], 0, v[0:1]
	s_barrier
	ds_read_b128 v[162:165], v144 offset:16384
	ds_read_b128 v[166:169], v144 offset:17408
	ds_read_b128 v[170:173], v144 offset:18432
	ds_read_b128 v[174:177], v144 offset:19456
	ds_read_b128 v[182:185], v144 offset:20480
	ds_read_b128 v[186:189], v144 offset:21504
	ds_read_b128 v[190:193], v144 offset:22528
	ds_read_b128 v[194:197], v144 offset:23552
	global_load_lds_dwordx4 v[238:239], off
	v_lshl_add_u64 v[240:241], s[38:39], 0, v[130:131]
	s_mov_b32 m0, s50
	s_nop 0
	global_load_lds_dwordx4 v[240:241], off
	s_barrier
	s_waitcnt lgkmcnt(0)
	s_waitcnt lgkmcnt(0)
	v_mfma_f32_16x16x32_bf16 v[62:65], v[146:149], v[162:165], v[62:65]
	v_mfma_f32_16x16x32_bf16 v[58:61], v[154:157], v[162:165], v[58:61]
	v_mfma_f32_16x16x32_bf16 v[54:57], v[146:149], v[170:173], v[54:57]
	v_mfma_f32_16x16x32_bf16 v[50:53], v[154:157], v[170:173], v[50:53]
	v_mfma_f32_16x16x32_bf16 v[46:49], v[146:149], v[182:185], v[46:49]
	v_mfma_f32_16x16x32_bf16 v[42:45], v[154:157], v[182:185], v[42:45]
	v_mfma_f32_16x16x32_bf16 v[38:41], v[146:149], v[190:193], v[38:41]
	v_mfma_f32_16x16x32_bf16 v[34:37], v[154:157], v[190:193], v[34:37]
	v_mfma_f32_16x16x32_bf16 v[62:65], v[150:153], v[166:169], v[62:65]
	v_mfma_f32_16x16x32_bf16 v[58:61], v[158:161], v[166:169], v[58:61]
	v_mfma_f32_16x16x32_bf16 v[54:57], v[150:153], v[174:177], v[54:57]
	v_mfma_f32_16x16x32_bf16 v[50:53], v[158:161], v[174:177], v[50:53]
	v_mfma_f32_16x16x32_bf16 v[46:49], v[150:153], v[186:189], v[46:49]
	v_mfma_f32_16x16x32_bf16 v[42:45], v[158:161], v[186:189], v[42:45]
	v_mfma_f32_16x16x32_bf16 v[38:41], v[150:153], v[194:197], v[38:41]
	v_mfma_f32_16x16x32_bf16 v[34:37], v[158:161], v[194:197], v[34:37]
	s_barrier
; #define PG8_STAGE(bufoff, gbase, voff) do { _Pragma("unroll") for (int _i = 0; _i < 2; ++_i) \
;         __builtin_amdgcn_global_load_lds((const unsigned*)((const char*)(gbase) + (voff)[_i]), (LAS unsigned*)(lds + (bufoff) + ldsw + _i * 8192), 16, 0, 0); } while (0)
; #define PG8_LDA(dst, b, h) do { _Pragma("unroll") for (int m = 0; m < 4; ++m) _Pragma("unroll") for (int k = 0; k < 2; ++k) dst[m][k] = *(const LAS bf16x8*)(lds + PG8_SA(b, h) + aoff + m * 2048 + k * 1024); } while (0)
; #define PG8_LDB(dst, b, h) do { _Pragma("unroll") for (int n = 0; n < 2; ++n) _Pragma("unroll") for (int k = 0; k < 2; ++k) dst[n][k] = *(const LAS bf16x8*)(lds + PG8_SB(b, h) + boff + n * 2048 + k * 1024); } while (0)
; #define PG8_MMA(ai, bj, At, Bt) do { __builtin_amdgcn_s_setprio(1); _Pragma("unroll") for (int m = 0; m < 4; ++m) _Pragma("unroll") for (int n = 0; n < 2; ++n) _Pragma("unroll") for (int k = 0; k < 2; ++k) \
;         acc[ai][bj][m][n] = __builtin_amdgcn_mfma_f32_16x16x32_bf16(Bt[n][k], At[m][k], acc[ai][bj][m][n], 0, 0, 0); __builtin_amdgcn_s_setprio(0); } while (0)
; #define PG8_WAIT_V(n) asm volatile("s_waitcnt vmcnt(" #n ")" ::: "memory")
; #define PG8_WAIT_L(n) asm volatile("s_waitcnt lgkmcnt(" #n ")" ::: "memory")
; #define PG8_BAR __builtin_amdgcn_s_barrier()
; #define PG8_SCHED __builtin_amdgcn_sched_barrier(0)
; template <int MODE, class EpiT, class Sched>
; __device__ __forceinline__ void gemm_phase(LAS unsigned char* lds, const Gemm g, const Sched& S, const EpiT& E) {
;     ...
;             PG8_STAGE(PG8_SB(0, 1), b2 + hstep, voffB);
;             PG8_WAIT_V(6); PG8_BAR; PG8_MMA(1, 1, At, B1); PG8_BAR;
;             PG8_LDB(B0, 1, 0); PG8_SCHED; PG8_LDA(At, 1, 0); PG8_STAGE(PG8_SA(0, 1), a2 + hstep, voffA);
;             PG8_WAIT_L(8); PG8_BAR; PG8_WAIT_L(0); PG8_MMA(0, 0, At, B0); PG8_BAR; PG8_SCHED;
;             PG8_LDB(B1, 1, 1); PG8_STAGE(PG8_SB(1, 0), b3, voffB);
;             PG8_BAR; PG8_WAIT_L(0); PG8_MMA(0, 1, At, B1); PG8_BAR;
;             PG8_LDA(At, 1, 1); PG8_STAGE(PG8_SA(1, 0), a3, voffA);
;             PG8_BAR; PG8_WAIT_L(0); PG8_MMA(1, 0, At, B0); PG8_BAR; PG8_SCHED;
;             PG8_STAGE(PG8_SB(1, 1), b3 + hstep, voffB);
	s_add_u32 s44, s44, s21
	s_addc_u32 s45, s45, 0
	s_add_i32 s22, s22, s46
	v_lshl_add_u64 v[242:243], s[44:45], 0, v[0:1]
	s_mov_b32 m0, s22
	v_lshl_add_u64 v[244:245], s[44:45], 0, v[130:131]
	global_load_lds_dwordx4 v[242:243], off
	s_add_i32 m0, s22, 0x2000
	s_nop 0
	global_load_lds_dwordx4 v[244:245], off
	s_waitcnt vmcnt(6)
	s_barrier
	v_mfma_f32_16x16x32_bf16 v[30:33], v[220:223], v[162:165], v[30:33]
	v_mfma_f32_16x16x32_bf16 v[26:29], v[228:231], v[162:165], v[26:29]
	v_mfma_f32_16x16x32_bf16 v[22:25], v[220:223], v[170:173], v[22:25]
	v_mfma_f32_16x16x32_bf16 v[18:21], v[228:231], v[170:173], v[18:21]
	v_mfma_f32_16x16x32_bf16 v[14:17], v[220:223], v[182:185], v[14:17]
	v_mfma_f32_16x16x32_bf16 v[10:13], v[228:231], v[182:185], v[10:13]
	v_mfma_f32_16x16x32_bf16 v[6:9], v[220:223], v[190:193], v[6:9]
	v_mfma_f32_16x16x32_bf16 v[2:5], v[228:231], v[190:193], v[2:5]
	v_mfma_f32_16x16x32_bf16 v[30:33], v[224:227], v[166:169], v[30:33]
	v_mfma_f32_16x16x32_bf16 v[26:29], v[232:235], v[166:169], v[26:29]
	v_mfma_f32_16x16x32_bf16 v[22:25], v[224:227], v[174:177], v[22:25]
	v_mfma_f32_16x16x32_bf16 v[18:21], v[232:235], v[174:177], v[18:21]
	v_mfma_f32_16x16x32_bf16 v[14:17], v[224:227], v[186:189], v[14:17]
	v_mfma_f32_16x16x32_bf16 v[10:13], v[232:235], v[186:189], v[10:13]
	v_mfma_f32_16x16x32_bf16 v[6:9], v[224:227], v[194:197], v[6:9]
	v_mfma_f32_16x16x32_bf16 v[2:5], v[232:235], v[194:197], v[2:5]
	s_add_i32 s22, 0, 0x18000
	v_add_u32_e32 v145, s22, v141
	s_barrier
	ds_read_b128 v[146:149], v145
	ds_read_b128 v[150:153], v145 offset:1024
	ds_read_b128 v[154:157], v145 offset:2048
	ds_read_b128 v[158:161], v145 offset:3072
	s_add_u32 s38, s38, s21
	s_addc_u32 s39, s39, 0
	s_mov_b32 m0, s51
	v_lshl_add_u64 v[220:221], s[38:39], 0, v[0:1]
	ds_read_b128 v[162:165], v144 offset:32768
	ds_read_b128 v[166:169], v144 offset:33792
	ds_read_b128 v[170:173], v144 offset:34816
	ds_read_b128 v[174:177], v144 offset:35840
	ds_read_b128 v[182:185], v144 offset:36864
	ds_read_b128 v[186:189], v144 offset:37888
	ds_read_b128 v[190:193], v144 offset:38912
	ds_read_b128 v[194:197], v144 offset:39936
	global_load_lds_dwordx4 v[220:221], off
	v_lshl_add_u64 v[220:221], s[38:39], 0, v[130:131]
	s_mov_b32 m0, s52
	s_nop 0
	global_load_lds_dwordx4 v[220:221], off
	s_waitcnt lgkmcnt(8)
	s_barrier
	s_waitcnt lgkmcnt(0)
	s_waitcnt lgkmcnt(0)
	v_mfma_f32_16x16x32_bf16 v[126:129], v[146:149], v[162:165], v[126:129]
	v_mfma_f32_16x16x32_bf16 v[122:125], v[154:157], v[162:165], v[122:125]
	v_mfma_f32_16x16x32_bf16 v[118:121], v[146:149], v[170:173], v[118:121]
	v_mfma_f32_16x16x32_bf16 v[114:117], v[154:157], v[170:173], v[114:117]
	v_mfma_f32_16x16x32_bf16 v[110:113], v[146:149], v[182:185], v[110:113]
	v_mfma_f32_16x16x32_bf16 v[106:109], v[154:157], v[182:185], v[106:109]
	v_mfma_f32_16x16x32_bf16 v[102:105], v[146:149], v[190:193], v[102:105]
	v_mfma_f32_16x16x32_bf16 v[98:101], v[154:157], v[190:193], v[98:101]
	v_mfma_f32_16x16x32_bf16 v[126:129], v[150:153], v[166:169], v[126:129]
	v_mfma_f32_16x16x32_bf16 v[122:125], v[158:161], v[166:169], v[122:125]
	v_mfma_f32_16x16x32_bf16 v[118:121], v[150:153], v[174:177], v[118:121]
	v_mfma_f32_16x16x32_bf16 v[114:117], v[158:161], v[174:177], v[114:117]
	v_mfma_f32_16x16x32_bf16 v[110:113], v[150:153], v[186:189], v[110:113]
	v_mfma_f32_16x16x32_bf16 v[106:109], v[158:161], v[186:189], v[106:109]
	v_mfma_f32_16x16x32_bf16 v[102:105], v[150:153], v[194:197], v[102:105]
	v_mfma_f32_16x16x32_bf16 v[98:101], v[158:161], v[194:197], v[98:101]
	s_barrier
	s_add_i32 s30, 0, 0x1c000
	s_add_i32 s22, s22, s46
	v_add_u32_e32 v145, s30, v141
	v_lshl_add_u64 v[198:199], v[198:199], 0, s[76:77]
	s_mov_b32 m0, s22
	ds_read_b128 v[220:223], v145
	ds_read_b128 v[224:227], v145 offset:1024
	ds_read_b128 v[228:231], v145 offset:2048
	ds_read_b128 v[232:235], v145 offset:3072
	global_load_lds_dwordx4 v[198:199], off
	v_lshl_add_u64 v[198:199], v[236:237], 0, s[76:77]
	s_add_i32 m0, s22, 0x2000
	s_nop 0
	global_load_lds_dwordx4 v[198:199], off
	s_barrier
	s_waitcnt lgkmcnt(0)
	s_waitcnt lgkmcnt(0)
	v_mfma_f32_16x16x32_bf16 v[94:97], v[220:223], v[162:165], v[94:97]
	v_mfma_f32_16x16x32_bf16 v[90:93], v[228:231], v[162:165], v[90:93]
	v_mfma_f32_16x16x32_bf16 v[86:89], v[220:223], v[170:173], v[86:89]
	v_mfma_f32_16x16x32_bf16 v[82:85], v[228:231], v[170:173], v[82:85]
	v_mfma_f32_16x16x32_bf16 v[78:81], v[220:223], v[182:185], v[78:81]
	v_mfma_f32_16x16x32_bf16 v[74:77], v[228:231], v[182:185], v[74:77]
	v_mfma_f32_16x16x32_bf16 v[70:73], v[220:223], v[190:193], v[70:73]
	v_mfma_f32_16x16x32_bf16 v[66:69], v[228:231], v[190:193], v[66:69]
	v_mfma_f32_16x16x32_bf16 v[94:97], v[224:227], v[166:169], v[94:97]
	v_mfma_f32_16x16x32_bf16 v[90:93], v[232:235], v[166:169], v[90:93]
	v_mfma_f32_16x16x32_bf16 v[86:89], v[224:227], v[174:177], v[86:89]
	v_mfma_f32_16x16x32_bf16 v[82:85], v[232:235], v[174:177], v[82:85]
	v_mfma_f32_16x16x32_bf16 v[78:81], v[224:227], v[186:189], v[78:81]
	v_mfma_f32_16x16x32_bf16 v[74:77], v[232:235], v[186:189], v[74:77]
	v_mfma_f32_16x16x32_bf16 v[70:73], v[224:227], v[194:197], v[70:73]
	v_mfma_f32_16x16x32_bf16 v[66:69], v[232:235], v[194:197], v[66:69]
	s_mov_b32 m0, s53
	v_lshl_add_u64 v[198:199], v[238:239], 0, s[76:77]
	s_barrier
	ds_read_b128 v[162:165], v144 offset:49152
	ds_read_b128 v[166:169], v144 offset:50176
	ds_read_b128 v[170:173], v144 offset:51200
	ds_read_b128 v[174:177], v144 offset:52224
	ds_read_b128 v[182:185], v144 offset:53248
	ds_read_b128 v[186:189], v144 offset:54272
	ds_read_b128 v[190:193], v144 offset:55296
	ds_read_b128 v[194:197], v144 offset:56320
	global_load_lds_dwordx4 v[198:199], off
	v_lshl_add_u64 v[198:199], v[240:241], 0, s[76:77]
	s_mov_b32 m0, s54
	s_nop 0
	global_load_lds_dwordx4 v[198:199], off
	s_barrier
; __device__ __forceinline__ unsigned pk2(float lo, float hi) { unsigned r; asm volatile("v_cvt_pk_bf16_f32 %0, %1, %2" : "=v"(r) : "v"(lo), "v"(hi)); return r; }
; __device__ __forceinline__ float siluf_(float x) { return x * __builtin_amdgcn_rcpf(1.0f + __expf(-x)); }
; #define PG8_STAGE(bufoff, gbase, voff) do { _Pragma("unroll") for (int _i = 0; _i < 2; ++_i) \
;         __builtin_amdgcn_global_load_lds((const unsigned*)((const char*)(gbase) + (voff)[_i]), (LAS unsigned*)(lds + (bufoff) + ldsw + _i * 8192), 16, 0, 0); } while (0)
; #define PG8_MMA(ai, bj, At, Bt) do { __builtin_amdgcn_s_setprio(1); _Pragma("unroll") for (int m = 0; m < 4; ++m) _Pragma("unroll") for (int n = 0; n < 2; ++n) _Pragma("unroll") for (int k = 0; k < 2; ++k) \
;         acc[ai][bj][m][n] = __builtin_amdgcn_mfma_f32_16x16x32_bf16(Bt[n][k], At[m][k], acc[ai][bj][m][n], 0, 0, 0); __builtin_amdgcn_s_setprio(0); } while (0)
; #define PG8_BAR __builtin_amdgcn_s_barrier()
;     template <int mode> __device__ __forceinline__ void run(const f32x4 (&acc)[2][2][4][2], const Unit& u, int wr, int wc, int fr, int fq, const LAS float* sc) const {
;     ...
;         if (mode == 0) {
;             const int col0 = u.pn * HALF + wc * 32 + 8 * fq;
; #pragma unroll
;             for (int ai = 0; ai < 2; ++ai)
; #pragma unroll
;                 for (int m = 0; m < 4; ++m) {
;                     const int row = row0 + ai * HALF + m * 16;
;                     const float s = sc[ai * HALF + wr * 64 + m * 16 + fr];
;                     const f32x4 g0 = acc[ai][0][m][0] * s, u0 = acc[ai][1][m][0] * s, g1 = acc[ai][0][m][1] * s, u1 = acc[ai][1][m][1] * s;
;                     u32x4 w;
;                     w.x = pk2(siluf_(g0[0]) * u0[0], siluf_(g0[1]) * u0[1]); w.y = pk2(siluf_(g0[2]) * u0[2], siluf_(g0[3]) * u0[3]);
;                     w.z = pk2(siluf_(g1[0]) * u1[0], siluf_(g1[1]) * u1[1]); w.w = pk2(siluf_(g1[2]) * u1[2], siluf_(g1[3]) * u1[3]);
;                     *(u32x4*)(ob + (size_t)row * FF + col0) = w;
; template <int MODE, class EpiT, class Sched>
; __device__ __forceinline__ void gemm_phase(LAS unsigned char* lds, const Gemm g, const Sched& S, const EpiT& E) {
;     ...
;             PG8_BAR; PG8_WAIT_L(0); PG8_MMA(1, 0, At, B0); PG8_BAR; PG8_SCHED;
;             PG8_STAGE(PG8_SB(1, 1), b3 + hstep, voffB);
;             PG8_WAIT_V(6); PG8_BAR; PG8_MMA(1, 1, At, B1); PG8_BAR;
	s_waitcnt lgkmcnt(0)
	s_waitcnt lgkmcnt(0)
	v_mfma_f32_16x16x32_bf16 v[62:65], v[146:149], v[162:165], v[62:65]
	v_mfma_f32_16x16x32_bf16 v[58:61], v[154:157], v[162:165], v[58:61]
	v_mfma_f32_16x16x32_bf16 v[54:57], v[146:149], v[170:173], v[54:57]
	v_mfma_f32_16x16x32_bf16 v[50:53], v[154:157], v[170:173], v[50:53]
	v_mfma_f32_16x16x32_bf16 v[46:49], v[146:149], v[182:185], v[46:49]
	v_mfma_f32_16x16x32_bf16 v[42:45], v[154:157], v[182:185], v[42:45]
	v_mfma_f32_16x16x32_bf16 v[38:41], v[146:149], v[190:193], v[38:41]
	v_mfma_f32_16x16x32_bf16 v[34:37], v[154:157], v[190:193], v[34:37]
	v_mfma_f32_16x16x32_bf16 v[62:65], v[150:153], v[166:169], v[62:65]
	v_mfma_f32_16x16x32_bf16 v[58:61], v[158:161], v[166:169], v[58:61]
	v_mfma_f32_16x16x32_bf16 v[54:57], v[150:153], v[174:177], v[54:57]
	v_mfma_f32_16x16x32_bf16 v[50:53], v[158:161], v[174:177], v[50:53]
	v_mfma_f32_16x16x32_bf16 v[46:49], v[150:153], v[186:189], v[46:49]
	v_mfma_f32_16x16x32_bf16 v[42:45], v[158:161], v[186:189], v[42:45]
	v_mfma_f32_16x16x32_bf16 v[38:41], v[150:153], v[194:197], v[38:41]
	v_mfma_f32_16x16x32_bf16 v[34:37], v[158:161], v[194:197], v[34:37]
	s_barrier
	s_add_i32 s22, s30, s46
	v_lshl_add_u64 v[146:147], v[242:243], 0, s[76:77]
	s_mov_b32 m0, s22
	s_nop 0
	global_load_lds_dwordx4 v[146:147], off
	v_lshl_add_u64 v[146:147], v[244:245], 0, s[76:77]
	s_add_i32 m0, s22, 0x2000
	s_nop 0
	global_load_lds_dwordx4 v[146:147], off
	s_waitcnt vmcnt(6)
	s_barrier
	v_mfma_f32_16x16x32_bf16 v[30:33], v[220:223], v[162:165], v[30:33]
	v_mfma_f32_16x16x32_bf16 v[26:29], v[228:231], v[162:165], v[26:29]
	v_mfma_f32_16x16x32_bf16 v[22:25], v[220:223], v[170:173], v[22:25]
	v_mfma_f32_16x16x32_bf16 v[18:21], v[228:231], v[170:173], v[18:21]
	v_mfma_f32_16x16x32_bf16 v[14:17], v[220:223], v[182:185], v[14:17]
	v_mfma_f32_16x16x32_bf16 v[10:13], v[228:231], v[182:185], v[10:13]
	v_mfma_f32_16x16x32_bf16 v[6:9], v[220:223], v[190:193], v[6:9]
	v_mfma_f32_16x16x32_bf16 v[2:5], v[228:231], v[190:193], v[2:5]
	v_mfma_f32_16x16x32_bf16 v[30:33], v[224:227], v[166:169], v[30:33]
	v_mfma_f32_16x16x32_bf16 v[26:29], v[232:235], v[166:169], v[26:29]
	v_mfma_f32_16x16x32_bf16 v[22:25], v[224:227], v[174:177], v[22:25]
	v_mfma_f32_16x16x32_bf16 v[18:21], v[232:235], v[174:177], v[18:21]
	v_mfma_f32_16x16x32_bf16 v[14:17], v[224:227], v[186:189], v[14:17]
	v_mfma_f32_16x16x32_bf16 v[10:13], v[232:235], v[186:189], v[10:13]
	v_mfma_f32_16x16x32_bf16 v[6:9], v[224:227], v[194:197], v[6:9]
	v_mfma_f32_16x16x32_bf16 v[2:5], v[232:235], v[194:197], v[2:5]
	s_add_u32 s4, s4, 0x100
	s_addc_u32 s5, s5, 0
	v_lshl_add_u64 v[138:139], v[138:139], 0, s[80:81]
	v_lshl_add_u64 v[136:137], v[136:137], 0, s[80:81]
	s_cmp_ge_u32 s23, s16
	s_mov_b32 s22, s23
	s_barrier
	s_cbranch_scc0 .LBB0_332
	v_lshl_add_u32 v145, s57, 10, v142
	ds_read_b32 v136, v145
	v_lshl_or_b32 v138, s8, 7, v143
	v_lshl_add_u32 v146, s9, 8, v140
	v_ashrrev_i32_e32 v139, 31, v138
	v_lshlrev_b64 v[138:139], 1, v[138:139]
	s_waitcnt lgkmcnt(0)
	v_pk_mul_f32 v[148:149], v[126:127], v[136:137] op_sel_hi:[1,0]
	v_pk_mul_f32 v[154:155], v[94:95], v[136:137] op_sel_hi:[1,0]
	v_mul_f32_e32 v147, 0xbfb8aa3b, v148
	v_exp_f32_e32 v147, v147
	v_pk_mul_f32 v[150:151], v[128:129], v[136:137] op_sel_hi:[1,0]
	v_pk_mul_f32 v[152:153], v[96:97], v[136:137] op_sel_hi:[1,0]
	v_pk_mul_f32 v[158:159], v[122:123], v[136:137] op_sel_hi:[1,0]
	v_add_f32_e32 v147, 1.0, v147
	v_rcp_f32_e32 v147, v147
	v_pk_mul_f32 v[156:157], v[124:125], v[136:137] op_sel_hi:[1,0]
	v_pk_mul_f32 v[160:161], v[92:93], v[136:137] op_sel_hi:[1,0]
	v_pk_mul_f32 v[136:137], v[90:91], v[136:137] op_sel_hi:[1,0]
	v_mul_f32_e32 v147, v148, v147
	v_mul_f32_e32 v148, 0xbfb8aa3b, v149
	v_exp_f32_e32 v148, v148
	v_mul_f32_e32 v147, v154, v147
	s_and_b64 vcc, exec, s[42:43]
	v_add_f32_e32 v148, 1.0, v148
	v_rcp_f32_e32 v148, v148
	s_nop 0
	v_mul_f32_e32 v148, v149, v148
	v_mul_f32_e32 v148, v155, v148
	v_cvt_pk_bf16_f32 v148, v147, v148
	v_mul_f32_e32 v147, 0xbfb8aa3b, v150
	v_mul_f32_e32 v149, 0xbfb8aa3b, v151
	v_exp_f32_e32 v147, v147
	v_exp_f32_e32 v149, v149
	v_add_f32_e32 v147, 1.0, v147
	v_add_f32_e32 v149, 1.0, v149
	v_rcp_f32_e32 v147, v147
	v_rcp_f32_e32 v149, v149
	v_mul_f32_e32 v147, v150, v147
	v_mul_f32_e32 v149, v151, v149
	v_mul_f32_e32 v147, v152, v147
	v_mul_f32_e32 v149, v153, v149
	v_cvt_pk_bf16_f32 v149, v147, v149
	v_mul_f32_e32 v147, 0xbfb8aa3b, v158
	v_exp_f32_e32 v147, v147
	s_nop 0
	v_add_f32_e32 v147, 1.0, v147
	v_rcp_f32_e32 v147, v147
	s_nop 0
	v_mul_f32_e32 v147, v158, v147
	v_mul_f32_e32 v136, v136, v147
	v_mul_f32_e32 v147, 0xbfb8aa3b, v159
	v_exp_f32_e32 v147, v147
	s_nop 0
	v_add_f32_e32 v147, 1.0, v147
	v_rcp_f32_e32 v147, v147
	s_nop 0
	v_mul_f32_e32 v147, v159, v147
	v_mul_f32_e32 v137, v137, v147
	v_cvt_pk_bf16_f32 v150, v136, v137
	v_mul_f32_e32 v136, 0xbfb8aa3b, v156
	v_mul_f32_e32 v137, 0xbfb8aa3b, v157
	v_exp_f32_e32 v136, v136
	v_exp_f32_e32 v137, v137
	v_or_b32_e32 v147, 16, v146
	v_add_f32_e32 v136, 1.0, v136
	v_add_f32_e32 v137, 1.0, v137
	v_rcp_f32_e32 v136, v136
	v_rcp_f32_e32 v137, v137
	v_mul_f32_e32 v136, v156, v136
	v_mul_f32_e32 v137, v157, v137
	v_mul_f32_e32 v136, v160, v136
	v_mul_f32_e32 v137, v161, v137
	v_cvt_pk_bf16_f32 v151, v136, v137
	v_mov_b64_e32 v[136:137], s[6:7]
	v_mad_i64_i32 v[152:153], s[4:5], v146, s33, v[136:137]
	v_lshl_add_u64 v[152:153], v[152:153], 0, v[138:139]
	global_store_dwordx4 v[152:153], v[148:151], off
	ds_read_b32 v148, v145 offset:64
	s_waitcnt lgkmcnt(0)
; __device__ __forceinline__ unsigned pk2(float lo, float hi) { unsigned r; asm volatile("v_cvt_pk_bf16_f32 %0, %1, %2" : "=v"(r) : "v"(lo), "v"(hi)); return r; }
; __device__ __forceinline__ float siluf_(float x) { return x * __builtin_amdgcn_rcpf(1.0f + __expf(-x)); }
;     template <int mode> __device__ __forceinline__ void run(const f32x4 (&acc)[2][2][4][2], const Unit& u, int wr, int wc, int fr, int fq, const LAS float* sc) const {
;     ...
;                 for (int m = 0; m < 4; ++m) {
;                     const int row = row0 + ai * HALF + m * 16;
;                     const float s = sc[ai * HALF + wr * 64 + m * 16 + fr];
;                     const f32x4 g0 = acc[ai][0][m][0] * s, u0 = acc[ai][1][m][0] * s, g1 = acc[ai][0][m][1] * s, u1 = acc[ai][1][m][1] * s;
;                     u32x4 w;
;                     w.x = pk2(siluf_(g0[0]) * u0[0], siluf_(g0[1]) * u0[1]); w.y = pk2(siluf_(g0[2]) * u0[2], siluf_(g0[3]) * u0[3]);
;                     w.z = pk2(siluf_(g1[0]) * u1[0], siluf_(g1[1]) * u1[1]); w.w = pk2(siluf_(g1[2]) * u1[2], siluf_(g1[3]) * u1[3]);
;                     *(u32x4*)(ob + (size_t)row * FF + col0) = w;
	v_pk_mul_f32 v[152:153], v[118:119], v[148:149] op_sel_hi:[1,0]
	v_pk_mul_f32 v[150:151], v[120:121], v[148:149] op_sel_hi:[1,0]
	v_pk_mul_f32 v[154:155], v[88:89], v[148:149] op_sel_hi:[1,0]
	v_pk_mul_f32 v[156:157], v[86:87], v[148:149] op_sel_hi:[1,0]
	v_pk_mul_f32 v[158:159], v[116:117], v[148:149] op_sel_hi:[1,0]
	v_pk_mul_f32 v[160:161], v[114:115], v[148:149] op_sel_hi:[1,0]
	v_pk_mul_f32 v[162:163], v[84:85], v[148:149] op_sel_hi:[1,0]
	v_pk_mul_f32 v[164:165], v[82:83], v[148:149] op_sel_hi:[1,0]
	v_mul_f32_e32 v148, 0xbfb8aa3b, v152
	v_mul_f32_e32 v149, 0xbfb8aa3b, v153
	v_exp_f32_e32 v148, v148
	v_exp_f32_e32 v149, v149
	v_add_f32_e32 v148, 1.0, v148
	v_add_f32_e32 v149, 1.0, v149
	v_rcp_f32_e32 v148, v148
	v_rcp_f32_e32 v149, v149
	v_mul_f32_e32 v148, v152, v148
	v_mul_f32_e32 v149, v153, v149
	v_mul_f32_e32 v148, v156, v148
	v_mul_f32_e32 v149, v157, v149
	v_cvt_pk_bf16_f32 v148, v148, v149
	v_mul_f32_e32 v149, 0xbfb8aa3b, v150
	v_exp_f32_e32 v149, v149
	v_mul_f32_e32 v152, 0xbfb8aa3b, v159
	v_exp_f32_e32 v152, v152
	v_add_f32_e32 v149, 1.0, v149
	v_rcp_f32_e32 v149, v149
	v_add_f32_e32 v152, 1.0, v152
	v_rcp_f32_e32 v152, v152
	v_mul_f32_e32 v149, v150, v149
	v_mul_f32_e32 v150, 0xbfb8aa3b, v151
	v_exp_f32_e32 v150, v150
	v_mul_f32_e32 v149, v154, v149
	v_mul_f32_e32 v152, v159, v152
	v_mul_f32_e32 v152, v163, v152
	v_add_f32_e32 v150, 1.0, v150
	v_rcp_f32_e32 v150, v150
	s_nop 0
	v_mul_f32_e32 v150, v151, v150
	v_mul_f32_e32 v150, v155, v150
	v_cvt_pk_bf16_f32 v149, v149, v150
	v_mul_f32_e32 v150, 0xbfb8aa3b, v160
	v_mul_f32_e32 v151, 0xbfb8aa3b, v161
	v_exp_f32_e32 v150, v150
	v_exp_f32_e32 v151, v151
	v_add_f32_e32 v150, 1.0, v150
	v_add_f32_e32 v151, 1.0, v151
	v_rcp_f32_e32 v150, v150
	v_rcp_f32_e32 v151, v151
	v_mul_f32_e32 v150, v160, v150
	v_mul_f32_e32 v151, v161, v151
	v_mul_f32_e32 v150, v164, v150
	v_mul_f32_e32 v151, v165, v151
	v_cvt_pk_bf16_f32 v150, v150, v151
	v_mul_f32_e32 v151, 0xbfb8aa3b, v158
	v_exp_f32_e32 v151, v151
	s_nop 0
	v_add_f32_e32 v151, 1.0, v151
	v_rcp_f32_e32 v151, v151
	s_nop 0
	v_mul_f32_e32 v151, v158, v151
	v_mul_f32_e32 v151, v162, v151
	v_cvt_pk_bf16_f32 v151, v151, v152
	v_mad_i64_i32 v[152:153], s[4:5], v147, s33, v[136:137]
	v_lshl_add_u64 v[152:153], v[152:153], 0, v[138:139]
	global_store_dwordx4 v[152:153], v[148:151], off
	ds_read_b32 v148, v145 offset:128
	v_or_b32_e32 v147, 32, v146
	s_waitcnt lgkmcnt(0)
	v_pk_mul_f32 v[152:153], v[110:111], v[148:149] op_sel_hi:[1,0]
	v_pk_mul_f32 v[150:151], v[112:113], v[148:149] op_sel_hi:[1,0]
	v_pk_mul_f32 v[154:155], v[80:81], v[148:149] op_sel_hi:[1,0]
	v_pk_mul_f32 v[156:157], v[78:79], v[148:149] op_sel_hi:[1,0]
	v_pk_mul_f32 v[158:159], v[108:109], v[148:149] op_sel_hi:[1,0]
	v_pk_mul_f32 v[160:161], v[106:107], v[148:149] op_sel_hi:[1,0]
	v_pk_mul_f32 v[162:163], v[76:77], v[148:149] op_sel_hi:[1,0]
	v_pk_mul_f32 v[164:165], v[74:75], v[148:149] op_sel_hi:[1,0]
	v_mul_f32_e32 v148, 0xbfb8aa3b, v152
	v_mul_f32_e32 v149, 0xbfb8aa3b, v153
	v_exp_f32_e32 v148, v148
	v_exp_f32_e32 v149, v149
	v_add_f32_e32 v148, 1.0, v148
	v_add_f32_e32 v149, 1.0, v149
	v_rcp_f32_e32 v148, v148
	v_rcp_f32_e32 v149, v149
	v_mul_f32_e32 v148, v152, v148
	v_mul_f32_e32 v149, v153, v149
	v_mul_f32_e32 v148, v156, v148
	v_mul_f32_e32 v149, v157, v149
	v_cvt_pk_bf16_f32 v148, v148, v149
	v_mul_f32_e32 v149, 0xbfb8aa3b, v150
	v_exp_f32_e32 v149, v149
	v_mul_f32_e32 v152, 0xbfb8aa3b, v159
	v_exp_f32_e32 v152, v152
	v_add_f32_e32 v149, 1.0, v149
	v_rcp_f32_e32 v149, v149
	v_add_f32_e32 v152, 1.0, v152
	v_rcp_f32_e32 v152, v152
	v_mul_f32_e32 v149, v150, v149
	v_mul_f32_e32 v150, 0xbfb8aa3b, v151
	v_exp_f32_e32 v150, v150
	v_mul_f32_e32 v149, v154, v149
	v_mul_f32_e32 v152, v159, v152
	v_mul_f32_e32 v152, v163, v152
	v_add_f32_e32 v150, 1.0, v150
	v_rcp_f32_e32 v150, v150
	s_nop 0
	v_mul_f32_e32 v150, v151, v150
	v_mul_f32_e32 v150, v155, v150
	v_cvt_pk_bf16_f32 v149, v149, v150
	v_mul_f32_e32 v150, 0xbfb8aa3b, v160
	v_mul_f32_e32 v151, 0xbfb8aa3b, v161
	v_exp_f32_e32 v150, v150
	v_exp_f32_e32 v151, v151
	v_add_f32_e32 v150, 1.0, v150
	v_add_f32_e32 v151, 1.0, v151
	v_rcp_f32_e32 v150, v150
	v_rcp_f32_e32 v151, v151
	v_mul_f32_e32 v150, v160, v150
	v_mul_f32_e32 v151, v161, v151
	v_mul_f32_e32 v150, v164, v150
	v_mul_f32_e32 v151, v165, v151
	v_cvt_pk_bf16_f32 v150, v150, v151
	v_mul_f32_e32 v151, 0xbfb8aa3b, v158
	v_exp_f32_e32 v151, v151
	s_nop 0
	v_add_f32_e32 v151, 1.0, v151
	v_rcp_f32_e32 v151, v151
	s_nop 0
	v_mul_f32_e32 v151, v158, v151
	v_mul_f32_e32 v151, v162, v151
	v_cvt_pk_bf16_f32 v151, v151, v152
	v_mad_i64_i32 v[152:153], s[4:5], v147, s33, v[136:137]
	v_lshl_add_u64 v[152:153], v[152:153], 0, v[138:139]
	global_store_dwordx4 v[152:153], v[148:151], off
	ds_read_b32 v148, v145 offset:192
	v_or_b32_e32 v147, 48, v146
	s_waitcnt lgkmcnt(0)
; __device__ __forceinline__ unsigned pk2(float lo, float hi) { unsigned r; asm volatile("v_cvt_pk_bf16_f32 %0, %1, %2" : "=v"(r) : "v"(lo), "v"(hi)); return r; }
; __device__ __forceinline__ float siluf_(float x) { return x * __builtin_amdgcn_rcpf(1.0f + __expf(-x)); }
;     template <int mode> __device__ __forceinline__ void run(const f32x4 (&acc)[2][2][4][2], const Unit& u, int wr, int wc, int fr, int fq, const LAS float* sc) const {
;     ...
;                 for (int m = 0; m < 4; ++m) {
;                     const int row = row0 + ai * HALF + m * 16;
;                     const float s = sc[ai * HALF + wr * 64 + m * 16 + fr];
;                     const f32x4 g0 = acc[ai][0][m][0] * s, u0 = acc[ai][1][m][0] * s, g1 = acc[ai][0][m][1] * s, u1 = acc[ai][1][m][1] * s;
;                     u32x4 w;
;                     w.x = pk2(siluf_(g0[0]) * u0[0], siluf_(g0[1]) * u0[1]); w.y = pk2(siluf_(g0[2]) * u0[2], siluf_(g0[3]) * u0[3]);
;                     w.z = pk2(siluf_(g1[0]) * u1[0], siluf_(g1[1]) * u1[1]); w.w = pk2(siluf_(g1[2]) * u1[2], siluf_(g1[3]) * u1[3]);
;                     *(u32x4*)(ob + (size_t)row * FF + col0) = w;
	v_pk_mul_f32 v[152:153], v[102:103], v[148:149] op_sel_hi:[1,0]
	v_pk_mul_f32 v[150:151], v[104:105], v[148:149] op_sel_hi:[1,0]
	v_pk_mul_f32 v[154:155], v[72:73], v[148:149] op_sel_hi:[1,0]
	v_pk_mul_f32 v[156:157], v[70:71], v[148:149] op_sel_hi:[1,0]
	v_pk_mul_f32 v[158:159], v[100:101], v[148:149] op_sel_hi:[1,0]
	v_pk_mul_f32 v[160:161], v[98:99], v[148:149] op_sel_hi:[1,0]
	v_pk_mul_f32 v[162:163], v[68:69], v[148:149] op_sel_hi:[1,0]
	v_pk_mul_f32 v[164:165], v[66:67], v[148:149] op_sel_hi:[1,0]
	v_mul_f32_e32 v148, 0xbfb8aa3b, v152
	v_mul_f32_e32 v149, 0xbfb8aa3b, v153
	v_exp_f32_e32 v148, v148
	v_exp_f32_e32 v149, v149
	v_add_f32_e32 v148, 1.0, v148
	v_add_f32_e32 v149, 1.0, v149
	v_rcp_f32_e32 v148, v148
	v_rcp_f32_e32 v149, v149
	v_mul_f32_e32 v148, v152, v148
	v_mul_f32_e32 v149, v153, v149
	v_mul_f32_e32 v148, v156, v148
	v_mul_f32_e32 v149, v157, v149
	v_cvt_pk_bf16_f32 v148, v148, v149
	v_mul_f32_e32 v149, 0xbfb8aa3b, v150
	v_exp_f32_e32 v149, v149
	v_mul_f32_e32 v152, 0xbfb8aa3b, v159
	v_exp_f32_e32 v152, v152
	v_add_f32_e32 v149, 1.0, v149
	v_rcp_f32_e32 v149, v149
	v_add_f32_e32 v152, 1.0, v152
	v_rcp_f32_e32 v152, v152
	v_mul_f32_e32 v149, v150, v149
	v_mul_f32_e32 v150, 0xbfb8aa3b, v151
	v_exp_f32_e32 v150, v150
	v_mul_f32_e32 v149, v154, v149
	v_mul_f32_e32 v152, v159, v152
	v_mul_f32_e32 v152, v163, v152
	v_add_f32_e32 v150, 1.0, v150
	v_rcp_f32_e32 v150, v150
	s_nop 0
	v_mul_f32_e32 v150, v151, v150
	v_mul_f32_e32 v150, v155, v150
	v_cvt_pk_bf16_f32 v149, v149, v150
	v_mul_f32_e32 v150, 0xbfb8aa3b, v160
	v_mul_f32_e32 v151, 0xbfb8aa3b, v161
	v_exp_f32_e32 v150, v150
	v_exp_f32_e32 v151, v151
	v_add_f32_e32 v150, 1.0, v150
	v_add_f32_e32 v151, 1.0, v151
	v_rcp_f32_e32 v150, v150
	v_rcp_f32_e32 v151, v151
	v_mul_f32_e32 v150, v160, v150
	v_mul_f32_e32 v151, v161, v151
	v_mul_f32_e32 v150, v164, v150
	v_mul_f32_e32 v151, v165, v151
	v_cvt_pk_bf16_f32 v150, v150, v151
	v_mul_f32_e32 v151, 0xbfb8aa3b, v158
	v_exp_f32_e32 v151, v151
	s_nop 0
	v_add_f32_e32 v151, 1.0, v151
	v_rcp_f32_e32 v151, v151
	s_nop 0
	v_mul_f32_e32 v151, v158, v151
	v_mul_f32_e32 v151, v162, v151
	v_cvt_pk_bf16_f32 v151, v151, v152
	v_mad_i64_i32 v[152:153], s[4:5], v147, s33, v[136:137]
	v_lshl_add_u64 v[152:153], v[152:153], 0, v[138:139]
	global_store_dwordx4 v[152:153], v[148:151], off
	ds_read_b32 v148, v145 offset:512
	v_add_u32_e32 v147, 0x80, v146
	s_waitcnt lgkmcnt(0)
	v_pk_mul_f32 v[152:153], v[62:63], v[148:149] op_sel_hi:[1,0]
	v_pk_mul_f32 v[150:151], v[64:65], v[148:149] op_sel_hi:[1,0]
	v_pk_mul_f32 v[154:155], v[32:33], v[148:149] op_sel_hi:[1,0]
	v_pk_mul_f32 v[156:157], v[30:31], v[148:149] op_sel_hi:[1,0]
	v_pk_mul_f32 v[158:159], v[60:61], v[148:149] op_sel_hi:[1,0]
	v_pk_mul_f32 v[160:161], v[58:59], v[148:149] op_sel_hi:[1,0]
	v_pk_mul_f32 v[162:163], v[28:29], v[148:149] op_sel_hi:[1,0]
	v_pk_mul_f32 v[164:165], v[26:27], v[148:149] op_sel_hi:[1,0]
	v_mul_f32_e32 v148, 0xbfb8aa3b, v152
	v_mul_f32_e32 v149, 0xbfb8aa3b, v153
	v_exp_f32_e32 v148, v148
	v_exp_f32_e32 v149, v149
	v_add_f32_e32 v148, 1.0, v148
	v_add_f32_e32 v149, 1.0, v149
	v_rcp_f32_e32 v148, v148
	v_rcp_f32_e32 v149, v149
	v_mul_f32_e32 v148, v152, v148
	v_mul_f32_e32 v149, v153, v149
	v_mul_f32_e32 v148, v156, v148
	v_mul_f32_e32 v149, v157, v149
	v_cvt_pk_bf16_f32 v148, v148, v149
	v_mul_f32_e32 v149, 0xbfb8aa3b, v150
	v_exp_f32_e32 v149, v149
	v_mul_f32_e32 v152, 0xbfb8aa3b, v159
	v_exp_f32_e32 v152, v152
	v_add_f32_e32 v149, 1.0, v149
	v_rcp_f32_e32 v149, v149
	v_add_f32_e32 v152, 1.0, v152
	v_rcp_f32_e32 v152, v152
	v_mul_f32_e32 v149, v150, v149
	v_mul_f32_e32 v150, 0xbfb8aa3b, v151
	v_exp_f32_e32 v150, v150
	v_mul_f32_e32 v149, v154, v149
	v_mul_f32_e32 v152, v159, v152
	v_mul_f32_e32 v152, v163, v152
	v_add_f32_e32 v150, 1.0, v150
	v_rcp_f32_e32 v150, v150
	s_nop 0
	v_mul_f32_e32 v150, v151, v150
	v_mul_f32_e32 v150, v155, v150
	v_cvt_pk_bf16_f32 v149, v149, v150
	v_mul_f32_e32 v150, 0xbfb8aa3b, v160
	v_mul_f32_e32 v151, 0xbfb8aa3b, v161
	v_exp_f32_e32 v150, v150
	v_exp_f32_e32 v151, v151
	v_add_f32_e32 v150, 1.0, v150
	v_add_f32_e32 v151, 1.0, v151
	v_rcp_f32_e32 v150, v150
	v_rcp_f32_e32 v151, v151
	v_mul_f32_e32 v150, v160, v150
	v_mul_f32_e32 v151, v161, v151
	v_mul_f32_e32 v150, v164, v150
	v_mul_f32_e32 v151, v165, v151
	v_cvt_pk_bf16_f32 v150, v150, v151
	v_mul_f32_e32 v151, 0xbfb8aa3b, v158
	v_exp_f32_e32 v151, v151
	s_nop 0
	v_add_f32_e32 v151, 1.0, v151
	v_rcp_f32_e32 v151, v151
	s_nop 0
	v_mul_f32_e32 v151, v158, v151
	v_mul_f32_e32 v151, v162, v151
	v_cvt_pk_bf16_f32 v151, v151, v152
	v_mad_i64_i32 v[152:153], s[4:5], v147, s33, v[136:137]
	v_lshl_add_u64 v[152:153], v[152:153], 0, v[138:139]
	global_store_dwordx4 v[152:153], v[148:151], off
	ds_read_b32 v148, v145 offset:576
	v_add_u32_e32 v147, 0x90, v146
	s_waitcnt lgkmcnt(0)
; __device__ __forceinline__ unsigned pk2(float lo, float hi) { unsigned r; asm volatile("v_cvt_pk_bf16_f32 %0, %1, %2" : "=v"(r) : "v"(lo), "v"(hi)); return r; }
; __device__ __forceinline__ float siluf_(float x) { return x * __builtin_amdgcn_rcpf(1.0f + __expf(-x)); }
;     template <int mode> __device__ __forceinline__ void run(const f32x4 (&acc)[2][2][4][2], const Unit& u, int wr, int wc, int fr, int fq, const LAS float* sc) const {
;     ...
;                 for (int m = 0; m < 4; ++m) {
;                     const int row = row0 + ai * HALF + m * 16;
;                     const float s = sc[ai * HALF + wr * 64 + m * 16 + fr];
;                     const f32x4 g0 = acc[ai][0][m][0] * s, u0 = acc[ai][1][m][0] * s, g1 = acc[ai][0][m][1] * s, u1 = acc[ai][1][m][1] * s;
;                     u32x4 w;
;                     w.x = pk2(siluf_(g0[0]) * u0[0], siluf_(g0[1]) * u0[1]); w.y = pk2(siluf_(g0[2]) * u0[2], siluf_(g0[3]) * u0[3]);
;                     w.z = pk2(siluf_(g1[0]) * u1[0], siluf_(g1[1]) * u1[1]); w.w = pk2(siluf_(g1[2]) * u1[2], siluf_(g1[3]) * u1[3]);
;                     *(u32x4*)(ob + (size_t)row * FF + col0) = w;
	v_pk_mul_f32 v[152:153], v[54:55], v[148:149] op_sel_hi:[1,0]
	v_pk_mul_f32 v[150:151], v[56:57], v[148:149] op_sel_hi:[1,0]
	v_pk_mul_f32 v[154:155], v[24:25], v[148:149] op_sel_hi:[1,0]
	v_pk_mul_f32 v[156:157], v[22:23], v[148:149] op_sel_hi:[1,0]
	v_pk_mul_f32 v[158:159], v[52:53], v[148:149] op_sel_hi:[1,0]
	v_pk_mul_f32 v[160:161], v[50:51], v[148:149] op_sel_hi:[1,0]
	v_pk_mul_f32 v[162:163], v[20:21], v[148:149] op_sel_hi:[1,0]
	v_pk_mul_f32 v[164:165], v[18:19], v[148:149] op_sel_hi:[1,0]
	v_mul_f32_e32 v148, 0xbfb8aa3b, v152
	v_mul_f32_e32 v149, 0xbfb8aa3b, v153
	v_exp_f32_e32 v148, v148
	v_exp_f32_e32 v149, v149
	v_add_f32_e32 v148, 1.0, v148
	v_add_f32_e32 v149, 1.0, v149
	v_rcp_f32_e32 v148, v148
	v_rcp_f32_e32 v149, v149
	v_mul_f32_e32 v148, v152, v148
	v_mul_f32_e32 v149, v153, v149
	v_mul_f32_e32 v148, v156, v148
	v_mul_f32_e32 v149, v157, v149
	v_cvt_pk_bf16_f32 v148, v148, v149
	v_mul_f32_e32 v149, 0xbfb8aa3b, v150
	v_exp_f32_e32 v149, v149
	v_mul_f32_e32 v152, 0xbfb8aa3b, v159
	v_exp_f32_e32 v152, v152
	v_add_f32_e32 v149, 1.0, v149
	v_rcp_f32_e32 v149, v149
	v_add_f32_e32 v152, 1.0, v152
	v_rcp_f32_e32 v152, v152
	v_mul_f32_e32 v149, v150, v149
	v_mul_f32_e32 v150, 0xbfb8aa3b, v151
	v_exp_f32_e32 v150, v150
	v_mul_f32_e32 v149, v154, v149
	v_mul_f32_e32 v152, v159, v152
	v_mul_f32_e32 v152, v163, v152
	v_add_f32_e32 v150, 1.0, v150
	v_rcp_f32_e32 v150, v150
	s_nop 0
	v_mul_f32_e32 v150, v151, v150
	v_mul_f32_e32 v150, v155, v150
	v_cvt_pk_bf16_f32 v149, v149, v150
	v_mul_f32_e32 v150, 0xbfb8aa3b, v160
	v_mul_f32_e32 v151, 0xbfb8aa3b, v161
	v_exp_f32_e32 v150, v150
	v_exp_f32_e32 v151, v151
	v_add_f32_e32 v150, 1.0, v150
	v_add_f32_e32 v151, 1.0, v151
	v_rcp_f32_e32 v150, v150
	v_rcp_f32_e32 v151, v151
	v_mul_f32_e32 v150, v160, v150
	v_mul_f32_e32 v151, v161, v151
	v_mul_f32_e32 v150, v164, v150
	v_mul_f32_e32 v151, v165, v151
	v_cvt_pk_bf16_f32 v150, v150, v151
	v_mul_f32_e32 v151, 0xbfb8aa3b, v158
	v_exp_f32_e32 v151, v151
	s_nop 0
	v_add_f32_e32 v151, 1.0, v151
	v_rcp_f32_e32 v151, v151
	s_nop 0
	v_mul_f32_e32 v151, v158, v151
	v_mul_f32_e32 v151, v162, v151
	v_cvt_pk_bf16_f32 v151, v151, v152
	v_mad_i64_i32 v[152:153], s[4:5], v147, s33, v[136:137]
	v_lshl_add_u64 v[152:153], v[152:153], 0, v[138:139]
	global_store_dwordx4 v[152:153], v[148:151], off
	ds_read_b32 v148, v145 offset:640
	v_add_u32_e32 v147, 0xa0, v146
	s_waitcnt lgkmcnt(0)
	v_pk_mul_f32 v[152:153], v[46:47], v[148:149] op_sel_hi:[1,0]
	v_pk_mul_f32 v[150:151], v[48:49], v[148:149] op_sel_hi:[1,0]
	v_pk_mul_f32 v[154:155], v[16:17], v[148:149] op_sel_hi:[1,0]
	v_pk_mul_f32 v[156:157], v[14:15], v[148:149] op_sel_hi:[1,0]
	v_pk_mul_f32 v[158:159], v[44:45], v[148:149] op_sel_hi:[1,0]
	v_pk_mul_f32 v[160:161], v[42:43], v[148:149] op_sel_hi:[1,0]
	v_pk_mul_f32 v[162:163], v[12:13], v[148:149] op_sel_hi:[1,0]
	v_pk_mul_f32 v[164:165], v[10:11], v[148:149] op_sel_hi:[1,0]
	v_mul_f32_e32 v148, 0xbfb8aa3b, v152
	v_mul_f32_e32 v149, 0xbfb8aa3b, v153
	v_exp_f32_e32 v148, v148
	v_exp_f32_e32 v149, v149
	v_add_f32_e32 v148, 1.0, v148
	v_add_f32_e32 v149, 1.0, v149
	v_rcp_f32_e32 v148, v148
	v_rcp_f32_e32 v149, v149
	v_mul_f32_e32 v148, v152, v148
	v_mul_f32_e32 v149, v153, v149
	v_mul_f32_e32 v148, v156, v148
	v_mul_f32_e32 v149, v157, v149
	v_cvt_pk_bf16_f32 v148, v148, v149
	v_mul_f32_e32 v149, 0xbfb8aa3b, v150
	v_exp_f32_e32 v149, v149
	v_mul_f32_e32 v152, 0xbfb8aa3b, v159
	v_exp_f32_e32 v152, v152
	v_add_f32_e32 v149, 1.0, v149
	v_rcp_f32_e32 v149, v149
	v_add_f32_e32 v152, 1.0, v152
	v_rcp_f32_e32 v152, v152
	v_mul_f32_e32 v149, v150, v149
	v_mul_f32_e32 v150, 0xbfb8aa3b, v151
	v_exp_f32_e32 v150, v150
	v_mul_f32_e32 v149, v154, v149
	v_mul_f32_e32 v152, v159, v152
	v_mul_f32_e32 v152, v163, v152
	v_add_f32_e32 v150, 1.0, v150
	v_rcp_f32_e32 v150, v150
	s_nop 0
	v_mul_f32_e32 v150, v151, v150
	v_mul_f32_e32 v150, v155, v150
	v_cvt_pk_bf16_f32 v149, v149, v150
	v_mul_f32_e32 v150, 0xbfb8aa3b, v160
	v_mul_f32_e32 v151, 0xbfb8aa3b, v161
	v_exp_f32_e32 v150, v150
	v_exp_f32_e32 v151, v151
	v_add_f32_e32 v150, 1.0, v150
	v_add_f32_e32 v151, 1.0, v151
	v_rcp_f32_e32 v150, v150
	v_rcp_f32_e32 v151, v151
	v_mul_f32_e32 v150, v160, v150
	v_mul_f32_e32 v151, v161, v151
	v_mul_f32_e32 v150, v164, v150
	v_mul_f32_e32 v151, v165, v151
	v_cvt_pk_bf16_f32 v150, v150, v151
	v_mul_f32_e32 v151, 0xbfb8aa3b, v158
	v_exp_f32_e32 v151, v151
	v_add_u32_e32 v164, 0xb0, v146
	v_add_f32_e32 v151, 1.0, v151
	v_rcp_f32_e32 v151, v151
	s_nop 0
	v_mul_f32_e32 v151, v158, v151
	v_mul_f32_e32 v151, v162, v151
	v_cvt_pk_bf16_f32 v151, v151, v152
	ds_read_b32 v146, v145 offset:704
	v_mad_i64_i32 v[152:153], s[4:5], v147, s33, v[136:137]
	v_lshl_add_u64 v[152:153], v[152:153], 0, v[138:139]
	global_store_dwordx4 v[152:153], v[148:151], off
	s_waitcnt lgkmcnt(0)
; __device__ __forceinline__ unsigned pk2(float lo, float hi) { unsigned r; asm volatile("v_cvt_pk_bf16_f32 %0, %1, %2" : "=v"(r) : "v"(lo), "v"(hi)); return r; }
; __device__ __forceinline__ float siluf_(float x) { return x * __builtin_amdgcn_rcpf(1.0f + __expf(-x)); }
;     template <int mode> __device__ __forceinline__ void run(const f32x4 (&acc)[2][2][4][2], const Unit& u, int wr, int wc, int fr, int fq, const LAS float* sc) const {
;     ...
;                 for (int m = 0; m < 4; ++m) {
;                     const int row = row0 + ai * HALF + m * 16;
;                     const float s = sc[ai * HALF + wr * 64 + m * 16 + fr];
;                     const f32x4 g0 = acc[ai][0][m][0] * s, u0 = acc[ai][1][m][0] * s, g1 = acc[ai][0][m][1] * s, u1 = acc[ai][1][m][1] * s;
;                     u32x4 w;
;                     w.x = pk2(siluf_(g0[0]) * u0[0], siluf_(g0[1]) * u0[1]); w.y = pk2(siluf_(g0[2]) * u0[2], siluf_(g0[3]) * u0[3]);
;                     w.z = pk2(siluf_(g1[0]) * u1[0], siluf_(g1[1]) * u1[1]); w.w = pk2(siluf_(g1[2]) * u1[2], siluf_(g1[3]) * u1[3]);
;                     *(u32x4*)(ob + (size_t)row * FF + col0) = w;
; template <int MODE, class EpiT, class Sched>
; __device__ __forceinline__ void gemm_phase(LAS unsigned char* lds, const Gemm g, const Sched& S, const EpiT& E) {
;     ...
;         if (!has_next) break;
; #pragma unroll
;         for (int a = 0; a < 2; ++a)
; #pragma unroll
;             for (int b = 0; b < 2; ++b)
; #pragma unroll
;                 for (int m = 0; m < 4; ++m)
; #pragma unroll
;                     for (int n = 0; n < 2; ++n) acc[a][b][m][n] = (f32x4){0.f, 0.f, 0.f, 0.f};
;         cur = nxt; cA = nA; cB = nB; ++ui;
	v_pk_mul_f32 v[152:153], v[8:9], v[146:147] op_sel_hi:[1,0]
	v_pk_mul_f32 v[154:155], v[6:7], v[146:147] op_sel_hi:[1,0]
	v_pk_mul_f32 v[150:151], v[38:39], v[146:147] op_sel_hi:[1,0]
	v_pk_mul_f32 v[148:149], v[40:41], v[146:147] op_sel_hi:[1,0]
	v_pk_mul_f32 v[156:157], v[36:37], v[146:147] op_sel_hi:[1,0]
	v_pk_mul_f32 v[158:159], v[34:35], v[146:147] op_sel_hi:[1,0]
	v_pk_mul_f32 v[160:161], v[4:5], v[146:147] op_sel_hi:[1,0]
	v_pk_mul_f32 v[162:163], v[2:3], v[146:147] op_sel_hi:[1,0]
	v_mul_f32_e32 v145, 0xbfb8aa3b, v150
	v_mul_f32_e32 v146, 0xbfb8aa3b, v151
	v_exp_f32_e32 v145, v145
	v_exp_f32_e32 v146, v146
	v_mul_f32_e32 v147, 0xbfb8aa3b, v149
	v_exp_f32_e32 v147, v147
	v_add_f32_e32 v145, 1.0, v145
	v_add_f32_e32 v146, 1.0, v146
	v_rcp_f32_e32 v145, v145
	v_rcp_f32_e32 v146, v146
	v_add_f32_e32 v147, 1.0, v147
	v_rcp_f32_e32 v147, v147
	v_mul_f32_e32 v145, v150, v145
	v_mul_f32_e32 v146, v151, v146
	v_mul_f32_e32 v145, v154, v145
	v_mul_f32_e32 v146, v155, v146
	v_cvt_pk_bf16_f32 v146, v145, v146
	v_mul_f32_e32 v145, 0xbfb8aa3b, v148
	v_exp_f32_e32 v145, v145
	v_mul_f32_e32 v147, v149, v147
	v_mul_f32_e32 v147, v153, v147
	v_mul_f32_e32 v149, 0xbfb8aa3b, v157
	v_add_f32_e32 v145, 1.0, v145
	v_rcp_f32_e32 v145, v145
	v_exp_f32_e32 v149, v149
	v_mad_i64_i32 v[136:137], s[4:5], v164, s33, v[136:137]
	v_mul_f32_e32 v145, v148, v145
	v_mul_f32_e32 v145, v152, v145
	v_cvt_pk_bf16_f32 v147, v145, v147
	v_mul_f32_e32 v145, 0xbfb8aa3b, v158
	v_mul_f32_e32 v148, 0xbfb8aa3b, v159
	v_exp_f32_e32 v145, v145
	v_exp_f32_e32 v148, v148
	v_add_f32_e32 v149, 1.0, v149
	v_rcp_f32_e32 v149, v149
	v_add_f32_e32 v145, 1.0, v145
	v_add_f32_e32 v148, 1.0, v148
	v_rcp_f32_e32 v145, v145
	v_rcp_f32_e32 v148, v148
	v_mul_f32_e32 v149, v157, v149
	v_mul_f32_e32 v149, v161, v149
	v_mul_f32_e32 v145, v158, v145
	v_mul_f32_e32 v148, v159, v148
	v_mul_f32_e32 v145, v162, v145
	v_mul_f32_e32 v148, v163, v148
	v_cvt_pk_bf16_f32 v148, v145, v148
	v_mul_f32_e32 v145, 0xbfb8aa3b, v156
	v_exp_f32_e32 v145, v145
	v_lshl_add_u64 v[136:137], v[136:137], 0, v[138:139]
	v_add_f32_e32 v145, 1.0, v145
	v_rcp_f32_e32 v145, v145
	s_nop 0
	v_mul_f32_e32 v145, v156, v145
	v_mul_f32_e32 v145, v160, v145
	v_cvt_pk_bf16_f32 v149, v145, v149
	global_store_dwordx4 v[136:137], v[146:149], off
	s_cbranch_vccnz .LBB0_324
	v_mov_b32_e32 v2, 0
	s_mov_b32 s9, s61
	s_mov_b32 s8, s60
	s_mov_b64 s[12:13], s[28:29]
	s_mov_b64 s[10:11], s[34:35]
	s_mov_b32 s57, s2
	v_mov_b32_e32 v3, v2
	v_mov_b32_e32 v4, v2
	v_mov_b32_e32 v5, v2
	v_mov_b32_e32 v6, v2
	v_mov_b32_e32 v7, v2
	v_mov_b32_e32 v8, v2
	v_mov_b32_e32 v9, v2
	v_mov_b32_e32 v10, v2
	v_mov_b32_e32 v11, v2
	v_mov_b32_e32 v12, v2
	v_mov_b32_e32 v13, v2
	v_mov_b32_e32 v14, v2
	v_mov_b32_e32 v15, v2
	v_mov_b32_e32 v16, v2
	v_mov_b32_e32 v17, v2
	v_mov_b32_e32 v18, v2
	v_mov_b32_e32 v19, v2
	v_mov_b32_e32 v20, v2
	v_mov_b32_e32 v21, v2
	v_mov_b32_e32 v22, v2
	v_mov_b32_e32 v23, v2
	v_mov_b32_e32 v24, v2
	v_mov_b32_e32 v25, v2
	v_mov_b32_e32 v26, v2
	v_mov_b32_e32 v27, v2
	v_mov_b32_e32 v28, v2
	v_mov_b32_e32 v29, v2
	v_mov_b32_e32 v30, v2
	v_mov_b32_e32 v31, v2
	v_mov_b32_e32 v32, v2
	v_mov_b32_e32 v33, v2
	v_mov_b32_e32 v34, v2
	v_mov_b32_e32 v35, v2
	v_mov_b32_e32 v36, v2
	v_mov_b32_e32 v37, v2
	v_mov_b32_e32 v38, v2
	v_mov_b32_e32 v39, v2
	v_mov_b32_e32 v40, v2
	v_mov_b32_e32 v41, v2
	v_mov_b32_e32 v42, v2
	v_mov_b32_e32 v43, v2
	v_mov_b32_e32 v44, v2
	v_mov_b32_e32 v45, v2
	v_mov_b32_e32 v46, v2
	v_mov_b32_e32 v47, v2
	v_mov_b32_e32 v48, v2
	v_mov_b32_e32 v49, v2
	v_mov_b32_e32 v50, v2
	v_mov_b32_e32 v51, v2
	v_mov_b32_e32 v52, v2
	v_mov_b32_e32 v53, v2
	v_mov_b32_e32 v54, v2
	v_mov_b32_e32 v55, v2
	v_mov_b32_e32 v56, v2
	v_mov_b32_e32 v57, v2
	v_mov_b32_e32 v58, v2
	v_mov_b32_e32 v59, v2
	v_mov_b32_e32 v60, v2
	v_mov_b32_e32 v61, v2
	v_mov_b32_e32 v62, v2
	v_mov_b32_e32 v63, v2
	v_mov_b32_e32 v64, v2
	v_mov_b32_e32 v65, v2
	v_mov_b32_e32 v66, v2
	v_mov_b32_e32 v67, v2
	v_mov_b32_e32 v68, v2
	v_mov_b32_e32 v69, v2
	v_mov_b32_e32 v70, v2
	v_mov_b32_e32 v71, v2
	v_mov_b32_e32 v72, v2
	v_mov_b32_e32 v73, v2
	v_mov_b32_e32 v74, v2
	v_mov_b32_e32 v75, v2
	v_mov_b32_e32 v76, v2
	v_mov_b32_e32 v77, v2
	v_mov_b32_e32 v78, v2
	v_mov_b32_e32 v79, v2
	v_mov_b32_e32 v80, v2
	v_mov_b32_e32 v81, v2
	v_mov_b32_e32 v82, v2
	v_mov_b32_e32 v83, v2
	v_mov_b32_e32 v84, v2
	v_mov_b32_e32 v85, v2
	v_mov_b32_e32 v86, v2
	v_mov_b32_e32 v87, v2
	v_mov_b32_e32 v88, v2
	v_mov_b32_e32 v89, v2
	v_mov_b32_e32 v90, v2
	v_mov_b32_e32 v91, v2
	v_mov_b32_e32 v92, v2
	v_mov_b32_e32 v93, v2
	v_mov_b32_e32 v94, v2
	v_mov_b32_e32 v95, v2
	v_mov_b32_e32 v96, v2
	v_mov_b32_e32 v97, v2
	v_mov_b32_e32 v98, v2
	v_mov_b32_e32 v99, v2
	v_mov_b32_e32 v100, v2
	v_mov_b32_e32 v101, v2
	v_mov_b32_e32 v102, v2
	v_mov_b32_e32 v103, v2
	v_mov_b32_e32 v104, v2
	v_mov_b32_e32 v105, v2
	v_mov_b32_e32 v106, v2
	v_mov_b32_e32 v107, v2
	v_mov_b32_e32 v108, v2
	v_mov_b32_e32 v109, v2
	v_mov_b32_e32 v110, v2
	v_mov_b32_e32 v111, v2
	v_mov_b32_e32 v112, v2
	v_mov_b32_e32 v113, v2
	v_mov_b32_e32 v114, v2
	v_mov_b32_e32 v115, v2
	v_mov_b32_e32 v116, v2
	v_mov_b32_e32 v117, v2
	v_mov_b32_e32 v118, v2
	v_mov_b32_e32 v119, v2
	v_mov_b32_e32 v120, v2
	v_mov_b32_e32 v121, v2
	v_mov_b32_e32 v122, v2
	v_mov_b32_e32 v123, v2
	v_mov_b32_e32 v124, v2
	v_mov_b32_e32 v125, v2
	v_mov_b32_e32 v126, v2
	v_mov_b32_e32 v127, v2
	v_mov_b32_e32 v128, v2
	v_mov_b32_e32 v129, v2
	s_branch .LBB0_324

; __global__ void __launch_bounds__(NTHREADS, 2) mk_fwd(Params P_arg) {
	.amdhsa_kernel _Z6mk_fwd6Params
		.amdhsa_group_segment_fixed_size 0
		.amdhsa_private_segment_fixed_size 0
		.amdhsa_kernarg_size 544
		.amdhsa_user_sgpr_count 2
		.amdhsa_user_sgpr_dispatch_ptr 0
		.amdhsa_user_sgpr_queue_ptr 0
		.amdhsa_user_sgpr_kernarg_segment_ptr 1
		.amdhsa_user_sgpr_dispatch_id 0
		.amdhsa_user_sgpr_kernarg_preload_length 0
		.amdhsa_user_sgpr_kernarg_preload_offset 0
		.amdhsa_user_sgpr_private_segment_size 0
		.amdhsa_uses_dynamic_stack 0
		.amdhsa_enable_private_segment 0
		.amdhsa_system_sgpr_workgroup_id_x 1
		.amdhsa_system_sgpr_workgroup_id_y 0
		.amdhsa_system_sgpr_workgroup_id_z 0
		.amdhsa_system_sgpr_workgroup_info 0
		.amdhsa_system_vgpr_workitem_id 2
		.amdhsa_next_free_vgpr 249
		.amdhsa_next_free_sgpr 100
		.amdhsa_accum_offset 252
		.amdhsa_reserve_vcc 1
		.amdhsa_float_round_mode_32 0
		.amdhsa_float_round_mode_16_64 0
		.amdhsa_float_denorm_mode_32 3
		.amdhsa_float_denorm_mode_16_64 3
		.amdhsa_dx10_clamp 1
		.amdhsa_ieee_mode 1
		.amdhsa_fp16_overflow 0
		.amdhsa_tg_split 0
		.amdhsa_exception_fp_ieee_invalid_op 0
		.amdhsa_exception_fp_denorm_src 0
		.amdhsa_exception_fp_ieee_div_zero 0
		.amdhsa_exception_fp_ieee_overflow 0
		.amdhsa_exception_fp_ieee_underflow 0
		.amdhsa_exception_fp_ieee_inexact 0
		.amdhsa_exception_int_div_zero 0
	.end_amdhsa_kernel

amdhsa.kernels:
  - .agpr_count:     0
    .args:
      - .offset:         0
        .size:           288
        .value_kind:     by_value
      - .offset:         288
        .size:           4
        .value_kind:     hidden_block_count_x
      - .offset:         292
        .size:           4
        .value_kind:     hidden_block_count_y
      - .offset:         296
        .size:           4
        .value_kind:     hidden_block_count_z
      - .offset:         300
        .size:           2
        .value_kind:     hidden_group_size_x
      - .offset:         302
        .size:           2
        .value_kind:     hidden_group_size_y
      - .offset:         304
        .size:           2
        .value_kind:     hidden_group_size_z
      - .offset:         306
        .size:           2
        .value_kind:     hidden_remainder_x
      - .offset:         308
        .size:           2
        .value_kind:     hidden_remainder_y
      - .offset:         310
        .size:           2
        .value_kind:     hidden_remainder_z
      - .offset:         328
        .size:           8
        .value_kind:     hidden_global_offset_x
      - .offset:         336
        .size:           8
        .value_kind:     hidden_global_offset_y
      - .offset:         344
        .size:           8
        .value_kind:     hidden_global_offset_z
      - .offset:         352
        .size:           2
        .value_kind:     hidden_grid_dims
      - .offset:         376
        .size:           8
        .value_kind:     hidden_multigrid_sync_arg
      - .offset:         408
        .size:           4
        .value_kind:     hidden_dynamic_lds_size
    .group_segment_fixed_size: 0
    .kernarg_segment_align: 8
    .kernarg_segment_size: 544
    .language:       OpenCL C
    .language_version:
      - 2
      - 0
    .max_flat_workgroup_size: 512
    .name:           _Z6mk_fwd6Params
    .private_segment_fixed_size: 0
    .sgpr_count:     106
    .sgpr_spill_count: 174
    .symbol:         _Z6mk_fwd6Params.kd
    .uniform_work_group_size: 1
    .uses_dynamic_stack: false
    .vgpr_count:     249
    .vgpr_spill_count: 0
    .wavefront_size: 64
